# GDN prep: L2 prefetch of next chunk raw q/k/v rows issued at start of forward substitution
# baseline (speedup 1.0000x reference)
; #define LAS __attribute__((address_space(3)))
; DI void gdn_prep_phase(const int tid, LAS unsigned char* lds, const P& p, int G, int c) {
;     ...
;             const int ch = ht & 127, th = ht >> 7, isv = th, colq = h * 128 + ch, colkv = 768 + isv * 768 + h * 128 + ch, t0 = th * 32;
;             bf16_t qraw[35], kvraw[67];
;             const bool haloq = (n > 0) || (t0 > 0), halokv = (n > 0);
; #pragma unroll
;             for (int e = 0; e < 3; ++e) { qraw[e] = haloq ? qkv[(tok0 + t0 - 3 + e) * 2304 + colq] : (bf16_t)0; kvraw[e] = halokv ? qkv[(tok0 - 3 + e) * 2304 + colkv] : (bf16_t)0; }
; #pragma unroll
;             for (int e = 0; e < 32; ++e) qraw[3 + e] = qkv[(tok0 + t0 + e) * 2304 + colq];
; #pragma unroll
;             for (int e = 0; e < 64; ++e) kvraw[3 + e] = qkv[(tok0 + e) * 2304 + colkv];
;     ...
;           for (int kb = 0; kb < 8; ++kb) {
; #pragma unroll
;               for (int pp = 0; pp < 4; ++pp) { const int pr = 4 * kb + pp;
;                   f32x2 s = (f32x2){xs[2 * pr], xs[2 * pr + 1]};
; #pragma unroll
;                   for (int j = 8 * kb; j < 2 * pr; j += 2) { const f32x4 l = *(const LAS f32x4*)(Ls + pr * 136 + j * 2);
;                       s -= (f32x2){l[0], l[1]} * (f32x2){xs[j], xs[j]}; s -= (f32x2){l[2], l[3]} * (f32x2){xs[j + 1], xs[j + 1]}; }
;                   xs[2 * pr] = s[0];
;                   xs[2 * pr + 1] = s[1] - Ls[pr * 136 + 4 * pr + 1] * s[0]; }
; #pragma unroll
;               for (int pr = 4 * kb + 4; pr < 32; ++pr) {
;                   f32x2 s0 = (f32x2){xs[2 * pr], xs[2 * pr + 1]}, s1 = (f32x2){0.f, 0.f};
; #pragma unroll
;                   for (int q = 0; q < 4; ++q) { const int j = 8 * kb + 2 * q; const f32x4 l = *(const LAS f32x4*)(Ls + pr * 136 + j * 2);
;                       s0 -= (f32x2){l[0], l[1]} * (f32x2){xs[j], xs[j]}; s1 -= (f32x2){l[2], l[3]} * (f32x2){xs[j + 1], xs[j + 1]}; }
;                   const f32x2 s = s0 + s1; xs[2 * pr] = s[0]; xs[2 * pr + 1] = s[1]; }
.LBB0_630:
	s_or_b64 exec, exec, s[0:1]
	v_readlane_b32 s26, v253, 24
	v_mul_u32_u24_e32 v238, 0x556, v68
	v_lshrrev_b32_e32 v238, 16, v238
	v_add_u32_e32 v232, s26, v70
	v_lshrrev_b32_e32 v233, 5, v232
	v_and_b32_e32 v232, 31, v232
	s_mov_b32 s26, 0xaaaaaaab
	v_mul_hi_u32 v239, v233, s26
	v_lshrrev_b32_e32 v239, 2, v239
	v_mul_u32_u24_e32 v240, 6, v239
	v_sub_u32_e32 v233, v233, v240
	v_lshlrev_b32_e32 v239, 11, v239
	v_lshl_add_u32 v232, v232, 6, v239
	v_mul_u32_u24_e32 v239, 48, v238
	v_sub_u32_e32 v239, v68, v239
	v_add3_u32 v232, v232, v238, -3
	v_max_i32_e32 v232, 0, v232
	v_mul_u32_u24_e32 v232, 0x1200, v232
	v_lshrrev_b32_e32 v238, 4, v239
	v_and_b32_e32 v239, 15, v239
	s_movk_i32 s26, 0x600
	v_mad_u32_u24 v232, v238, s26, v232
	v_lshl_add_u32 v232, v233, 8, v232
	v_lshl_add_u32 v232, v239, 4, v232
	v_readlane_b32 s26, v250, 7
	v_readlane_b32 s27, v250, 8
	s_nop 4
	global_load_dwordx4 v[246:249], v232, s[26:27]
	v_add_u32_e32 v232, 0x5a00, v232
	global_load_dwordx4 v[246:249], v232, s[26:27]
	v_add_u32_e32 v232, 0x5a00, v232
	global_load_dwordx4 v[246:249], v232, s[26:27]
	v_add_u32_e32 v232, 0x5a00, v232
	global_load_dwordx4 v[246:249], v232, s[26:27]
	v_add_u32_e32 v232, 0x5a00, v232
	global_load_dwordx4 v[246:249], v232, s[26:27]
	v_add_u32_e32 v232, 0x5a00, v232
	global_load_dwordx4 v[246:249], v232, s[26:27]
	v_add_u32_e32 v232, 0x5a00, v232
	global_load_dwordx4 v[246:249], v232, s[26:27]
	v_add_u32_e32 v232, 0x5a00, v232
	global_load_dwordx4 v[246:249], v232, s[26:27]
	v_add_u32_e32 v232, 0x5a00, v232
	global_load_dwordx4 v[246:249], v232, s[26:27]
	v_add_u32_e32 v232, 0x5a00, v232
	global_load_dwordx4 v[246:249], v232, s[26:27]
	v_add_u32_e32 v232, 0x5a00, v232
	global_load_dwordx4 v[246:249], v232, s[26:27]
	v_add_u32_e32 v232, 0x5a00, v232
	global_load_dwordx4 v[246:249], v232, s[26:27]
	v_add_u32_e32 v232, 0x5a00, v232
	global_load_dwordx4 v[246:249], v232, s[26:27]
	v_add_u32_e32 v232, 0x5a00, v232
	global_load_dwordx4 v[246:249], v232, s[26:27]
	ds_read_b128 v[112:115], v69 offset:35360
	v_add_u32_e32 v141, 0x8800, v69
	ds_read2_b32 v[116:117], v141 offset0:1 offset1:141
	ds_read_b128 v[120:123], v69 offset:35904
	ds_read_b128 v[124:127], v69 offset:35920
	ds_read_b128 v[128:131], v69 offset:36448
	v_add_u32_e32 v183, 0x8c00, v69
	ds_read2_b32 v[132:133], v183 offset0:25 offset1:165
	ds_read_b128 v[136:139], v69 offset:36464
	ds_read_b128 v[238:241], v69 offset:36480
	ds_read_b128 v[242:245], v69 offset:36992
	s_waitcnt lgkmcnt(15)
	v_pk_mul_f32 v[66:67], v[158:159], v[60:61]
	s_waitcnt lgkmcnt(8)
	v_pk_mul_f32 v[60:61], v[66:67], v[112:113] op_sel_hi:[0,1]
	s_waitcnt lgkmcnt(7)
	v_fma_f32 v158, -v66, v116, v67
	v_pk_fma_f32 v[60:61], v[188:189], v[62:63], v[60:61] neg_lo:[0,0,1] neg_hi:[0,0,1]
	s_nop 0
	v_pk_fma_f32 v[60:61], v[114:115], v[158:159], v[60:61] op_sel_hi:[1,0,1] neg_lo:[1,0,0] neg_hi:[1,0,0]
	ds_read_b128 v[112:115], v69 offset:37008
	v_fma_f32 v62, -v117, v60, v61
	ds_read_b128 v[116:119], v69 offset:37024
	s_waitcnt lgkmcnt(8)
	v_pk_mul_f32 v[188:189], v[66:67], v[120:121] op_sel_hi:[0,1]
	v_pk_fma_f32 v[56:57], v[160:161], v[56:57], v[188:189] neg_lo:[0,0,1] neg_hi:[0,0,1]
	s_nop 0
	v_pk_fma_f32 v[56:57], v[122:123], v[158:159], v[56:57] op_sel_hi:[1,0,1] neg_lo:[1,0,0] neg_hi:[1,0,0]
	ds_read_b128 v[120:123], v69 offset:37040
	s_waitcnt lgkmcnt(8)
	v_pk_fma_f32 v[56:57], v[124:125], v[60:61], v[56:57] op_sel_hi:[1,0,1] neg_lo:[1,0,0] neg_hi:[1,0,0]
	s_nop 0
	v_pk_fma_f32 v[56:57], v[126:127], v[62:63], v[56:57] op_sel_hi:[1,0,1] neg_lo:[1,0,0] neg_hi:[1,0,0]
	ds_read_b128 v[124:127], v69 offset:37536
	s_waitcnt lgkmcnt(8)
	v_pk_mul_f32 v[188:189], v[66:67], v[128:129] op_sel_hi:[0,1]
	v_pk_fma_f32 v[58:59], v[162:163], v[58:59], v[188:189] neg_lo:[0,0,1] neg_hi:[0,0,1]
	s_waitcnt lgkmcnt(7)
	v_fma_f32 v160, -v132, v56, v57
	v_pk_fma_f32 v[58:59], v[158:159], v[130:131], v[58:59] op_sel_hi:[0,1,1] neg_lo:[1,0,0] neg_hi:[1,0,0]
	ds_read_b128 v[128:131], v69 offset:37552
	s_waitcnt lgkmcnt(7)
	v_pk_fma_f32 v[58:59], v[60:61], v[136:137], v[58:59] op_sel_hi:[0,1,1] neg_lo:[1,0,0] neg_hi:[1,0,0]
	v_pk_fma_f32 v[58:59], v[138:139], v[62:63], v[58:59] op_sel_hi:[1,0,1] neg_lo:[1,0,0] neg_hi:[1,0,0]
	ds_read_b128 v[136:139], v69 offset:37568
	s_waitcnt lgkmcnt(7)
	v_pk_fma_f32 v[58:59], v[238:239], v[56:57], v[58:59] op_sel_hi:[1,0,1] neg_lo:[1,0,0] neg_hi:[1,0,0]
	s_nop 0
	v_pk_fma_f32 v[58:59], v[240:241], v[160:161], v[58:59] op_sel_hi:[1,0,1] neg_lo:[1,0,0] neg_hi:[1,0,0]
	ds_read_b128 v[238:241], v69 offset:37584
	v_fma_f32 v162, -v133, v58, v59
	ds_read_b128 v[132:135], v69 offset:38080
	s_waitcnt lgkmcnt(8)
	v_pk_mul_f32 v[188:189], v[66:67], v[242:243] op_sel_hi:[0,1]
	v_pk_fma_f32 v[48:49], v[178:179], v[48:49], v[188:189] neg_lo:[0,0,1] neg_hi:[0,0,1]
	v_pk_fma_f32 v[178:179], v[158:159], v[244:245], 0 op_sel_hi:[0,1,0] neg_lo:[1,0,0] neg_hi:[1,0,0]
	ds_read_b128 v[242:245], v69 offset:38096
	s_waitcnt lgkmcnt(8)
	v_pk_fma_f32 v[48:49], v[60:61], v[112:113], v[48:49] op_sel_hi:[0,1,1] neg_lo:[1,0,0] neg_hi:[1,0,0]
	v_pk_fma_f32 v[178:179], v[62:63], v[114:115], v[178:179] op_sel_hi:[0,1,1] neg_lo:[1,0,0] neg_hi:[1,0,0]
	ds_read_b128 v[112:115], v69 offset:38112
	s_waitcnt lgkmcnt(8)
	v_pk_fma_f32 v[48:49], v[116:117], v[56:57], v[48:49] op_sel_hi:[1,0,1] neg_lo:[1,0,0] neg_hi:[1,0,0]
	v_pk_fma_f32 v[178:179], v[118:119], v[160:161], v[178:179] op_sel_hi:[1,0,1] neg_lo:[1,0,0] neg_hi:[1,0,0]
	ds_read_b128 v[116:119], v69 offset:38128
	s_waitcnt lgkmcnt(8)
; #define LAS __attribute__((address_space(3)))
; DI void gdn_prep_phase(const int tid, LAS unsigned char* lds, const P& p, int G, int c) {
;     ...
;           for (int kb = 0; kb < 8; ++kb) {
; #pragma unroll
;               for (int pp = 0; pp < 4; ++pp) { const int pr = 4 * kb + pp;
;                   f32x2 s = (f32x2){xs[2 * pr], xs[2 * pr + 1]};
; #pragma unroll
;                   for (int j = 8 * kb; j < 2 * pr; j += 2) { const f32x4 l = *(const LAS f32x4*)(Ls + pr * 136 + j * 2);
;                       s -= (f32x2){l[0], l[1]} * (f32x2){xs[j], xs[j]}; s -= (f32x2){l[2], l[3]} * (f32x2){xs[j + 1], xs[j + 1]}; }
;                   xs[2 * pr] = s[0];
;                   xs[2 * pr + 1] = s[1] - Ls[pr * 136 + 4 * pr + 1] * s[0]; }
; #pragma unroll
;               for (int pr = 4 * kb + 4; pr < 32; ++pr) {
;                   f32x2 s0 = (f32x2){xs[2 * pr], xs[2 * pr + 1]}, s1 = (f32x2){0.f, 0.f};
; #pragma unroll
;                   for (int q = 0; q < 4; ++q) { const int j = 8 * kb + 2 * q; const f32x4 l = *(const LAS f32x4*)(Ls + pr * 136 + j * 2);
;                       s0 -= (f32x2){l[0], l[1]} * (f32x2){xs[j], xs[j]}; s1 -= (f32x2){l[2], l[3]} * (f32x2){xs[j + 1], xs[j + 1]}; }
;                   const f32x2 s = s0 + s1; xs[2 * pr] = s[0]; xs[2 * pr + 1] = s[1]; }
	v_pk_fma_f32 v[48:49], v[120:121], v[58:59], v[48:49] op_sel_hi:[1,0,1] neg_lo:[1,0,0] neg_hi:[1,0,0]
	v_pk_fma_f32 v[178:179], v[122:123], v[162:163], v[178:179] op_sel_hi:[1,0,1] neg_lo:[1,0,0] neg_hi:[1,0,0]
	ds_read_b128 v[120:123], v69 offset:38624
	v_pk_add_f32 v[48:49], v[48:49], v[178:179]
	s_waitcnt lgkmcnt(8)
	v_pk_mul_f32 v[178:179], v[66:67], v[124:125] op_sel_hi:[0,1]
	v_pk_fma_f32 v[50:51], v[172:173], v[50:51], v[178:179] neg_lo:[0,0,1] neg_hi:[0,0,1]
	v_pk_fma_f32 v[172:173], v[158:159], v[126:127], 0 op_sel_hi:[0,1,0] neg_lo:[1,0,0] neg_hi:[1,0,0]
	ds_read_b128 v[124:127], v69 offset:38640
	s_waitcnt lgkmcnt(8)
	v_pk_fma_f32 v[50:51], v[60:61], v[128:129], v[50:51] op_sel_hi:[0,1,1] neg_lo:[1,0,0] neg_hi:[1,0,0]
	v_pk_fma_f32 v[172:173], v[62:63], v[130:131], v[172:173] op_sel_hi:[0,1,1] neg_lo:[1,0,0] neg_hi:[1,0,0]
	ds_read_b128 v[128:131], v69 offset:38656
	s_waitcnt lgkmcnt(8)
	v_pk_fma_f32 v[50:51], v[56:57], v[136:137], v[50:51] op_sel_hi:[0,1,1] neg_lo:[1,0,0] neg_hi:[1,0,0]
	v_pk_fma_f32 v[172:173], v[138:139], v[160:161], v[172:173] op_sel_hi:[1,0,1] neg_lo:[1,0,0] neg_hi:[1,0,0]
	ds_read_b128 v[136:139], v69 offset:38672
	s_waitcnt lgkmcnt(8)
	v_pk_fma_f32 v[50:51], v[238:239], v[58:59], v[50:51] op_sel_hi:[1,0,1] neg_lo:[1,0,0] neg_hi:[1,0,0]
	v_pk_fma_f32 v[172:173], v[240:241], v[162:163], v[172:173] op_sel_hi:[1,0,1] neg_lo:[1,0,0] neg_hi:[1,0,0]
	ds_read_b128 v[238:241], v69 offset:39168
	v_pk_add_f32 v[178:179], v[50:51], v[172:173]
	s_waitcnt lgkmcnt(8)
	v_pk_mul_f32 v[50:51], v[66:67], v[132:133] op_sel_hi:[0,1]
	v_pk_fma_f32 v[4:5], v[164:165], v[4:5], v[50:51] neg_lo:[0,0,1] neg_hi:[0,0,1]
	v_pk_fma_f32 v[50:51], v[158:159], v[134:135], 0 op_sel_hi:[0,1,0] neg_lo:[1,0,0] neg_hi:[1,0,0]
	ds_read_b128 v[132:135], v69 offset:39184
	s_waitcnt lgkmcnt(8)
	v_pk_fma_f32 v[4:5], v[60:61], v[242:243], v[4:5] op_sel_hi:[0,1,1] neg_lo:[1,0,0] neg_hi:[1,0,0]
	v_pk_fma_f32 v[50:51], v[62:63], v[244:245], v[50:51] op_sel_hi:[0,1,1] neg_lo:[1,0,0] neg_hi:[1,0,0]
	ds_read_b128 v[242:245], v69 offset:39200
	s_waitcnt lgkmcnt(8)
	v_pk_fma_f32 v[4:5], v[56:57], v[112:113], v[4:5] op_sel_hi:[0,1,1] neg_lo:[1,0,0] neg_hi:[1,0,0]
	v_pk_fma_f32 v[50:51], v[160:161], v[114:115], v[50:51] op_sel_hi:[0,1,1] neg_lo:[1,0,0] neg_hi:[1,0,0]
	ds_read_b128 v[112:115], v69 offset:39216
	s_waitcnt lgkmcnt(8)
	v_pk_fma_f32 v[4:5], v[58:59], v[116:117], v[4:5] op_sel_hi:[0,1,1] neg_lo:[1,0,0] neg_hi:[1,0,0]
	v_pk_fma_f32 v[50:51], v[118:119], v[162:163], v[50:51] op_sel_hi:[1,0,1] neg_lo:[1,0,0] neg_hi:[1,0,0]
	ds_read_b128 v[116:119], v69 offset:39712
	v_pk_add_f32 v[188:189], v[4:5], v[50:51]
	s_waitcnt lgkmcnt(8)
	v_pk_mul_f32 v[4:5], v[66:67], v[120:121] op_sel_hi:[0,1]
	v_pk_fma_f32 v[50:51], v[166:167], v[6:7], v[4:5] neg_lo:[0,0,1] neg_hi:[0,0,1]
	v_pk_fma_f32 v[164:165], v[158:159], v[122:123], 0 op_sel_hi:[0,1,0] neg_lo:[1,0,0] neg_hi:[1,0,0]
	ds_read_b128 v[120:123], v69 offset:39728
	s_waitcnt lgkmcnt(8)
	v_pk_fma_f32 v[50:51], v[60:61], v[124:125], v[50:51] op_sel_hi:[0,1,1] neg_lo:[1,0,0] neg_hi:[1,0,0]
	v_pk_fma_f32 v[164:165], v[62:63], v[126:127], v[164:165] op_sel_hi:[0,1,1] neg_lo:[1,0,0] neg_hi:[1,0,0]
	ds_read_b128 v[124:127], v69 offset:39744
	s_waitcnt lgkmcnt(8)
	v_pk_fma_f32 v[50:51], v[56:57], v[128:129], v[50:51] op_sel_hi:[0,1,1] neg_lo:[1,0,0] neg_hi:[1,0,0]
	v_pk_fma_f32 v[164:165], v[160:161], v[130:131], v[164:165] op_sel_hi:[0,1,1] neg_lo:[1,0,0] neg_hi:[1,0,0]
	ds_read_b128 v[128:131], v69 offset:39760
	s_waitcnt lgkmcnt(8)
	v_pk_fma_f32 v[4:5], v[58:59], v[136:137], v[50:51] op_sel_hi:[0,1,1] neg_lo:[1,0,0] neg_hi:[1,0,0]
	v_pk_fma_f32 v[6:7], v[162:163], v[138:139], v[164:165] op_sel_hi:[0,1,1] neg_lo:[1,0,0] neg_hi:[1,0,0]
	ds_read_b128 v[136:139], v69 offset:40256
	v_pk_add_f32 v[50:51], v[4:5], v[6:7]
	s_waitcnt lgkmcnt(8)
	v_pk_mul_f32 v[4:5], v[66:67], v[238:239] op_sel_hi:[0,1]
	v_pk_fma_f32 v[8:9], v[168:169], v[8:9], v[4:5] neg_lo:[0,0,1] neg_hi:[0,0,1]
	v_pk_fma_f32 v[164:165], v[158:159], v[240:241], 0 op_sel_hi:[0,1,0] neg_lo:[1,0,0] neg_hi:[1,0,0]
	ds_read_b128 v[238:241], v69 offset:40272
	s_waitcnt lgkmcnt(8)
	v_pk_fma_f32 v[8:9], v[60:61], v[132:133], v[8:9] op_sel_hi:[0,1,1] neg_lo:[1,0,0] neg_hi:[1,0,0]
	v_pk_fma_f32 v[164:165], v[62:63], v[134:135], v[164:165] op_sel_hi:[0,1,1] neg_lo:[1,0,0] neg_hi:[1,0,0]
	ds_read_b128 v[132:135], v69 offset:40288
	s_waitcnt lgkmcnt(8)
	v_pk_fma_f32 v[8:9], v[56:57], v[242:243], v[8:9] op_sel_hi:[0,1,1] neg_lo:[1,0,0] neg_hi:[1,0,0]
	v_pk_fma_f32 v[164:165], v[160:161], v[244:245], v[164:165] op_sel_hi:[0,1,1] neg_lo:[1,0,0] neg_hi:[1,0,0]
	ds_read_b128 v[242:245], v69 offset:40304
	s_waitcnt lgkmcnt(8)
	v_pk_fma_f32 v[4:5], v[58:59], v[112:113], v[8:9] op_sel_hi:[0,1,1] neg_lo:[1,0,0] neg_hi:[1,0,0]
	v_pk_fma_f32 v[6:7], v[162:163], v[114:115], v[164:165] op_sel_hi:[0,1,1] neg_lo:[1,0,0] neg_hi:[1,0,0]
	ds_read_b128 v[112:115], v69 offset:40800
	v_pk_add_f32 v[164:165], v[4:5], v[6:7]
	s_waitcnt lgkmcnt(8)
	v_pk_mul_f32 v[4:5], v[66:67], v[116:117] op_sel_hi:[0,1]
	v_pk_fma_f32 v[8:9], v[170:171], v[10:11], v[4:5] neg_lo:[0,0,1] neg_hi:[0,0,1]
	v_pk_fma_f32 v[10:11], v[158:159], v[118:119], 0 op_sel_hi:[0,1,0] neg_lo:[1,0,0] neg_hi:[1,0,0]
	ds_read_b128 v[116:119], v69 offset:40816
	s_waitcnt lgkmcnt(8)
	v_pk_fma_f32 v[8:9], v[60:61], v[120:121], v[8:9] op_sel_hi:[0,1,1] neg_lo:[1,0,0] neg_hi:[1,0,0]
	v_pk_fma_f32 v[10:11], v[62:63], v[122:123], v[10:11] op_sel_hi:[0,1,1] neg_lo:[1,0,0] neg_hi:[1,0,0]
	ds_read_b128 v[120:123], v69 offset:40832
	s_waitcnt lgkmcnt(8)
; #define LAS __attribute__((address_space(3)))
; DI void gdn_prep_phase(const int tid, LAS unsigned char* lds, const P& p, int G, int c) {
;     ...
;           for (int kb = 0; kb < 8; ++kb) {
; #pragma unroll
;               for (int pp = 0; pp < 4; ++pp) { const int pr = 4 * kb + pp;
;                   f32x2 s = (f32x2){xs[2 * pr], xs[2 * pr + 1]};
; #pragma unroll
;                   for (int j = 8 * kb; j < 2 * pr; j += 2) { const f32x4 l = *(const LAS f32x4*)(Ls + pr * 136 + j * 2);
;                       s -= (f32x2){l[0], l[1]} * (f32x2){xs[j], xs[j]}; s -= (f32x2){l[2], l[3]} * (f32x2){xs[j + 1], xs[j + 1]}; }
;                   xs[2 * pr] = s[0];
;                   xs[2 * pr + 1] = s[1] - Ls[pr * 136 + 4 * pr + 1] * s[0]; }
; #pragma unroll
;               for (int pr = 4 * kb + 4; pr < 32; ++pr) {
;                   f32x2 s0 = (f32x2){xs[2 * pr], xs[2 * pr + 1]}, s1 = (f32x2){0.f, 0.f};
; #pragma unroll
;                   for (int q = 0; q < 4; ++q) { const int j = 8 * kb + 2 * q; const f32x4 l = *(const LAS f32x4*)(Ls + pr * 136 + j * 2);
;                       s0 -= (f32x2){l[0], l[1]} * (f32x2){xs[j], xs[j]}; s1 -= (f32x2){l[2], l[3]} * (f32x2){xs[j + 1], xs[j + 1]}; }
;                   const f32x2 s = s0 + s1; xs[2 * pr] = s[0]; xs[2 * pr + 1] = s[1]; }
	v_pk_fma_f32 v[8:9], v[56:57], v[124:125], v[8:9] op_sel_hi:[0,1,1] neg_lo:[1,0,0] neg_hi:[1,0,0]
	v_pk_fma_f32 v[10:11], v[160:161], v[126:127], v[10:11] op_sel_hi:[0,1,1] neg_lo:[1,0,0] neg_hi:[1,0,0]
	ds_read_b128 v[124:127], v69 offset:40848
	s_waitcnt lgkmcnt(8)
	v_pk_fma_f32 v[4:5], v[58:59], v[128:129], v[8:9] op_sel_hi:[0,1,1] neg_lo:[1,0,0] neg_hi:[1,0,0]
	v_pk_fma_f32 v[6:7], v[162:163], v[130:131], v[10:11] op_sel_hi:[0,1,1] neg_lo:[1,0,0] neg_hi:[1,0,0]
	ds_read_b128 v[128:131], v69 offset:41344
	v_pk_add_f32 v[166:167], v[4:5], v[6:7]
	s_waitcnt lgkmcnt(8)
	v_pk_mul_f32 v[4:5], v[66:67], v[136:137] op_sel_hi:[0,1]
	v_pk_fma_f32 v[0:1], v[174:175], v[0:1], v[4:5] neg_lo:[0,0,1] neg_hi:[0,0,1]
	v_pk_fma_f32 v[8:9], v[158:159], v[138:139], 0 op_sel_hi:[0,1,0] neg_lo:[1,0,0] neg_hi:[1,0,0]
	ds_read_b128 v[136:139], v69 offset:41360
	s_waitcnt lgkmcnt(8)
	v_pk_fma_f32 v[0:1], v[60:61], v[238:239], v[0:1] op_sel_hi:[0,1,1] neg_lo:[1,0,0] neg_hi:[1,0,0]
	v_pk_fma_f32 v[8:9], v[62:63], v[240:241], v[8:9] op_sel_hi:[0,1,1] neg_lo:[1,0,0] neg_hi:[1,0,0]
	ds_read_b128 v[238:241], v69 offset:41376
	s_waitcnt lgkmcnt(8)
	v_pk_fma_f32 v[0:1], v[56:57], v[132:133], v[0:1] op_sel_hi:[0,1,1] neg_lo:[1,0,0] neg_hi:[1,0,0]
	v_pk_fma_f32 v[8:9], v[160:161], v[134:135], v[8:9] op_sel_hi:[0,1,1] neg_lo:[1,0,0] neg_hi:[1,0,0]
	ds_read_b128 v[132:135], v69 offset:41392
	s_waitcnt lgkmcnt(8)
	v_pk_fma_f32 v[0:1], v[58:59], v[242:243], v[0:1] op_sel_hi:[0,1,1] neg_lo:[1,0,0] neg_hi:[1,0,0]
	v_pk_fma_f32 v[4:5], v[162:163], v[244:245], v[8:9] op_sel_hi:[0,1,1] neg_lo:[1,0,0] neg_hi:[1,0,0]
	ds_read_b128 v[242:245], v69 offset:41888
	v_pk_add_f32 v[168:169], v[0:1], v[4:5]
	s_waitcnt lgkmcnt(8)
	v_pk_mul_f32 v[0:1], v[66:67], v[112:113] op_sel_hi:[0,1]
	v_pk_fma_f32 v[4:5], v[176:177], v[2:3], v[0:1] neg_lo:[0,0,1] neg_hi:[0,0,1]
	v_pk_fma_f32 v[6:7], v[158:159], v[114:115], 0 op_sel_hi:[0,1,0] neg_lo:[1,0,0] neg_hi:[1,0,0]
	ds_read_b128 v[112:115], v69 offset:41904
	s_waitcnt lgkmcnt(8)
	v_pk_fma_f32 v[4:5], v[60:61], v[116:117], v[4:5] op_sel_hi:[0,1,1] neg_lo:[1,0,0] neg_hi:[1,0,0]
	v_pk_fma_f32 v[6:7], v[62:63], v[118:119], v[6:7] op_sel_hi:[0,1,1] neg_lo:[1,0,0] neg_hi:[1,0,0]
	ds_read_b128 v[116:119], v69 offset:41920
	s_waitcnt lgkmcnt(8)
	v_pk_fma_f32 v[4:5], v[56:57], v[120:121], v[4:5] op_sel_hi:[0,1,1] neg_lo:[1,0,0] neg_hi:[1,0,0]
	v_pk_fma_f32 v[6:7], v[160:161], v[122:123], v[6:7] op_sel_hi:[0,1,1] neg_lo:[1,0,0] neg_hi:[1,0,0]
	ds_read_b128 v[120:123], v69 offset:41936
	s_waitcnt lgkmcnt(8)
	v_pk_fma_f32 v[0:1], v[58:59], v[124:125], v[4:5] op_sel_hi:[0,1,1] neg_lo:[1,0,0] neg_hi:[1,0,0]
	v_pk_fma_f32 v[2:3], v[162:163], v[126:127], v[6:7] op_sel_hi:[0,1,1] neg_lo:[1,0,0] neg_hi:[1,0,0]
	ds_read_b128 v[124:127], v69 offset:42432
	v_pk_add_f32 v[170:171], v[0:1], v[2:3]
	s_waitcnt lgkmcnt(8)
	v_pk_mul_f32 v[0:1], v[66:67], v[128:129] op_sel_hi:[0,1]
	v_pk_fma_f32 v[4:5], v[184:185], v[16:17], v[0:1] neg_lo:[0,0,1] neg_hi:[0,0,1]
	v_pk_fma_f32 v[6:7], v[158:159], v[130:131], 0 op_sel_hi:[0,1,0] neg_lo:[1,0,0] neg_hi:[1,0,0]
	ds_read_b128 v[128:131], v69 offset:42448
	s_waitcnt lgkmcnt(8)
	v_pk_fma_f32 v[4:5], v[60:61], v[136:137], v[4:5] op_sel_hi:[0,1,1] neg_lo:[1,0,0] neg_hi:[1,0,0]
	v_pk_fma_f32 v[6:7], v[62:63], v[138:139], v[6:7] op_sel_hi:[0,1,1] neg_lo:[1,0,0] neg_hi:[1,0,0]
	ds_read_b128 v[136:139], v69 offset:42464
	s_waitcnt lgkmcnt(8)
	v_pk_fma_f32 v[4:5], v[56:57], v[238:239], v[4:5] op_sel_hi:[0,1,1] neg_lo:[1,0,0] neg_hi:[1,0,0]
	v_pk_fma_f32 v[6:7], v[160:161], v[240:241], v[6:7] op_sel_hi:[0,1,1] neg_lo:[1,0,0] neg_hi:[1,0,0]
	ds_read_b128 v[238:241], v69 offset:42480
	s_waitcnt lgkmcnt(8)
	v_pk_fma_f32 v[0:1], v[58:59], v[132:133], v[4:5] op_sel_hi:[0,1,1] neg_lo:[1,0,0] neg_hi:[1,0,0]
	v_pk_fma_f32 v[2:3], v[162:163], v[134:135], v[6:7] op_sel_hi:[0,1,1] neg_lo:[1,0,0] neg_hi:[1,0,0]
	ds_read_b128 v[132:135], v69 offset:42976
	v_pk_add_f32 v[16:17], v[0:1], v[2:3]
	s_waitcnt lgkmcnt(8)
	v_pk_mul_f32 v[0:1], v[66:67], v[242:243] op_sel_hi:[0,1]
	v_pk_fma_f32 v[4:5], v[186:187], v[18:19], v[0:1] neg_lo:[0,0,1] neg_hi:[0,0,1]
	v_pk_fma_f32 v[6:7], v[158:159], v[244:245], 0 op_sel_hi:[0,1,0] neg_lo:[1,0,0] neg_hi:[1,0,0]
	ds_read_b128 v[242:245], v69 offset:42992
	s_waitcnt lgkmcnt(8)
	v_pk_fma_f32 v[4:5], v[60:61], v[112:113], v[4:5] op_sel_hi:[0,1,1] neg_lo:[1,0,0] neg_hi:[1,0,0]
	v_pk_fma_f32 v[6:7], v[62:63], v[114:115], v[6:7] op_sel_hi:[0,1,1] neg_lo:[1,0,0] neg_hi:[1,0,0]
	ds_read_b128 v[112:115], v69 offset:43008
	s_waitcnt lgkmcnt(8)
	v_pk_fma_f32 v[4:5], v[56:57], v[116:117], v[4:5] op_sel_hi:[0,1,1] neg_lo:[1,0,0] neg_hi:[1,0,0]
	v_pk_fma_f32 v[6:7], v[160:161], v[118:119], v[6:7] op_sel_hi:[0,1,1] neg_lo:[1,0,0] neg_hi:[1,0,0]
	ds_read_b128 v[116:119], v69 offset:43024
	s_waitcnt lgkmcnt(8)
	v_pk_fma_f32 v[0:1], v[58:59], v[120:121], v[4:5] op_sel_hi:[0,1,1] neg_lo:[1,0,0] neg_hi:[1,0,0]
	v_pk_fma_f32 v[2:3], v[162:163], v[122:123], v[6:7] op_sel_hi:[0,1,1] neg_lo:[1,0,0] neg_hi:[1,0,0]
	ds_read_b128 v[120:123], v69 offset:43520
	v_pk_add_f32 v[18:19], v[0:1], v[2:3]
	s_waitcnt lgkmcnt(8)
	v_pk_mul_f32 v[0:1], v[66:67], v[124:125] op_sel_hi:[0,1]
	v_pk_fma_f32 v[4:5], v[190:191], v[12:13], v[0:1] neg_lo:[0,0,1] neg_hi:[0,0,1]
	v_pk_fma_f32 v[6:7], v[158:159], v[126:127], 0 op_sel_hi:[0,1,0] neg_lo:[1,0,0] neg_hi:[1,0,0]
	ds_read_b128 v[124:127], v69 offset:43536
	s_waitcnt lgkmcnt(8)
	v_pk_fma_f32 v[4:5], v[60:61], v[128:129], v[4:5] op_sel_hi:[0,1,1] neg_lo:[1,0,0] neg_hi:[1,0,0]
	v_pk_fma_f32 v[6:7], v[62:63], v[130:131], v[6:7] op_sel_hi:[0,1,1] neg_lo:[1,0,0] neg_hi:[1,0,0]
	ds_read_b128 v[128:131], v69 offset:43552
	s_waitcnt lgkmcnt(8)
; #define LAS __attribute__((address_space(3)))
; DI void gdn_prep_phase(const int tid, LAS unsigned char* lds, const P& p, int G, int c) {
;     ...
;           for (int kb = 0; kb < 8; ++kb) {
; #pragma unroll
;               for (int pp = 0; pp < 4; ++pp) { const int pr = 4 * kb + pp;
;                   f32x2 s = (f32x2){xs[2 * pr], xs[2 * pr + 1]};
; #pragma unroll
;                   for (int j = 8 * kb; j < 2 * pr; j += 2) { const f32x4 l = *(const LAS f32x4*)(Ls + pr * 136 + j * 2);
;                       s -= (f32x2){l[0], l[1]} * (f32x2){xs[j], xs[j]}; s -= (f32x2){l[2], l[3]} * (f32x2){xs[j + 1], xs[j + 1]}; }
;                   xs[2 * pr] = s[0];
;                   xs[2 * pr + 1] = s[1] - Ls[pr * 136 + 4 * pr + 1] * s[0]; }
; #pragma unroll
;               for (int pr = 4 * kb + 4; pr < 32; ++pr) {
;                   f32x2 s0 = (f32x2){xs[2 * pr], xs[2 * pr + 1]}, s1 = (f32x2){0.f, 0.f};
; #pragma unroll
;                   for (int q = 0; q < 4; ++q) { const int j = 8 * kb + 2 * q; const f32x4 l = *(const LAS f32x4*)(Ls + pr * 136 + j * 2);
;                       s0 -= (f32x2){l[0], l[1]} * (f32x2){xs[j], xs[j]}; s1 -= (f32x2){l[2], l[3]} * (f32x2){xs[j + 1], xs[j + 1]}; }
;                   const f32x2 s = s0 + s1; xs[2 * pr] = s[0]; xs[2 * pr + 1] = s[1]; }
	v_pk_fma_f32 v[4:5], v[56:57], v[136:137], v[4:5] op_sel_hi:[0,1,1] neg_lo:[1,0,0] neg_hi:[1,0,0]
	v_pk_fma_f32 v[6:7], v[160:161], v[138:139], v[6:7] op_sel_hi:[0,1,1] neg_lo:[1,0,0] neg_hi:[1,0,0]
	ds_read_b128 v[136:139], v69 offset:43568
	s_waitcnt lgkmcnt(8)
	v_pk_fma_f32 v[0:1], v[58:59], v[238:239], v[4:5] op_sel_hi:[0,1,1] neg_lo:[1,0,0] neg_hi:[1,0,0]
	v_pk_fma_f32 v[2:3], v[162:163], v[240:241], v[6:7] op_sel_hi:[0,1,1] neg_lo:[1,0,0] neg_hi:[1,0,0]
	ds_read_b128 v[238:241], v69 offset:44064
	v_pk_add_f32 v[172:173], v[0:1], v[2:3]
	s_waitcnt lgkmcnt(8)
	v_pk_mul_f32 v[0:1], v[66:67], v[132:133] op_sel_hi:[0,1]
	v_pk_fma_f32 v[4:5], v[192:193], v[14:15], v[0:1] neg_lo:[0,0,1] neg_hi:[0,0,1]
	v_pk_fma_f32 v[6:7], v[158:159], v[134:135], 0 op_sel_hi:[0,1,0] neg_lo:[1,0,0] neg_hi:[1,0,0]
	ds_read_b128 v[132:135], v69 offset:44080
	s_waitcnt lgkmcnt(8)
	v_pk_fma_f32 v[4:5], v[60:61], v[242:243], v[4:5] op_sel_hi:[0,1,1] neg_lo:[1,0,0] neg_hi:[1,0,0]
	v_pk_fma_f32 v[6:7], v[62:63], v[244:245], v[6:7] op_sel_hi:[0,1,1] neg_lo:[1,0,0] neg_hi:[1,0,0]
	ds_read_b128 v[242:245], v69 offset:44096
	s_waitcnt lgkmcnt(8)
	v_pk_fma_f32 v[4:5], v[56:57], v[112:113], v[4:5] op_sel_hi:[0,1,1] neg_lo:[1,0,0] neg_hi:[1,0,0]
	v_pk_fma_f32 v[6:7], v[160:161], v[114:115], v[6:7] op_sel_hi:[0,1,1] neg_lo:[1,0,0] neg_hi:[1,0,0]
	ds_read_b128 v[112:115], v69 offset:44112
	s_waitcnt lgkmcnt(8)
	v_pk_fma_f32 v[0:1], v[58:59], v[116:117], v[4:5] op_sel_hi:[0,1,1] neg_lo:[1,0,0] neg_hi:[1,0,0]
	v_pk_fma_f32 v[2:3], v[162:163], v[118:119], v[6:7] op_sel_hi:[0,1,1] neg_lo:[1,0,0] neg_hi:[1,0,0]
	ds_read_b128 v[116:119], v69 offset:44608
	v_pk_add_f32 v[174:175], v[0:1], v[2:3]
	s_waitcnt lgkmcnt(8)
	v_pk_mul_f32 v[0:1], v[66:67], v[120:121] op_sel_hi:[0,1]
	v_pk_fma_f32 v[4:5], v[194:195], v[36:37], v[0:1] neg_lo:[0,0,1] neg_hi:[0,0,1]
	v_pk_fma_f32 v[6:7], v[158:159], v[122:123], 0 op_sel_hi:[0,1,0] neg_lo:[1,0,0] neg_hi:[1,0,0]
	ds_read_b128 v[120:123], v69 offset:44624
	s_waitcnt lgkmcnt(8)
	v_pk_fma_f32 v[4:5], v[60:61], v[124:125], v[4:5] op_sel_hi:[0,1,1] neg_lo:[1,0,0] neg_hi:[1,0,0]
	v_pk_fma_f32 v[6:7], v[62:63], v[126:127], v[6:7] op_sel_hi:[0,1,1] neg_lo:[1,0,0] neg_hi:[1,0,0]
	ds_read_b128 v[124:127], v69 offset:44640
	s_waitcnt lgkmcnt(8)
	v_pk_fma_f32 v[4:5], v[56:57], v[128:129], v[4:5] op_sel_hi:[0,1,1] neg_lo:[1,0,0] neg_hi:[1,0,0]
	v_pk_fma_f32 v[6:7], v[160:161], v[130:131], v[6:7] op_sel_hi:[0,1,1] neg_lo:[1,0,0] neg_hi:[1,0,0]
	ds_read_b128 v[128:131], v69 offset:44656
	s_waitcnt lgkmcnt(8)
	v_pk_fma_f32 v[0:1], v[58:59], v[136:137], v[4:5] op_sel_hi:[0,1,1] neg_lo:[1,0,0] neg_hi:[1,0,0]
	v_pk_fma_f32 v[2:3], v[162:163], v[138:139], v[6:7] op_sel_hi:[0,1,1] neg_lo:[1,0,0] neg_hi:[1,0,0]
	ds_read_b128 v[136:139], v69 offset:45152
	v_pk_add_f32 v[36:37], v[0:1], v[2:3]
	s_waitcnt lgkmcnt(8)
	v_pk_mul_f32 v[0:1], v[66:67], v[238:239] op_sel_hi:[0,1]
	v_pk_fma_f32 v[4:5], v[196:197], v[38:39], v[0:1] neg_lo:[0,0,1] neg_hi:[0,0,1]
	v_pk_fma_f32 v[6:7], v[158:159], v[240:241], 0 op_sel_hi:[0,1,0] neg_lo:[1,0,0] neg_hi:[1,0,0]
	ds_read_b128 v[238:241], v69 offset:45168
	s_waitcnt lgkmcnt(8)
	v_pk_fma_f32 v[4:5], v[60:61], v[132:133], v[4:5] op_sel_hi:[0,1,1] neg_lo:[1,0,0] neg_hi:[1,0,0]
	v_pk_fma_f32 v[6:7], v[62:63], v[134:135], v[6:7] op_sel_hi:[0,1,1] neg_lo:[1,0,0] neg_hi:[1,0,0]
	ds_read_b128 v[132:135], v69 offset:45184
	s_waitcnt lgkmcnt(8)
	v_pk_fma_f32 v[4:5], v[56:57], v[242:243], v[4:5] op_sel_hi:[0,1,1] neg_lo:[1,0,0] neg_hi:[1,0,0]
	v_pk_fma_f32 v[6:7], v[160:161], v[244:245], v[6:7] op_sel_hi:[0,1,1] neg_lo:[1,0,0] neg_hi:[1,0,0]
	ds_read_b128 v[242:245], v69 offset:45200
	s_waitcnt lgkmcnt(8)
	v_pk_fma_f32 v[0:1], v[58:59], v[112:113], v[4:5] op_sel_hi:[0,1,1] neg_lo:[1,0,0] neg_hi:[1,0,0]
	v_pk_fma_f32 v[2:3], v[162:163], v[114:115], v[6:7] op_sel_hi:[0,1,1] neg_lo:[1,0,0] neg_hi:[1,0,0]
	ds_read_b128 v[112:115], v69 offset:45696
	v_pk_add_f32 v[38:39], v[0:1], v[2:3]
	s_waitcnt lgkmcnt(8)
	v_pk_mul_f32 v[0:1], v[66:67], v[116:117] op_sel_hi:[0,1]
	v_pk_fma_f32 v[4:5], v[198:199], v[24:25], v[0:1] neg_lo:[0,0,1] neg_hi:[0,0,1]
	v_pk_fma_f32 v[6:7], v[158:159], v[118:119], 0 op_sel_hi:[0,1,0] neg_lo:[1,0,0] neg_hi:[1,0,0]
	ds_read_b128 v[116:119], v69 offset:45712
	s_waitcnt lgkmcnt(8)
	v_pk_fma_f32 v[4:5], v[60:61], v[120:121], v[4:5] op_sel_hi:[0,1,1] neg_lo:[1,0,0] neg_hi:[1,0,0]
	v_pk_fma_f32 v[6:7], v[62:63], v[122:123], v[6:7] op_sel_hi:[0,1,1] neg_lo:[1,0,0] neg_hi:[1,0,0]
	ds_read_b128 v[120:123], v69 offset:45728
	s_waitcnt lgkmcnt(8)
	v_pk_fma_f32 v[4:5], v[56:57], v[124:125], v[4:5] op_sel_hi:[0,1,1] neg_lo:[1,0,0] neg_hi:[1,0,0]
	v_pk_fma_f32 v[6:7], v[160:161], v[126:127], v[6:7] op_sel_hi:[0,1,1] neg_lo:[1,0,0] neg_hi:[1,0,0]
	ds_read_b128 v[124:127], v69 offset:45744
	s_waitcnt lgkmcnt(8)
	v_pk_fma_f32 v[0:1], v[58:59], v[128:129], v[4:5] op_sel_hi:[0,1,1] neg_lo:[1,0,0] neg_hi:[1,0,0]
	v_pk_fma_f32 v[2:3], v[162:163], v[130:131], v[6:7] op_sel_hi:[0,1,1] neg_lo:[1,0,0] neg_hi:[1,0,0]
	ds_read_b128 v[128:131], v69 offset:46240
	v_pk_add_f32 v[24:25], v[0:1], v[2:3]
	s_waitcnt lgkmcnt(8)
	v_pk_mul_f32 v[0:1], v[66:67], v[136:137] op_sel_hi:[0,1]
	v_pk_fma_f32 v[4:5], v[200:201], v[26:27], v[0:1] neg_lo:[0,0,1] neg_hi:[0,0,1]
	v_pk_fma_f32 v[6:7], v[158:159], v[138:139], 0 op_sel_hi:[0,1,0] neg_lo:[1,0,0] neg_hi:[1,0,0]
	ds_read_b128 v[136:139], v69 offset:46256
	s_waitcnt lgkmcnt(8)
	v_pk_fma_f32 v[4:5], v[60:61], v[238:239], v[4:5] op_sel_hi:[0,1,1] neg_lo:[1,0,0] neg_hi:[1,0,0]
	v_pk_fma_f32 v[6:7], v[62:63], v[240:241], v[6:7] op_sel_hi:[0,1,1] neg_lo:[1,0,0] neg_hi:[1,0,0]
	ds_read_b128 v[238:241], v69 offset:46272
	s_waitcnt lgkmcnt(8)
; #define LAS __attribute__((address_space(3)))
; DI void gdn_prep_phase(const int tid, LAS unsigned char* lds, const P& p, int G, int c) {
;     ...
;           for (int kb = 0; kb < 8; ++kb) {
; #pragma unroll
;               for (int pp = 0; pp < 4; ++pp) { const int pr = 4 * kb + pp;
;                   f32x2 s = (f32x2){xs[2 * pr], xs[2 * pr + 1]};
; #pragma unroll
;                   for (int j = 8 * kb; j < 2 * pr; j += 2) { const f32x4 l = *(const LAS f32x4*)(Ls + pr * 136 + j * 2);
;                       s -= (f32x2){l[0], l[1]} * (f32x2){xs[j], xs[j]}; s -= (f32x2){l[2], l[3]} * (f32x2){xs[j + 1], xs[j + 1]}; }
;                   xs[2 * pr] = s[0];
;                   xs[2 * pr + 1] = s[1] - Ls[pr * 136 + 4 * pr + 1] * s[0]; }
; #pragma unroll
;               for (int pr = 4 * kb + 4; pr < 32; ++pr) {
;                   f32x2 s0 = (f32x2){xs[2 * pr], xs[2 * pr + 1]}, s1 = (f32x2){0.f, 0.f};
; #pragma unroll
;                   for (int q = 0; q < 4; ++q) { const int j = 8 * kb + 2 * q; const f32x4 l = *(const LAS f32x4*)(Ls + pr * 136 + j * 2);
;                       s0 -= (f32x2){l[0], l[1]} * (f32x2){xs[j], xs[j]}; s1 -= (f32x2){l[2], l[3]} * (f32x2){xs[j + 1], xs[j + 1]}; }
;                   const f32x2 s = s0 + s1; xs[2 * pr] = s[0]; xs[2 * pr + 1] = s[1]; }
	v_pk_fma_f32 v[4:5], v[56:57], v[132:133], v[4:5] op_sel_hi:[0,1,1] neg_lo:[1,0,0] neg_hi:[1,0,0]
	v_pk_fma_f32 v[6:7], v[160:161], v[134:135], v[6:7] op_sel_hi:[0,1,1] neg_lo:[1,0,0] neg_hi:[1,0,0]
	ds_read_b128 v[132:135], v69 offset:46288
	s_waitcnt lgkmcnt(8)
	v_pk_fma_f32 v[0:1], v[58:59], v[242:243], v[4:5] op_sel_hi:[0,1,1] neg_lo:[1,0,0] neg_hi:[1,0,0]
	v_pk_fma_f32 v[2:3], v[162:163], v[244:245], v[6:7] op_sel_hi:[0,1,1] neg_lo:[1,0,0] neg_hi:[1,0,0]
	ds_read_b128 v[242:245], v69 offset:46784
	v_pk_add_f32 v[26:27], v[0:1], v[2:3]
	s_waitcnt lgkmcnt(8)
	v_pk_mul_f32 v[0:1], v[66:67], v[112:113] op_sel_hi:[0,1]
	v_pk_fma_f32 v[4:5], v[202:203], v[40:41], v[0:1] neg_lo:[0,0,1] neg_hi:[0,0,1]
	v_pk_fma_f32 v[6:7], v[158:159], v[114:115], 0 op_sel_hi:[0,1,0] neg_lo:[1,0,0] neg_hi:[1,0,0]
	ds_read_b128 v[112:115], v69 offset:46800
	s_waitcnt lgkmcnt(8)
	v_pk_fma_f32 v[4:5], v[60:61], v[116:117], v[4:5] op_sel_hi:[0,1,1] neg_lo:[1,0,0] neg_hi:[1,0,0]
	v_pk_fma_f32 v[6:7], v[62:63], v[118:119], v[6:7] op_sel_hi:[0,1,1] neg_lo:[1,0,0] neg_hi:[1,0,0]
	ds_read_b128 v[116:119], v69 offset:46816
	s_waitcnt lgkmcnt(8)
	v_pk_fma_f32 v[4:5], v[56:57], v[120:121], v[4:5] op_sel_hi:[0,1,1] neg_lo:[1,0,0] neg_hi:[1,0,0]
	v_pk_fma_f32 v[6:7], v[160:161], v[122:123], v[6:7] op_sel_hi:[0,1,1] neg_lo:[1,0,0] neg_hi:[1,0,0]
	ds_read_b128 v[120:123], v69 offset:46832
	s_waitcnt lgkmcnt(8)
	v_pk_fma_f32 v[0:1], v[58:59], v[124:125], v[4:5] op_sel_hi:[0,1,1] neg_lo:[1,0,0] neg_hi:[1,0,0]
	v_pk_fma_f32 v[2:3], v[162:163], v[126:127], v[6:7] op_sel_hi:[0,1,1] neg_lo:[1,0,0] neg_hi:[1,0,0]
	ds_read_b128 v[124:127], v69 offset:47328
	v_pk_add_f32 v[40:41], v[0:1], v[2:3]
	s_waitcnt lgkmcnt(8)
	v_pk_mul_f32 v[0:1], v[66:67], v[128:129] op_sel_hi:[0,1]
	v_pk_fma_f32 v[4:5], v[204:205], v[42:43], v[0:1] neg_lo:[0,0,1] neg_hi:[0,0,1]
	v_pk_fma_f32 v[6:7], v[158:159], v[130:131], 0 op_sel_hi:[0,1,0] neg_lo:[1,0,0] neg_hi:[1,0,0]
	ds_read_b128 v[128:131], v69 offset:47344
	s_waitcnt lgkmcnt(8)
	v_pk_fma_f32 v[4:5], v[60:61], v[136:137], v[4:5] op_sel_hi:[0,1,1] neg_lo:[1,0,0] neg_hi:[1,0,0]
	v_pk_fma_f32 v[6:7], v[62:63], v[138:139], v[6:7] op_sel_hi:[0,1,1] neg_lo:[1,0,0] neg_hi:[1,0,0]
	ds_read_b128 v[136:139], v69 offset:47360
	s_waitcnt lgkmcnt(8)
	v_pk_fma_f32 v[4:5], v[56:57], v[238:239], v[4:5] op_sel_hi:[0,1,1] neg_lo:[1,0,0] neg_hi:[1,0,0]
	v_pk_fma_f32 v[6:7], v[160:161], v[240:241], v[6:7] op_sel_hi:[0,1,1] neg_lo:[1,0,0] neg_hi:[1,0,0]
	ds_read_b128 v[238:241], v69 offset:47376
	s_waitcnt lgkmcnt(8)
	v_pk_fma_f32 v[0:1], v[58:59], v[132:133], v[4:5] op_sel_hi:[0,1,1] neg_lo:[1,0,0] neg_hi:[1,0,0]
	v_pk_fma_f32 v[2:3], v[162:163], v[134:135], v[6:7] op_sel_hi:[0,1,1] neg_lo:[1,0,0] neg_hi:[1,0,0]
	ds_read_b128 v[132:135], v69 offset:47872
	v_pk_add_f32 v[42:43], v[0:1], v[2:3]
	s_waitcnt lgkmcnt(8)
	v_pk_mul_f32 v[0:1], v[66:67], v[242:243] op_sel_hi:[0,1]
	v_pk_fma_f32 v[4:5], v[206:207], v[32:33], v[0:1] neg_lo:[0,0,1] neg_hi:[0,0,1]
	v_pk_fma_f32 v[6:7], v[158:159], v[244:245], 0 op_sel_hi:[0,1,0] neg_lo:[1,0,0] neg_hi:[1,0,0]
	ds_read_b128 v[242:245], v69 offset:47888
	s_waitcnt lgkmcnt(8)
	v_pk_fma_f32 v[4:5], v[60:61], v[112:113], v[4:5] op_sel_hi:[0,1,1] neg_lo:[1,0,0] neg_hi:[1,0,0]
	v_pk_fma_f32 v[6:7], v[62:63], v[114:115], v[6:7] op_sel_hi:[0,1,1] neg_lo:[1,0,0] neg_hi:[1,0,0]
	ds_read_b128 v[112:115], v69 offset:47904
	s_waitcnt lgkmcnt(8)
	v_pk_fma_f32 v[4:5], v[56:57], v[116:117], v[4:5] op_sel_hi:[0,1,1] neg_lo:[1,0,0] neg_hi:[1,0,0]
	v_pk_fma_f32 v[6:7], v[160:161], v[118:119], v[6:7] op_sel_hi:[0,1,1] neg_lo:[1,0,0] neg_hi:[1,0,0]
	ds_read_b128 v[116:119], v69 offset:47920
	s_waitcnt lgkmcnt(8)
	v_pk_fma_f32 v[0:1], v[58:59], v[120:121], v[4:5] op_sel_hi:[0,1,1] neg_lo:[1,0,0] neg_hi:[1,0,0]
	v_pk_fma_f32 v[2:3], v[162:163], v[122:123], v[6:7] op_sel_hi:[0,1,1] neg_lo:[1,0,0] neg_hi:[1,0,0]
	ds_read_b128 v[120:123], v69 offset:48416
	v_pk_add_f32 v[32:33], v[0:1], v[2:3]
	s_waitcnt lgkmcnt(8)
	v_pk_mul_f32 v[0:1], v[66:67], v[124:125] op_sel_hi:[0,1]
	v_pk_fma_f32 v[4:5], v[208:209], v[34:35], v[0:1] neg_lo:[0,0,1] neg_hi:[0,0,1]
	v_pk_fma_f32 v[6:7], v[158:159], v[126:127], 0 op_sel_hi:[0,1,0] neg_lo:[1,0,0] neg_hi:[1,0,0]
	ds_read_b128 v[124:127], v69 offset:48432
	s_waitcnt lgkmcnt(8)
	v_pk_fma_f32 v[4:5], v[60:61], v[128:129], v[4:5] op_sel_hi:[0,1,1] neg_lo:[1,0,0] neg_hi:[1,0,0]
	v_pk_fma_f32 v[6:7], v[62:63], v[130:131], v[6:7] op_sel_hi:[0,1,1] neg_lo:[1,0,0] neg_hi:[1,0,0]
	ds_read_b128 v[128:131], v69 offset:48448
	s_waitcnt lgkmcnt(8)
	v_pk_fma_f32 v[4:5], v[56:57], v[136:137], v[4:5] op_sel_hi:[0,1,1] neg_lo:[1,0,0] neg_hi:[1,0,0]
	v_pk_fma_f32 v[6:7], v[160:161], v[138:139], v[6:7] op_sel_hi:[0,1,1] neg_lo:[1,0,0] neg_hi:[1,0,0]
	ds_read_b128 v[136:139], v69 offset:48464
	s_waitcnt lgkmcnt(8)
	v_pk_fma_f32 v[0:1], v[58:59], v[238:239], v[4:5] op_sel_hi:[0,1,1] neg_lo:[1,0,0] neg_hi:[1,0,0]
	v_pk_fma_f32 v[2:3], v[162:163], v[240:241], v[6:7] op_sel_hi:[0,1,1] neg_lo:[1,0,0] neg_hi:[1,0,0]
	ds_read_b128 v[238:241], v69 offset:48960
	v_pk_add_f32 v[34:35], v[0:1], v[2:3]
	s_waitcnt lgkmcnt(8)
	v_pk_mul_f32 v[0:1], v[66:67], v[132:133] op_sel_hi:[0,1]
	v_pk_fma_f32 v[4:5], v[210:211], v[28:29], v[0:1] neg_lo:[0,0,1] neg_hi:[0,0,1]
	v_pk_fma_f32 v[6:7], v[158:159], v[134:135], 0 op_sel_hi:[0,1,0] neg_lo:[1,0,0] neg_hi:[1,0,0]
	ds_read_b128 v[132:135], v69 offset:48976
	s_waitcnt lgkmcnt(8)
	v_pk_fma_f32 v[4:5], v[60:61], v[242:243], v[4:5] op_sel_hi:[0,1,1] neg_lo:[1,0,0] neg_hi:[1,0,0]
	v_pk_fma_f32 v[6:7], v[62:63], v[244:245], v[6:7] op_sel_hi:[0,1,1] neg_lo:[1,0,0] neg_hi:[1,0,0]
	ds_read_b128 v[242:245], v69 offset:48992
	s_waitcnt lgkmcnt(8)
; #define LAS __attribute__((address_space(3)))
; DI void gdn_prep_phase(const int tid, LAS unsigned char* lds, const P& p, int G, int c) {
;     ...
;           for (int kb = 0; kb < 8; ++kb) {
; #pragma unroll
;               for (int pp = 0; pp < 4; ++pp) { const int pr = 4 * kb + pp;
;                   f32x2 s = (f32x2){xs[2 * pr], xs[2 * pr + 1]};
; #pragma unroll
;                   for (int j = 8 * kb; j < 2 * pr; j += 2) { const f32x4 l = *(const LAS f32x4*)(Ls + pr * 136 + j * 2);
;                       s -= (f32x2){l[0], l[1]} * (f32x2){xs[j], xs[j]}; s -= (f32x2){l[2], l[3]} * (f32x2){xs[j + 1], xs[j + 1]}; }
;                   xs[2 * pr] = s[0];
;                   xs[2 * pr + 1] = s[1] - Ls[pr * 136 + 4 * pr + 1] * s[0]; }
; #pragma unroll
;               for (int pr = 4 * kb + 4; pr < 32; ++pr) {
;                   f32x2 s0 = (f32x2){xs[2 * pr], xs[2 * pr + 1]}, s1 = (f32x2){0.f, 0.f};
; #pragma unroll
;                   for (int q = 0; q < 4; ++q) { const int j = 8 * kb + 2 * q; const f32x4 l = *(const LAS f32x4*)(Ls + pr * 136 + j * 2);
;                       s0 -= (f32x2){l[0], l[1]} * (f32x2){xs[j], xs[j]}; s1 -= (f32x2){l[2], l[3]} * (f32x2){xs[j + 1], xs[j + 1]}; }
;                   const f32x2 s = s0 + s1; xs[2 * pr] = s[0]; xs[2 * pr + 1] = s[1]; }
	v_pk_fma_f32 v[4:5], v[56:57], v[112:113], v[4:5] op_sel_hi:[0,1,1] neg_lo:[1,0,0] neg_hi:[1,0,0]
	v_pk_fma_f32 v[6:7], v[160:161], v[114:115], v[6:7] op_sel_hi:[0,1,1] neg_lo:[1,0,0] neg_hi:[1,0,0]
	ds_read_b128 v[112:115], v69 offset:49008
	s_waitcnt lgkmcnt(8)
	v_pk_fma_f32 v[0:1], v[58:59], v[116:117], v[4:5] op_sel_hi:[0,1,1] neg_lo:[1,0,0] neg_hi:[1,0,0]
	v_pk_fma_f32 v[2:3], v[162:163], v[118:119], v[6:7] op_sel_hi:[0,1,1] neg_lo:[1,0,0] neg_hi:[1,0,0]
	ds_read_b128 v[116:119], v69 offset:49504
	v_pk_add_f32 v[28:29], v[0:1], v[2:3]
	s_waitcnt lgkmcnt(8)
	v_pk_mul_f32 v[0:1], v[66:67], v[120:121] op_sel_hi:[0,1]
	v_pk_fma_f32 v[4:5], v[212:213], v[30:31], v[0:1] neg_lo:[0,0,1] neg_hi:[0,0,1]
	v_pk_fma_f32 v[6:7], v[158:159], v[122:123], 0 op_sel_hi:[0,1,0] neg_lo:[1,0,0] neg_hi:[1,0,0]
	ds_read_b128 v[120:123], v69 offset:49520
	s_waitcnt lgkmcnt(8)
	v_pk_fma_f32 v[4:5], v[60:61], v[124:125], v[4:5] op_sel_hi:[0,1,1] neg_lo:[1,0,0] neg_hi:[1,0,0]
	v_pk_fma_f32 v[6:7], v[62:63], v[126:127], v[6:7] op_sel_hi:[0,1,1] neg_lo:[1,0,0] neg_hi:[1,0,0]
	ds_read_b128 v[124:127], v69 offset:49536
	s_waitcnt lgkmcnt(8)
	v_pk_fma_f32 v[4:5], v[56:57], v[128:129], v[4:5] op_sel_hi:[0,1,1] neg_lo:[1,0,0] neg_hi:[1,0,0]
	v_pk_fma_f32 v[6:7], v[160:161], v[130:131], v[6:7] op_sel_hi:[0,1,1] neg_lo:[1,0,0] neg_hi:[1,0,0]
	ds_read_b128 v[128:131], v69 offset:49552
	s_waitcnt lgkmcnt(8)
	v_pk_fma_f32 v[0:1], v[58:59], v[136:137], v[4:5] op_sel_hi:[0,1,1] neg_lo:[1,0,0] neg_hi:[1,0,0]
	v_pk_fma_f32 v[2:3], v[162:163], v[138:139], v[6:7] op_sel_hi:[0,1,1] neg_lo:[1,0,0] neg_hi:[1,0,0]
	ds_read_b128 v[136:139], v69 offset:50048
	v_pk_add_f32 v[30:31], v[0:1], v[2:3]
	s_waitcnt lgkmcnt(8)
	v_pk_mul_f32 v[0:1], v[66:67], v[238:239] op_sel_hi:[0,1]
	v_pk_fma_f32 v[4:5], v[214:215], v[20:21], v[0:1] neg_lo:[0,0,1] neg_hi:[0,0,1]
	v_pk_fma_f32 v[6:7], v[158:159], v[240:241], 0 op_sel_hi:[0,1,0] neg_lo:[1,0,0] neg_hi:[1,0,0]
	ds_read_b128 v[238:241], v69 offset:50064
	s_waitcnt lgkmcnt(8)
	v_pk_fma_f32 v[4:5], v[60:61], v[132:133], v[4:5] op_sel_hi:[0,1,1] neg_lo:[1,0,0] neg_hi:[1,0,0]
	v_pk_fma_f32 v[6:7], v[62:63], v[134:135], v[6:7] op_sel_hi:[0,1,1] neg_lo:[1,0,0] neg_hi:[1,0,0]
	ds_read_b128 v[132:135], v69 offset:50080
	s_waitcnt lgkmcnt(8)
	v_pk_fma_f32 v[4:5], v[56:57], v[242:243], v[4:5] op_sel_hi:[0,1,1] neg_lo:[1,0,0] neg_hi:[1,0,0]
	v_pk_fma_f32 v[6:7], v[160:161], v[244:245], v[6:7] op_sel_hi:[0,1,1] neg_lo:[1,0,0] neg_hi:[1,0,0]
	ds_read_b128 v[242:245], v69 offset:50096
	s_waitcnt lgkmcnt(8)
	v_pk_fma_f32 v[0:1], v[58:59], v[112:113], v[4:5] op_sel_hi:[0,1,1] neg_lo:[1,0,0] neg_hi:[1,0,0]
	v_pk_fma_f32 v[2:3], v[162:163], v[114:115], v[6:7] op_sel_hi:[0,1,1] neg_lo:[1,0,0] neg_hi:[1,0,0]
	ds_read_b128 v[112:115], v69 offset:50592
	v_pk_add_f32 v[20:21], v[0:1], v[2:3]
	s_waitcnt lgkmcnt(8)
	v_pk_mul_f32 v[0:1], v[66:67], v[116:117] op_sel_hi:[0,1]
	v_pk_fma_f32 v[4:5], v[216:217], v[22:23], v[0:1] neg_lo:[0,0,1] neg_hi:[0,0,1]
	v_pk_fma_f32 v[6:7], v[158:159], v[118:119], 0 op_sel_hi:[0,1,0] neg_lo:[1,0,0] neg_hi:[1,0,0]
	ds_read_b128 v[116:119], v69 offset:50608
	s_waitcnt lgkmcnt(8)
	v_pk_fma_f32 v[4:5], v[60:61], v[120:121], v[4:5] op_sel_hi:[0,1,1] neg_lo:[1,0,0] neg_hi:[1,0,0]
	v_pk_fma_f32 v[6:7], v[62:63], v[122:123], v[6:7] op_sel_hi:[0,1,1] neg_lo:[1,0,0] neg_hi:[1,0,0]
	ds_read_b128 v[120:123], v69 offset:50624
	s_waitcnt lgkmcnt(8)
	v_pk_fma_f32 v[4:5], v[56:57], v[124:125], v[4:5] op_sel_hi:[0,1,1] neg_lo:[1,0,0] neg_hi:[1,0,0]
	v_pk_fma_f32 v[6:7], v[160:161], v[126:127], v[6:7] op_sel_hi:[0,1,1] neg_lo:[1,0,0] neg_hi:[1,0,0]
	ds_read_b128 v[124:127], v69 offset:50640
	s_waitcnt lgkmcnt(8)
	v_pk_fma_f32 v[0:1], v[58:59], v[128:129], v[4:5] op_sel_hi:[0,1,1] neg_lo:[1,0,0] neg_hi:[1,0,0]
	v_pk_fma_f32 v[2:3], v[162:163], v[130:131], v[6:7] op_sel_hi:[0,1,1] neg_lo:[1,0,0] neg_hi:[1,0,0]
	ds_read_b128 v[128:131], v69 offset:51136
	v_pk_add_f32 v[22:23], v[0:1], v[2:3]
	s_waitcnt lgkmcnt(8)
	v_pk_mul_f32 v[0:1], v[66:67], v[136:137] op_sel_hi:[0,1]
	v_pk_fma_f32 v[4:5], v[218:219], v[52:53], v[0:1] neg_lo:[0,0,1] neg_hi:[0,0,1]
	v_pk_fma_f32 v[6:7], v[158:159], v[138:139], 0 op_sel_hi:[0,1,0] neg_lo:[1,0,0] neg_hi:[1,0,0]
	ds_read_b128 v[136:139], v69 offset:51152
	s_waitcnt lgkmcnt(8)
	v_pk_fma_f32 v[4:5], v[60:61], v[238:239], v[4:5] op_sel_hi:[0,1,1] neg_lo:[1,0,0] neg_hi:[1,0,0]
	v_pk_fma_f32 v[6:7], v[62:63], v[240:241], v[6:7] op_sel_hi:[0,1,1] neg_lo:[1,0,0] neg_hi:[1,0,0]
	ds_read_b128 v[238:241], v69 offset:51168
	s_waitcnt lgkmcnt(8)
	v_pk_fma_f32 v[4:5], v[56:57], v[132:133], v[4:5] op_sel_hi:[0,1,1] neg_lo:[1,0,0] neg_hi:[1,0,0]
	v_pk_fma_f32 v[6:7], v[160:161], v[134:135], v[6:7] op_sel_hi:[0,1,1] neg_lo:[1,0,0] neg_hi:[1,0,0]
	ds_read_b128 v[132:135], v69 offset:51184
	s_waitcnt lgkmcnt(8)
	v_pk_fma_f32 v[0:1], v[58:59], v[242:243], v[4:5] op_sel_hi:[0,1,1] neg_lo:[1,0,0] neg_hi:[1,0,0]
	v_pk_fma_f32 v[2:3], v[162:163], v[244:245], v[6:7] op_sel_hi:[0,1,1] neg_lo:[1,0,0] neg_hi:[1,0,0]
	ds_read_b128 v[242:245], v69 offset:51680
	v_pk_add_f32 v[52:53], v[0:1], v[2:3]
	s_waitcnt lgkmcnt(8)
	v_pk_mul_f32 v[0:1], v[66:67], v[112:113] op_sel_hi:[0,1]
	v_pk_fma_f32 v[4:5], v[220:221], v[54:55], v[0:1] neg_lo:[0,0,1] neg_hi:[0,0,1]
	v_pk_fma_f32 v[6:7], v[158:159], v[114:115], 0 op_sel_hi:[0,1,0] neg_lo:[1,0,0] neg_hi:[1,0,0]
	ds_read_b128 v[112:115], v69 offset:51696
	s_waitcnt lgkmcnt(8)
	v_pk_fma_f32 v[4:5], v[60:61], v[116:117], v[4:5] op_sel_hi:[0,1,1] neg_lo:[1,0,0] neg_hi:[1,0,0]
	v_pk_fma_f32 v[6:7], v[62:63], v[118:119], v[6:7] op_sel_hi:[0,1,1] neg_lo:[1,0,0] neg_hi:[1,0,0]
	ds_read_b128 v[116:119], v69 offset:51712
	s_waitcnt lgkmcnt(8)
; #define LAS __attribute__((address_space(3)))
; DI void gdn_prep_phase(const int tid, LAS unsigned char* lds, const P& p, int G, int c) {
;     ...
;           for (int kb = 0; kb < 8; ++kb) {
; #pragma unroll
;               for (int pp = 0; pp < 4; ++pp) { const int pr = 4 * kb + pp;
;                   f32x2 s = (f32x2){xs[2 * pr], xs[2 * pr + 1]};
; #pragma unroll
;                   for (int j = 8 * kb; j < 2 * pr; j += 2) { const f32x4 l = *(const LAS f32x4*)(Ls + pr * 136 + j * 2);
;                       s -= (f32x2){l[0], l[1]} * (f32x2){xs[j], xs[j]}; s -= (f32x2){l[2], l[3]} * (f32x2){xs[j + 1], xs[j + 1]}; }
;                   xs[2 * pr] = s[0];
;                   xs[2 * pr + 1] = s[1] - Ls[pr * 136 + 4 * pr + 1] * s[0]; }
; #pragma unroll
;               for (int pr = 4 * kb + 4; pr < 32; ++pr) {
;                   f32x2 s0 = (f32x2){xs[2 * pr], xs[2 * pr + 1]}, s1 = (f32x2){0.f, 0.f};
; #pragma unroll
;                   for (int q = 0; q < 4; ++q) { const int j = 8 * kb + 2 * q; const f32x4 l = *(const LAS f32x4*)(Ls + pr * 136 + j * 2);
;                       s0 -= (f32x2){l[0], l[1]} * (f32x2){xs[j], xs[j]}; s1 -= (f32x2){l[2], l[3]} * (f32x2){xs[j + 1], xs[j + 1]}; }
;                   const f32x2 s = s0 + s1; xs[2 * pr] = s[0]; xs[2 * pr + 1] = s[1]; }
	v_pk_fma_f32 v[4:5], v[56:57], v[120:121], v[4:5] op_sel_hi:[0,1,1] neg_lo:[1,0,0] neg_hi:[1,0,0]
	v_pk_fma_f32 v[6:7], v[160:161], v[122:123], v[6:7] op_sel_hi:[0,1,1] neg_lo:[1,0,0] neg_hi:[1,0,0]
	ds_read_b128 v[120:123], v69 offset:51728
	s_waitcnt lgkmcnt(8)
	v_pk_fma_f32 v[0:1], v[58:59], v[124:125], v[4:5] op_sel_hi:[0,1,1] neg_lo:[1,0,0] neg_hi:[1,0,0]
	v_pk_fma_f32 v[2:3], v[162:163], v[126:127], v[6:7] op_sel_hi:[0,1,1] neg_lo:[1,0,0] neg_hi:[1,0,0]
	v_add_u32_e32 v141, 0x9000, v69
	ds_read2_b32 v[124:125], v141 offset0:49 offset1:189
	v_pk_add_f32 v[54:55], v[0:1], v[2:3]
	s_waitcnt lgkmcnt(8)
	v_pk_mul_f32 v[0:1], v[66:67], v[128:129] op_sel_hi:[0,1]
	v_pk_fma_f32 v[4:5], v[222:223], v[44:45], v[0:1] neg_lo:[0,0,1] neg_hi:[0,0,1]
	v_pk_fma_f32 v[6:7], v[158:159], v[130:131], 0 op_sel_hi:[0,1,0] neg_lo:[1,0,0] neg_hi:[1,0,0]
	ds_read_b128 v[128:131], v69 offset:37600
	s_waitcnt lgkmcnt(8)
	v_pk_fma_f32 v[4:5], v[60:61], v[136:137], v[4:5] op_sel_hi:[0,1,1] neg_lo:[1,0,0] neg_hi:[1,0,0]
	v_pk_fma_f32 v[6:7], v[62:63], v[138:139], v[6:7] op_sel_hi:[0,1,1] neg_lo:[1,0,0] neg_hi:[1,0,0]
	ds_read_b128 v[136:139], v69 offset:38144
	s_waitcnt lgkmcnt(8)
	v_pk_fma_f32 v[4:5], v[56:57], v[238:239], v[4:5] op_sel_hi:[0,1,1] neg_lo:[1,0,0] neg_hi:[1,0,0]
	v_pk_fma_f32 v[6:7], v[160:161], v[240:241], v[6:7] op_sel_hi:[0,1,1] neg_lo:[1,0,0] neg_hi:[1,0,0]
	ds_read_b128 v[238:241], v69 offset:38160
	s_waitcnt lgkmcnt(8)
	v_pk_fma_f32 v[0:1], v[58:59], v[132:133], v[4:5] op_sel_hi:[0,1,1] neg_lo:[1,0,0] neg_hi:[1,0,0]
	v_pk_fma_f32 v[2:3], v[162:163], v[134:135], v[6:7] op_sel_hi:[0,1,1] neg_lo:[1,0,0] neg_hi:[1,0,0]
	ds_read_b128 v[132:135], v69 offset:38688
	v_pk_add_f32 v[44:45], v[0:1], v[2:3]
	s_waitcnt lgkmcnt(8)
	v_pk_mul_f32 v[0:1], v[66:67], v[242:243] op_sel_hi:[0,1]
	v_pk_fma_f32 v[4:5], v[224:225], v[46:47], v[0:1] neg_lo:[0,0,1] neg_hi:[0,0,1]
	v_pk_fma_f32 v[6:7], v[158:159], v[244:245], 0 op_sel_hi:[0,1,0] neg_lo:[1,0,0] neg_hi:[1,0,0]
	ds_read_b128 v[242:245], v69 offset:39232
	s_waitcnt lgkmcnt(8)
	v_pk_fma_f32 v[4:5], v[60:61], v[112:113], v[4:5] op_sel_hi:[0,1,1] neg_lo:[1,0,0] neg_hi:[1,0,0]
	v_pk_fma_f32 v[6:7], v[62:63], v[114:115], v[6:7] op_sel_hi:[0,1,1] neg_lo:[1,0,0] neg_hi:[1,0,0]
	v_add_u32_e32 v183, 0x9400, v69
	ds_read2_b32 v[112:113], v183 offset0:73 offset1:213
	s_waitcnt lgkmcnt(8)
	v_pk_fma_f32 v[4:5], v[56:57], v[116:117], v[4:5] op_sel_hi:[0,1,1] neg_lo:[1,0,0] neg_hi:[1,0,0]
	v_pk_fma_f32 v[6:7], v[160:161], v[118:119], v[6:7] op_sel_hi:[0,1,1] neg_lo:[1,0,0] neg_hi:[1,0,0]
	ds_read_b128 v[116:119], v69 offset:38704
	s_waitcnt lgkmcnt(8)
	v_pk_fma_f32 v[0:1], v[58:59], v[120:121], v[4:5] op_sel_hi:[0,1,1] neg_lo:[1,0,0] neg_hi:[1,0,0]
	v_pk_fma_f32 v[2:3], v[162:163], v[122:123], v[6:7] op_sel_hi:[0,1,1] neg_lo:[1,0,0] neg_hi:[1,0,0]
	ds_read_b128 v[120:123], v69 offset:38720
	v_pk_add_f32 v[46:47], v[0:1], v[2:3]
	s_waitcnt lgkmcnt(8)
	v_fma_f32 v0, -v48, v124, v49
	s_waitcnt lgkmcnt(7)
	v_pk_fma_f32 v[2:3], v[48:49], v[128:129], v[178:179] op_sel_hi:[0,1,1] neg_lo:[1,0,0] neg_hi:[1,0,0]
	s_waitcnt lgkmcnt(6)
	v_pk_fma_f32 v[6:7], v[48:49], v[136:137], v[188:189] op_sel_hi:[0,1,1] neg_lo:[1,0,0] neg_hi:[1,0,0]
	v_pk_fma_f32 v[10:11], v[138:139], v[0:1], v[6:7] op_sel_hi:[1,0,1] neg_lo:[1,0,0] neg_hi:[1,0,0]
	ds_read_b128 v[136:139], v69 offset:39248
	v_pk_fma_f32 v[4:5], v[130:131], v[0:1], v[2:3] op_sel_hi:[1,0,1] neg_lo:[1,0,0] neg_hi:[1,0,0]
	ds_read_b128 v[128:131], v69 offset:39264
	v_fma_f32 v2, -v125, v4, v5
	ds_read_b128 v[124:127], v69 offset:39280
	s_waitcnt lgkmcnt(8)
	v_pk_fma_f32 v[6:7], v[238:239], v[4:5], v[10:11] op_sel_hi:[1,0,1] neg_lo:[1,0,0] neg_hi:[1,0,0]
	s_nop 0
	v_pk_fma_f32 v[8:9], v[240:241], v[2:3], v[6:7] op_sel_hi:[1,0,1] neg_lo:[1,0,0] neg_hi:[1,0,0]
	ds_read_b128 v[238:241], v69 offset:39776
	s_waitcnt lgkmcnt(8)
	v_pk_fma_f32 v[10:11], v[48:49], v[132:133], v[50:51] op_sel_hi:[0,1,1] neg_lo:[1,0,0] neg_hi:[1,0,0]
	v_pk_fma_f32 v[14:15], v[0:1], v[134:135], v[10:11] op_sel_hi:[0,1,1] neg_lo:[1,0,0] neg_hi:[1,0,0]
	ds_read_b128 v[132:135], v69 offset:39792
	s_waitcnt lgkmcnt(8)
	v_pk_fma_f32 v[50:51], v[0:1], v[244:245], 0 op_sel_hi:[0,1,0] neg_lo:[1,0,0] neg_hi:[1,0,0]
	s_waitcnt lgkmcnt(7)
	v_fma_f32 v6, -v112, v8, v9
	s_waitcnt lgkmcnt(6)
	v_pk_fma_f32 v[10:11], v[4:5], v[116:117], v[14:15] op_sel_hi:[0,1,1] neg_lo:[1,0,0] neg_hi:[1,0,0]
	v_pk_fma_f32 v[14:15], v[118:119], v[2:3], v[10:11] op_sel_hi:[1,0,1] neg_lo:[1,0,0] neg_hi:[1,0,0]
	ds_read_b128 v[116:119], v69 offset:39808
	s_waitcnt lgkmcnt(6)
	v_pk_fma_f32 v[10:11], v[120:121], v[8:9], v[14:15] op_sel_hi:[1,0,1] neg_lo:[1,0,0] neg_hi:[1,0,0]
	v_pk_fma_f32 v[14:15], v[48:49], v[242:243], v[164:165] op_sel_hi:[0,1,1] neg_lo:[1,0,0] neg_hi:[1,0,0]
	ds_read_b128 v[242:245], v69 offset:39824
	v_pk_fma_f32 v[12:13], v[122:123], v[6:7], v[10:11] op_sel_hi:[1,0,1] neg_lo:[1,0,0] neg_hi:[1,0,0]
	ds_read_b128 v[120:123], v69 offset:40320
	s_waitcnt lgkmcnt(7)
	v_pk_fma_f32 v[14:15], v[4:5], v[136:137], v[14:15] op_sel_hi:[0,1,1] neg_lo:[1,0,0] neg_hi:[1,0,0]
	v_pk_fma_f32 v[50:51], v[2:3], v[138:139], v[50:51] op_sel_hi:[0,1,1] neg_lo:[1,0,0] neg_hi:[1,0,0]
	ds_read_b128 v[136:139], v69 offset:40336
	v_fma_f32 v10, -v113, v12, v13
	ds_read_b128 v[112:115], v69 offset:40352
	s_waitcnt lgkmcnt(8)
	v_pk_fma_f32 v[14:15], v[128:129], v[8:9], v[14:15] op_sel_hi:[1,0,1] neg_lo:[1,0,0] neg_hi:[1,0,0]
	v_pk_fma_f32 v[50:51], v[130:131], v[6:7], v[50:51] op_sel_hi:[1,0,1] neg_lo:[1,0,0] neg_hi:[1,0,0]
	ds_read_b128 v[128:131], v69 offset:40368
	s_waitcnt lgkmcnt(8)
; #define LAS __attribute__((address_space(3)))
; DI void gdn_prep_phase(const int tid, LAS unsigned char* lds, const P& p, int G, int c) {
;     ...
;           for (int kb = 0; kb < 8; ++kb) {
; #pragma unroll
;               for (int pp = 0; pp < 4; ++pp) { const int pr = 4 * kb + pp;
;                   f32x2 s = (f32x2){xs[2 * pr], xs[2 * pr + 1]};
; #pragma unroll
;                   for (int j = 8 * kb; j < 2 * pr; j += 2) { const f32x4 l = *(const LAS f32x4*)(Ls + pr * 136 + j * 2);
;                       s -= (f32x2){l[0], l[1]} * (f32x2){xs[j], xs[j]}; s -= (f32x2){l[2], l[3]} * (f32x2){xs[j + 1], xs[j + 1]}; }
;                   xs[2 * pr] = s[0];
;                   xs[2 * pr + 1] = s[1] - Ls[pr * 136 + 4 * pr + 1] * s[0]; }
; #pragma unroll
;               for (int pr = 4 * kb + 4; pr < 32; ++pr) {
;                   f32x2 s0 = (f32x2){xs[2 * pr], xs[2 * pr + 1]}, s1 = (f32x2){0.f, 0.f};
; #pragma unroll
;                   for (int q = 0; q < 4; ++q) { const int j = 8 * kb + 2 * q; const f32x4 l = *(const LAS f32x4*)(Ls + pr * 136 + j * 2);
;                       s0 -= (f32x2){l[0], l[1]} * (f32x2){xs[j], xs[j]}; s1 -= (f32x2){l[2], l[3]} * (f32x2){xs[j + 1], xs[j + 1]}; }
;                   const f32x2 s = s0 + s1; xs[2 * pr] = s[0]; xs[2 * pr + 1] = s[1]; }
	v_pk_fma_f32 v[14:15], v[124:125], v[12:13], v[14:15] op_sel_hi:[1,0,1] neg_lo:[1,0,0] neg_hi:[1,0,0]
	v_pk_fma_f32 v[50:51], v[126:127], v[10:11], v[50:51] op_sel_hi:[1,0,1] neg_lo:[1,0,0] neg_hi:[1,0,0]
	ds_read_b128 v[124:127], v69 offset:40864
	v_pk_add_f32 v[14:15], v[14:15], v[50:51]
	s_waitcnt lgkmcnt(8)
	v_pk_fma_f32 v[50:51], v[48:49], v[238:239], v[166:167] op_sel_hi:[0,1,1] neg_lo:[1,0,0] neg_hi:[1,0,0]
	v_pk_fma_f32 v[176:177], v[0:1], v[240:241], 0 op_sel_hi:[0,1,0] neg_lo:[1,0,0] neg_hi:[1,0,0]
	ds_read_b128 v[238:241], v69 offset:40880
	s_waitcnt lgkmcnt(8)
	v_pk_fma_f32 v[50:51], v[4:5], v[132:133], v[50:51] op_sel_hi:[0,1,1] neg_lo:[1,0,0] neg_hi:[1,0,0]
	v_pk_fma_f32 v[176:177], v[2:3], v[134:135], v[176:177] op_sel_hi:[0,1,1] neg_lo:[1,0,0] neg_hi:[1,0,0]
	ds_read_b128 v[132:135], v69 offset:40896
	s_waitcnt lgkmcnt(8)
	v_pk_fma_f32 v[50:51], v[8:9], v[116:117], v[50:51] op_sel_hi:[0,1,1] neg_lo:[1,0,0] neg_hi:[1,0,0]
	v_pk_fma_f32 v[176:177], v[118:119], v[6:7], v[176:177] op_sel_hi:[1,0,1] neg_lo:[1,0,0] neg_hi:[1,0,0]
	ds_read_b128 v[116:119], v69 offset:40912
	s_waitcnt lgkmcnt(8)
	v_pk_fma_f32 v[50:51], v[242:243], v[12:13], v[50:51] op_sel_hi:[1,0,1] neg_lo:[1,0,0] neg_hi:[1,0,0]
	v_pk_fma_f32 v[164:165], v[244:245], v[10:11], v[176:177] op_sel_hi:[1,0,1] neg_lo:[1,0,0] neg_hi:[1,0,0]
	ds_read_b128 v[242:245], v69 offset:41408
	v_pk_add_f32 v[188:189], v[50:51], v[164:165]
	s_waitcnt lgkmcnt(8)
	v_pk_fma_f32 v[50:51], v[48:49], v[120:121], v[168:169] op_sel_hi:[0,1,1] neg_lo:[1,0,0] neg_hi:[1,0,0]
	v_pk_fma_f32 v[168:169], v[0:1], v[122:123], 0 op_sel_hi:[0,1,0] neg_lo:[1,0,0] neg_hi:[1,0,0]
	ds_read_b128 v[120:123], v69 offset:41424
	s_waitcnt lgkmcnt(8)
	v_pk_fma_f32 v[50:51], v[4:5], v[136:137], v[50:51] op_sel_hi:[0,1,1] neg_lo:[1,0,0] neg_hi:[1,0,0]
	v_pk_fma_f32 v[168:169], v[2:3], v[138:139], v[168:169] op_sel_hi:[0,1,1] neg_lo:[1,0,0] neg_hi:[1,0,0]
	ds_read_b128 v[136:139], v69 offset:41440
	s_waitcnt lgkmcnt(8)
	v_pk_fma_f32 v[50:51], v[8:9], v[112:113], v[50:51] op_sel_hi:[0,1,1] neg_lo:[1,0,0] neg_hi:[1,0,0]
	v_pk_fma_f32 v[168:169], v[6:7], v[114:115], v[168:169] op_sel_hi:[0,1,1] neg_lo:[1,0,0] neg_hi:[1,0,0]
	ds_read_b128 v[112:115], v69 offset:41456
	s_waitcnt lgkmcnt(8)
	v_pk_fma_f32 v[50:51], v[12:13], v[128:129], v[50:51] op_sel_hi:[0,1,1] neg_lo:[1,0,0] neg_hi:[1,0,0]
	v_pk_fma_f32 v[164:165], v[130:131], v[10:11], v[168:169] op_sel_hi:[1,0,1] neg_lo:[1,0,0] neg_hi:[1,0,0]
	ds_read_b128 v[128:131], v69 offset:41952
	v_pk_add_f32 v[190:191], v[50:51], v[164:165]
	s_waitcnt lgkmcnt(8)
	v_pk_fma_f32 v[50:51], v[48:49], v[124:125], v[170:171] op_sel_hi:[0,1,1] neg_lo:[1,0,0] neg_hi:[1,0,0]
	v_pk_fma_f32 v[168:169], v[0:1], v[126:127], 0 op_sel_hi:[0,1,0] neg_lo:[1,0,0] neg_hi:[1,0,0]
	ds_read_b128 v[124:127], v69 offset:41968
	s_waitcnt lgkmcnt(8)
	v_pk_fma_f32 v[50:51], v[4:5], v[238:239], v[50:51] op_sel_hi:[0,1,1] neg_lo:[1,0,0] neg_hi:[1,0,0]
	v_pk_fma_f32 v[168:169], v[2:3], v[240:241], v[168:169] op_sel_hi:[0,1,1] neg_lo:[1,0,0] neg_hi:[1,0,0]
	ds_read_b128 v[238:241], v69 offset:41984
	s_waitcnt lgkmcnt(8)
	v_pk_fma_f32 v[50:51], v[8:9], v[132:133], v[50:51] op_sel_hi:[0,1,1] neg_lo:[1,0,0] neg_hi:[1,0,0]
	v_pk_fma_f32 v[168:169], v[6:7], v[134:135], v[168:169] op_sel_hi:[0,1,1] neg_lo:[1,0,0] neg_hi:[1,0,0]
	ds_read_b128 v[132:135], v69 offset:42000
	s_waitcnt lgkmcnt(8)
	v_pk_fma_f32 v[50:51], v[12:13], v[116:117], v[50:51] op_sel_hi:[0,1,1] neg_lo:[1,0,0] neg_hi:[1,0,0]
	v_pk_fma_f32 v[164:165], v[10:11], v[118:119], v[168:169] op_sel_hi:[0,1,1] neg_lo:[1,0,0] neg_hi:[1,0,0]
	ds_read_b128 v[116:119], v69 offset:42496
	v_pk_add_f32 v[50:51], v[50:51], v[164:165]
	s_waitcnt lgkmcnt(8)
	v_pk_fma_f32 v[16:17], v[48:49], v[242:243], v[16:17] op_sel_hi:[0,1,1] neg_lo:[1,0,0] neg_hi:[1,0,0]
	v_pk_fma_f32 v[168:169], v[0:1], v[244:245], 0 op_sel_hi:[0,1,0] neg_lo:[1,0,0] neg_hi:[1,0,0]
	ds_read_b128 v[242:245], v69 offset:42512
	s_waitcnt lgkmcnt(8)
	v_pk_fma_f32 v[16:17], v[4:5], v[120:121], v[16:17] op_sel_hi:[0,1,1] neg_lo:[1,0,0] neg_hi:[1,0,0]
	v_pk_fma_f32 v[168:169], v[2:3], v[122:123], v[168:169] op_sel_hi:[0,1,1] neg_lo:[1,0,0] neg_hi:[1,0,0]
	ds_read_b128 v[120:123], v69 offset:42528
	s_waitcnt lgkmcnt(8)
	v_pk_fma_f32 v[16:17], v[8:9], v[136:137], v[16:17] op_sel_hi:[0,1,1] neg_lo:[1,0,0] neg_hi:[1,0,0]
	v_pk_fma_f32 v[168:169], v[6:7], v[138:139], v[168:169] op_sel_hi:[0,1,1] neg_lo:[1,0,0] neg_hi:[1,0,0]
	ds_read_b128 v[136:139], v69 offset:42544
	s_waitcnt lgkmcnt(8)
	v_pk_fma_f32 v[16:17], v[12:13], v[112:113], v[16:17] op_sel_hi:[0,1,1] neg_lo:[1,0,0] neg_hi:[1,0,0]
	v_pk_fma_f32 v[164:165], v[10:11], v[114:115], v[168:169] op_sel_hi:[0,1,1] neg_lo:[1,0,0] neg_hi:[1,0,0]
	ds_read_b128 v[112:115], v69 offset:43040
	v_pk_add_f32 v[164:165], v[16:17], v[164:165]
	s_waitcnt lgkmcnt(8)
	v_pk_fma_f32 v[166:167], v[48:49], v[128:129], v[18:19] op_sel_hi:[0,1,1] neg_lo:[1,0,0] neg_hi:[1,0,0]
	v_pk_fma_f32 v[168:169], v[0:1], v[130:131], 0 op_sel_hi:[0,1,0] neg_lo:[1,0,0] neg_hi:[1,0,0]
	ds_read_b128 v[128:131], v69 offset:43056
	s_waitcnt lgkmcnt(8)
	v_pk_fma_f32 v[166:167], v[4:5], v[124:125], v[166:167] op_sel_hi:[0,1,1] neg_lo:[1,0,0] neg_hi:[1,0,0]
	v_pk_fma_f32 v[168:169], v[2:3], v[126:127], v[168:169] op_sel_hi:[0,1,1] neg_lo:[1,0,0] neg_hi:[1,0,0]
	ds_read_b128 v[124:127], v69 offset:43072
	s_waitcnt lgkmcnt(8)
	v_pk_fma_f32 v[166:167], v[8:9], v[238:239], v[166:167] op_sel_hi:[0,1,1] neg_lo:[1,0,0] neg_hi:[1,0,0]
	v_pk_fma_f32 v[168:169], v[6:7], v[240:241], v[168:169] op_sel_hi:[0,1,1] neg_lo:[1,0,0] neg_hi:[1,0,0]
	ds_read_b128 v[238:241], v69 offset:43088
	s_waitcnt lgkmcnt(8)
; #define LAS __attribute__((address_space(3)))
; DI void gdn_prep_phase(const int tid, LAS unsigned char* lds, const P& p, int G, int c) {
;     ...
;           for (int kb = 0; kb < 8; ++kb) {
; #pragma unroll
;               for (int pp = 0; pp < 4; ++pp) { const int pr = 4 * kb + pp;
;                   f32x2 s = (f32x2){xs[2 * pr], xs[2 * pr + 1]};
; #pragma unroll
;                   for (int j = 8 * kb; j < 2 * pr; j += 2) { const f32x4 l = *(const LAS f32x4*)(Ls + pr * 136 + j * 2);
;                       s -= (f32x2){l[0], l[1]} * (f32x2){xs[j], xs[j]}; s -= (f32x2){l[2], l[3]} * (f32x2){xs[j + 1], xs[j + 1]}; }
;                   xs[2 * pr] = s[0];
;                   xs[2 * pr + 1] = s[1] - Ls[pr * 136 + 4 * pr + 1] * s[0]; }
; #pragma unroll
;               for (int pr = 4 * kb + 4; pr < 32; ++pr) {
;                   f32x2 s0 = (f32x2){xs[2 * pr], xs[2 * pr + 1]}, s1 = (f32x2){0.f, 0.f};
; #pragma unroll
;                   for (int q = 0; q < 4; ++q) { const int j = 8 * kb + 2 * q; const f32x4 l = *(const LAS f32x4*)(Ls + pr * 136 + j * 2);
;                       s0 -= (f32x2){l[0], l[1]} * (f32x2){xs[j], xs[j]}; s1 -= (f32x2){l[2], l[3]} * (f32x2){xs[j + 1], xs[j + 1]}; }
;                   const f32x2 s = s0 + s1; xs[2 * pr] = s[0]; xs[2 * pr + 1] = s[1]; }
	v_pk_fma_f32 v[16:17], v[12:13], v[132:133], v[166:167] op_sel_hi:[0,1,1] neg_lo:[1,0,0] neg_hi:[1,0,0]
	v_pk_fma_f32 v[18:19], v[10:11], v[134:135], v[168:169] op_sel_hi:[0,1,1] neg_lo:[1,0,0] neg_hi:[1,0,0]
	ds_read_b128 v[132:135], v69 offset:43584
	v_pk_add_f32 v[166:167], v[16:17], v[18:19]
	s_waitcnt lgkmcnt(8)
	v_pk_fma_f32 v[168:169], v[48:49], v[116:117], v[172:173] op_sel_hi:[0,1,1] neg_lo:[1,0,0] neg_hi:[1,0,0]
	v_pk_fma_f32 v[170:171], v[0:1], v[118:119], 0 op_sel_hi:[0,1,0] neg_lo:[1,0,0] neg_hi:[1,0,0]
	ds_read_b128 v[116:119], v69 offset:43600
	s_waitcnt lgkmcnt(8)
	v_pk_fma_f32 v[168:169], v[4:5], v[242:243], v[168:169] op_sel_hi:[0,1,1] neg_lo:[1,0,0] neg_hi:[1,0,0]
	v_pk_fma_f32 v[170:171], v[2:3], v[244:245], v[170:171] op_sel_hi:[0,1,1] neg_lo:[1,0,0] neg_hi:[1,0,0]
	ds_read_b128 v[242:245], v69 offset:43616
	s_waitcnt lgkmcnt(8)
	v_pk_fma_f32 v[168:169], v[8:9], v[120:121], v[168:169] op_sel_hi:[0,1,1] neg_lo:[1,0,0] neg_hi:[1,0,0]
	v_pk_fma_f32 v[170:171], v[6:7], v[122:123], v[170:171] op_sel_hi:[0,1,1] neg_lo:[1,0,0] neg_hi:[1,0,0]
	ds_read_b128 v[120:123], v69 offset:43632
	s_waitcnt lgkmcnt(8)
	v_pk_fma_f32 v[16:17], v[12:13], v[136:137], v[168:169] op_sel_hi:[0,1,1] neg_lo:[1,0,0] neg_hi:[1,0,0]
	v_pk_fma_f32 v[18:19], v[10:11], v[138:139], v[170:171] op_sel_hi:[0,1,1] neg_lo:[1,0,0] neg_hi:[1,0,0]
	ds_read_b128 v[136:139], v69 offset:44128
	v_pk_add_f32 v[168:169], v[16:17], v[18:19]
	s_waitcnt lgkmcnt(8)
	v_pk_fma_f32 v[170:171], v[48:49], v[112:113], v[174:175] op_sel_hi:[0,1,1] neg_lo:[1,0,0] neg_hi:[1,0,0]
	v_pk_fma_f32 v[172:173], v[0:1], v[114:115], 0 op_sel_hi:[0,1,0] neg_lo:[1,0,0] neg_hi:[1,0,0]
	ds_read_b128 v[112:115], v69 offset:44144
	s_waitcnt lgkmcnt(8)
	v_pk_fma_f32 v[170:171], v[4:5], v[128:129], v[170:171] op_sel_hi:[0,1,1] neg_lo:[1,0,0] neg_hi:[1,0,0]
	v_pk_fma_f32 v[172:173], v[2:3], v[130:131], v[172:173] op_sel_hi:[0,1,1] neg_lo:[1,0,0] neg_hi:[1,0,0]
	ds_read_b128 v[128:131], v69 offset:44160
	s_waitcnt lgkmcnt(8)
	v_pk_fma_f32 v[170:171], v[8:9], v[124:125], v[170:171] op_sel_hi:[0,1,1] neg_lo:[1,0,0] neg_hi:[1,0,0]
	v_pk_fma_f32 v[172:173], v[6:7], v[126:127], v[172:173] op_sel_hi:[0,1,1] neg_lo:[1,0,0] neg_hi:[1,0,0]
	ds_read_b128 v[124:127], v69 offset:44176
	s_waitcnt lgkmcnt(8)
	v_pk_fma_f32 v[16:17], v[12:13], v[238:239], v[170:171] op_sel_hi:[0,1,1] neg_lo:[1,0,0] neg_hi:[1,0,0]
	v_pk_fma_f32 v[18:19], v[10:11], v[240:241], v[172:173] op_sel_hi:[0,1,1] neg_lo:[1,0,0] neg_hi:[1,0,0]
	ds_read_b128 v[238:241], v69 offset:44672
	v_pk_add_f32 v[170:171], v[16:17], v[18:19]
	s_waitcnt lgkmcnt(8)
	v_pk_fma_f32 v[36:37], v[48:49], v[132:133], v[36:37] op_sel_hi:[0,1,1] neg_lo:[1,0,0] neg_hi:[1,0,0]
	v_pk_fma_f32 v[172:173], v[0:1], v[134:135], 0 op_sel_hi:[0,1,0] neg_lo:[1,0,0] neg_hi:[1,0,0]
	ds_read_b128 v[132:135], v69 offset:44688
	s_waitcnt lgkmcnt(8)
	v_pk_fma_f32 v[36:37], v[4:5], v[116:117], v[36:37] op_sel_hi:[0,1,1] neg_lo:[1,0,0] neg_hi:[1,0,0]
	v_pk_fma_f32 v[172:173], v[2:3], v[118:119], v[172:173] op_sel_hi:[0,1,1] neg_lo:[1,0,0] neg_hi:[1,0,0]
	ds_read_b128 v[116:119], v69 offset:44704
	s_waitcnt lgkmcnt(8)
	v_pk_fma_f32 v[36:37], v[8:9], v[242:243], v[36:37] op_sel_hi:[0,1,1] neg_lo:[1,0,0] neg_hi:[1,0,0]
	v_pk_fma_f32 v[172:173], v[6:7], v[244:245], v[172:173] op_sel_hi:[0,1,1] neg_lo:[1,0,0] neg_hi:[1,0,0]
	ds_read_b128 v[242:245], v69 offset:44720
	s_waitcnt lgkmcnt(8)
	v_pk_fma_f32 v[16:17], v[12:13], v[120:121], v[36:37] op_sel_hi:[0,1,1] neg_lo:[1,0,0] neg_hi:[1,0,0]
	v_pk_fma_f32 v[18:19], v[10:11], v[122:123], v[172:173] op_sel_hi:[0,1,1] neg_lo:[1,0,0] neg_hi:[1,0,0]
	ds_read_b128 v[120:123], v69 offset:45216
	v_pk_add_f32 v[36:37], v[16:17], v[18:19]
	s_waitcnt lgkmcnt(8)
	v_pk_fma_f32 v[38:39], v[48:49], v[136:137], v[38:39] op_sel_hi:[0,1,1] neg_lo:[1,0,0] neg_hi:[1,0,0]
	v_pk_fma_f32 v[172:173], v[0:1], v[138:139], 0 op_sel_hi:[0,1,0] neg_lo:[1,0,0] neg_hi:[1,0,0]
	ds_read_b128 v[136:139], v69 offset:45232
	s_waitcnt lgkmcnt(8)
	v_pk_fma_f32 v[38:39], v[4:5], v[112:113], v[38:39] op_sel_hi:[0,1,1] neg_lo:[1,0,0] neg_hi:[1,0,0]
	v_pk_fma_f32 v[172:173], v[2:3], v[114:115], v[172:173] op_sel_hi:[0,1,1] neg_lo:[1,0,0] neg_hi:[1,0,0]
	ds_read_b128 v[112:115], v69 offset:45248
	s_waitcnt lgkmcnt(8)
	v_pk_fma_f32 v[38:39], v[8:9], v[128:129], v[38:39] op_sel_hi:[0,1,1] neg_lo:[1,0,0] neg_hi:[1,0,0]
	v_pk_fma_f32 v[172:173], v[6:7], v[130:131], v[172:173] op_sel_hi:[0,1,1] neg_lo:[1,0,0] neg_hi:[1,0,0]
	ds_read_b128 v[128:131], v69 offset:45264
	s_waitcnt lgkmcnt(8)
	v_pk_fma_f32 v[16:17], v[12:13], v[124:125], v[38:39] op_sel_hi:[0,1,1] neg_lo:[1,0,0] neg_hi:[1,0,0]
	v_pk_fma_f32 v[18:19], v[10:11], v[126:127], v[172:173] op_sel_hi:[0,1,1] neg_lo:[1,0,0] neg_hi:[1,0,0]
	ds_read_b128 v[124:127], v69 offset:45760
	v_pk_add_f32 v[38:39], v[16:17], v[18:19]
	s_waitcnt lgkmcnt(8)
	v_pk_fma_f32 v[24:25], v[48:49], v[238:239], v[24:25] op_sel_hi:[0,1,1] neg_lo:[1,0,0] neg_hi:[1,0,0]
	v_pk_fma_f32 v[172:173], v[0:1], v[240:241], 0 op_sel_hi:[0,1,0] neg_lo:[1,0,0] neg_hi:[1,0,0]
	ds_read_b128 v[238:241], v69 offset:45776
	s_waitcnt lgkmcnt(8)
	v_pk_fma_f32 v[24:25], v[4:5], v[132:133], v[24:25] op_sel_hi:[0,1,1] neg_lo:[1,0,0] neg_hi:[1,0,0]
	v_pk_fma_f32 v[172:173], v[2:3], v[134:135], v[172:173] op_sel_hi:[0,1,1] neg_lo:[1,0,0] neg_hi:[1,0,0]
	ds_read_b128 v[132:135], v69 offset:45792
	s_waitcnt lgkmcnt(8)
	v_pk_fma_f32 v[24:25], v[8:9], v[116:117], v[24:25] op_sel_hi:[0,1,1] neg_lo:[1,0,0] neg_hi:[1,0,0]
	v_pk_fma_f32 v[172:173], v[6:7], v[118:119], v[172:173] op_sel_hi:[0,1,1] neg_lo:[1,0,0] neg_hi:[1,0,0]
	ds_read_b128 v[116:119], v69 offset:45808
	s_waitcnt lgkmcnt(8)
; #define LAS __attribute__((address_space(3)))
; DI void gdn_prep_phase(const int tid, LAS unsigned char* lds, const P& p, int G, int c) {
;     ...
;           for (int kb = 0; kb < 8; ++kb) {
; #pragma unroll
;               for (int pp = 0; pp < 4; ++pp) { const int pr = 4 * kb + pp;
;                   f32x2 s = (f32x2){xs[2 * pr], xs[2 * pr + 1]};
; #pragma unroll
;                   for (int j = 8 * kb; j < 2 * pr; j += 2) { const f32x4 l = *(const LAS f32x4*)(Ls + pr * 136 + j * 2);
;                       s -= (f32x2){l[0], l[1]} * (f32x2){xs[j], xs[j]}; s -= (f32x2){l[2], l[3]} * (f32x2){xs[j + 1], xs[j + 1]}; }
;                   xs[2 * pr] = s[0];
;                   xs[2 * pr + 1] = s[1] - Ls[pr * 136 + 4 * pr + 1] * s[0]; }
; #pragma unroll
;               for (int pr = 4 * kb + 4; pr < 32; ++pr) {
;                   f32x2 s0 = (f32x2){xs[2 * pr], xs[2 * pr + 1]}, s1 = (f32x2){0.f, 0.f};
; #pragma unroll
;                   for (int q = 0; q < 4; ++q) { const int j = 8 * kb + 2 * q; const f32x4 l = *(const LAS f32x4*)(Ls + pr * 136 + j * 2);
;                       s0 -= (f32x2){l[0], l[1]} * (f32x2){xs[j], xs[j]}; s1 -= (f32x2){l[2], l[3]} * (f32x2){xs[j + 1], xs[j + 1]}; }
;                   const f32x2 s = s0 + s1; xs[2 * pr] = s[0]; xs[2 * pr + 1] = s[1]; }
	v_pk_fma_f32 v[16:17], v[12:13], v[242:243], v[24:25] op_sel_hi:[0,1,1] neg_lo:[1,0,0] neg_hi:[1,0,0]
	v_pk_fma_f32 v[18:19], v[10:11], v[244:245], v[172:173] op_sel_hi:[0,1,1] neg_lo:[1,0,0] neg_hi:[1,0,0]
	ds_read_b128 v[242:245], v69 offset:46304
	v_pk_add_f32 v[172:173], v[16:17], v[18:19]
	s_waitcnt lgkmcnt(8)
	v_pk_fma_f32 v[24:25], v[48:49], v[120:121], v[26:27] op_sel_hi:[0,1,1] neg_lo:[1,0,0] neg_hi:[1,0,0]
	v_pk_fma_f32 v[26:27], v[0:1], v[122:123], 0 op_sel_hi:[0,1,0] neg_lo:[1,0,0] neg_hi:[1,0,0]
	ds_read_b128 v[120:123], v69 offset:46320
	s_waitcnt lgkmcnt(8)
	v_pk_fma_f32 v[24:25], v[4:5], v[136:137], v[24:25] op_sel_hi:[0,1,1] neg_lo:[1,0,0] neg_hi:[1,0,0]
	v_pk_fma_f32 v[26:27], v[2:3], v[138:139], v[26:27] op_sel_hi:[0,1,1] neg_lo:[1,0,0] neg_hi:[1,0,0]
	ds_read_b128 v[136:139], v69 offset:46336
	s_waitcnt lgkmcnt(8)
	v_pk_fma_f32 v[24:25], v[8:9], v[112:113], v[24:25] op_sel_hi:[0,1,1] neg_lo:[1,0,0] neg_hi:[1,0,0]
	v_pk_fma_f32 v[26:27], v[6:7], v[114:115], v[26:27] op_sel_hi:[0,1,1] neg_lo:[1,0,0] neg_hi:[1,0,0]
	ds_read_b128 v[112:115], v69 offset:46352
	s_waitcnt lgkmcnt(8)
	v_pk_fma_f32 v[16:17], v[12:13], v[128:129], v[24:25] op_sel_hi:[0,1,1] neg_lo:[1,0,0] neg_hi:[1,0,0]
	v_pk_fma_f32 v[18:19], v[10:11], v[130:131], v[26:27] op_sel_hi:[0,1,1] neg_lo:[1,0,0] neg_hi:[1,0,0]
	ds_read_b128 v[128:131], v69 offset:46848
	v_pk_add_f32 v[174:175], v[16:17], v[18:19]
	s_waitcnt lgkmcnt(8)
	v_pk_fma_f32 v[24:25], v[48:49], v[124:125], v[40:41] op_sel_hi:[0,1,1] neg_lo:[1,0,0] neg_hi:[1,0,0]
	v_pk_fma_f32 v[26:27], v[0:1], v[126:127], 0 op_sel_hi:[0,1,0] neg_lo:[1,0,0] neg_hi:[1,0,0]
	ds_read_b128 v[124:127], v69 offset:46864
	s_waitcnt lgkmcnt(8)
	v_pk_fma_f32 v[24:25], v[4:5], v[238:239], v[24:25] op_sel_hi:[0,1,1] neg_lo:[1,0,0] neg_hi:[1,0,0]
	v_pk_fma_f32 v[26:27], v[2:3], v[240:241], v[26:27] op_sel_hi:[0,1,1] neg_lo:[1,0,0] neg_hi:[1,0,0]
	ds_read_b128 v[238:241], v69 offset:46880
	s_waitcnt lgkmcnt(8)
	v_pk_fma_f32 v[24:25], v[8:9], v[132:133], v[24:25] op_sel_hi:[0,1,1] neg_lo:[1,0,0] neg_hi:[1,0,0]
	v_pk_fma_f32 v[26:27], v[6:7], v[134:135], v[26:27] op_sel_hi:[0,1,1] neg_lo:[1,0,0] neg_hi:[1,0,0]
	ds_read_b128 v[132:135], v69 offset:46896
	s_waitcnt lgkmcnt(8)
	v_pk_fma_f32 v[16:17], v[12:13], v[116:117], v[24:25] op_sel_hi:[0,1,1] neg_lo:[1,0,0] neg_hi:[1,0,0]
	v_pk_fma_f32 v[18:19], v[10:11], v[118:119], v[26:27] op_sel_hi:[0,1,1] neg_lo:[1,0,0] neg_hi:[1,0,0]
	ds_read_b128 v[116:119], v69 offset:47392
	v_pk_add_f32 v[40:41], v[16:17], v[18:19]
	s_waitcnt lgkmcnt(8)
	v_pk_fma_f32 v[24:25], v[48:49], v[242:243], v[42:43] op_sel_hi:[0,1,1] neg_lo:[1,0,0] neg_hi:[1,0,0]
	v_pk_fma_f32 v[26:27], v[0:1], v[244:245], 0 op_sel_hi:[0,1,0] neg_lo:[1,0,0] neg_hi:[1,0,0]
	ds_read_b128 v[242:245], v69 offset:47408
	s_waitcnt lgkmcnt(8)
	v_pk_fma_f32 v[24:25], v[4:5], v[120:121], v[24:25] op_sel_hi:[0,1,1] neg_lo:[1,0,0] neg_hi:[1,0,0]
	v_pk_fma_f32 v[26:27], v[2:3], v[122:123], v[26:27] op_sel_hi:[0,1,1] neg_lo:[1,0,0] neg_hi:[1,0,0]
	ds_read_b128 v[120:123], v69 offset:47424
	s_waitcnt lgkmcnt(8)
	v_pk_fma_f32 v[24:25], v[8:9], v[136:137], v[24:25] op_sel_hi:[0,1,1] neg_lo:[1,0,0] neg_hi:[1,0,0]
	v_pk_fma_f32 v[26:27], v[6:7], v[138:139], v[26:27] op_sel_hi:[0,1,1] neg_lo:[1,0,0] neg_hi:[1,0,0]
	ds_read_b128 v[136:139], v69 offset:47440
	s_waitcnt lgkmcnt(8)
	v_pk_fma_f32 v[16:17], v[12:13], v[112:113], v[24:25] op_sel_hi:[0,1,1] neg_lo:[1,0,0] neg_hi:[1,0,0]
	v_pk_fma_f32 v[18:19], v[10:11], v[114:115], v[26:27] op_sel_hi:[0,1,1] neg_lo:[1,0,0] neg_hi:[1,0,0]
	ds_read_b128 v[112:115], v69 offset:47936
	v_pk_add_f32 v[42:43], v[16:17], v[18:19]
	s_waitcnt lgkmcnt(8)
	v_pk_fma_f32 v[24:25], v[48:49], v[128:129], v[32:33] op_sel_hi:[0,1,1] neg_lo:[1,0,0] neg_hi:[1,0,0]
	v_pk_fma_f32 v[26:27], v[0:1], v[130:131], 0 op_sel_hi:[0,1,0] neg_lo:[1,0,0] neg_hi:[1,0,0]
	ds_read_b128 v[128:131], v69 offset:47952
	s_waitcnt lgkmcnt(8)
	v_pk_fma_f32 v[24:25], v[4:5], v[124:125], v[24:25] op_sel_hi:[0,1,1] neg_lo:[1,0,0] neg_hi:[1,0,0]
	v_pk_fma_f32 v[26:27], v[2:3], v[126:127], v[26:27] op_sel_hi:[0,1,1] neg_lo:[1,0,0] neg_hi:[1,0,0]
	ds_read_b128 v[124:127], v69 offset:47968
	s_waitcnt lgkmcnt(8)
	v_pk_fma_f32 v[24:25], v[8:9], v[238:239], v[24:25] op_sel_hi:[0,1,1] neg_lo:[1,0,0] neg_hi:[1,0,0]
	v_pk_fma_f32 v[26:27], v[6:7], v[240:241], v[26:27] op_sel_hi:[0,1,1] neg_lo:[1,0,0] neg_hi:[1,0,0]
	ds_read_b128 v[238:241], v69 offset:47984
	s_waitcnt lgkmcnt(8)
	v_pk_fma_f32 v[16:17], v[12:13], v[132:133], v[24:25] op_sel_hi:[0,1,1] neg_lo:[1,0,0] neg_hi:[1,0,0]
	v_pk_fma_f32 v[18:19], v[10:11], v[134:135], v[26:27] op_sel_hi:[0,1,1] neg_lo:[1,0,0] neg_hi:[1,0,0]
	ds_read_b128 v[132:135], v69 offset:48480
	v_pk_add_f32 v[32:33], v[16:17], v[18:19]
	s_waitcnt lgkmcnt(8)
	v_pk_fma_f32 v[24:25], v[48:49], v[116:117], v[34:35] op_sel_hi:[0,1,1] neg_lo:[1,0,0] neg_hi:[1,0,0]
	v_pk_fma_f32 v[26:27], v[0:1], v[118:119], 0 op_sel_hi:[0,1,0] neg_lo:[1,0,0] neg_hi:[1,0,0]
	ds_read_b128 v[116:119], v69 offset:48496
	s_waitcnt lgkmcnt(8)
	v_pk_fma_f32 v[24:25], v[4:5], v[242:243], v[24:25] op_sel_hi:[0,1,1] neg_lo:[1,0,0] neg_hi:[1,0,0]
	v_pk_fma_f32 v[26:27], v[2:3], v[244:245], v[26:27] op_sel_hi:[0,1,1] neg_lo:[1,0,0] neg_hi:[1,0,0]
	ds_read_b128 v[242:245], v69 offset:48512
	s_waitcnt lgkmcnt(8)
	v_pk_fma_f32 v[24:25], v[8:9], v[120:121], v[24:25] op_sel_hi:[0,1,1] neg_lo:[1,0,0] neg_hi:[1,0,0]
	v_pk_fma_f32 v[26:27], v[6:7], v[122:123], v[26:27] op_sel_hi:[0,1,1] neg_lo:[1,0,0] neg_hi:[1,0,0]
	ds_read_b128 v[120:123], v69 offset:48528
	s_waitcnt lgkmcnt(8)
; #define LAS __attribute__((address_space(3)))
; DI void gdn_prep_phase(const int tid, LAS unsigned char* lds, const P& p, int G, int c) {
;     ...
;           for (int kb = 0; kb < 8; ++kb) {
; #pragma unroll
;               for (int pp = 0; pp < 4; ++pp) { const int pr = 4 * kb + pp;
;                   f32x2 s = (f32x2){xs[2 * pr], xs[2 * pr + 1]};
; #pragma unroll
;                   for (int j = 8 * kb; j < 2 * pr; j += 2) { const f32x4 l = *(const LAS f32x4*)(Ls + pr * 136 + j * 2);
;                       s -= (f32x2){l[0], l[1]} * (f32x2){xs[j], xs[j]}; s -= (f32x2){l[2], l[3]} * (f32x2){xs[j + 1], xs[j + 1]}; }
;                   xs[2 * pr] = s[0];
;                   xs[2 * pr + 1] = s[1] - Ls[pr * 136 + 4 * pr + 1] * s[0]; }
; #pragma unroll
;               for (int pr = 4 * kb + 4; pr < 32; ++pr) {
;                   f32x2 s0 = (f32x2){xs[2 * pr], xs[2 * pr + 1]}, s1 = (f32x2){0.f, 0.f};
; #pragma unroll
;                   for (int q = 0; q < 4; ++q) { const int j = 8 * kb + 2 * q; const f32x4 l = *(const LAS f32x4*)(Ls + pr * 136 + j * 2);
;                       s0 -= (f32x2){l[0], l[1]} * (f32x2){xs[j], xs[j]}; s1 -= (f32x2){l[2], l[3]} * (f32x2){xs[j + 1], xs[j + 1]}; }
;                   const f32x2 s = s0 + s1; xs[2 * pr] = s[0]; xs[2 * pr + 1] = s[1]; }
	v_pk_fma_f32 v[16:17], v[12:13], v[136:137], v[24:25] op_sel_hi:[0,1,1] neg_lo:[1,0,0] neg_hi:[1,0,0]
	v_pk_fma_f32 v[18:19], v[10:11], v[138:139], v[26:27] op_sel_hi:[0,1,1] neg_lo:[1,0,0] neg_hi:[1,0,0]
	ds_read_b128 v[136:139], v69 offset:49024
	v_pk_add_f32 v[34:35], v[16:17], v[18:19]
	s_waitcnt lgkmcnt(8)
	v_pk_fma_f32 v[24:25], v[48:49], v[112:113], v[28:29] op_sel_hi:[0,1,1] neg_lo:[1,0,0] neg_hi:[1,0,0]
	v_pk_fma_f32 v[26:27], v[0:1], v[114:115], 0 op_sel_hi:[0,1,0] neg_lo:[1,0,0] neg_hi:[1,0,0]
	ds_read_b128 v[112:115], v69 offset:49040
	s_waitcnt lgkmcnt(8)
	v_pk_fma_f32 v[24:25], v[4:5], v[128:129], v[24:25] op_sel_hi:[0,1,1] neg_lo:[1,0,0] neg_hi:[1,0,0]
	v_pk_fma_f32 v[26:27], v[2:3], v[130:131], v[26:27] op_sel_hi:[0,1,1] neg_lo:[1,0,0] neg_hi:[1,0,0]
	ds_read_b128 v[128:131], v69 offset:49056
	s_waitcnt lgkmcnt(8)
	v_pk_fma_f32 v[24:25], v[8:9], v[124:125], v[24:25] op_sel_hi:[0,1,1] neg_lo:[1,0,0] neg_hi:[1,0,0]
	v_pk_fma_f32 v[26:27], v[6:7], v[126:127], v[26:27] op_sel_hi:[0,1,1] neg_lo:[1,0,0] neg_hi:[1,0,0]
	ds_read_b128 v[124:127], v69 offset:49072
	s_waitcnt lgkmcnt(8)
	v_pk_fma_f32 v[16:17], v[12:13], v[238:239], v[24:25] op_sel_hi:[0,1,1] neg_lo:[1,0,0] neg_hi:[1,0,0]
	v_pk_fma_f32 v[18:19], v[10:11], v[240:241], v[26:27] op_sel_hi:[0,1,1] neg_lo:[1,0,0] neg_hi:[1,0,0]
	ds_read_b128 v[238:241], v69 offset:49568
	v_pk_add_f32 v[176:177], v[16:17], v[18:19]
	s_waitcnt lgkmcnt(8)
	v_pk_fma_f32 v[24:25], v[48:49], v[132:133], v[30:31] op_sel_hi:[0,1,1] neg_lo:[1,0,0] neg_hi:[1,0,0]
	v_pk_fma_f32 v[26:27], v[0:1], v[134:135], 0 op_sel_hi:[0,1,0] neg_lo:[1,0,0] neg_hi:[1,0,0]
	ds_read_b128 v[132:135], v69 offset:49584
	s_waitcnt lgkmcnt(8)
	v_pk_fma_f32 v[24:25], v[4:5], v[116:117], v[24:25] op_sel_hi:[0,1,1] neg_lo:[1,0,0] neg_hi:[1,0,0]
	v_pk_fma_f32 v[26:27], v[2:3], v[118:119], v[26:27] op_sel_hi:[0,1,1] neg_lo:[1,0,0] neg_hi:[1,0,0]
	ds_read_b128 v[116:119], v69 offset:49600
	s_waitcnt lgkmcnt(8)
	v_pk_fma_f32 v[24:25], v[8:9], v[242:243], v[24:25] op_sel_hi:[0,1,1] neg_lo:[1,0,0] neg_hi:[1,0,0]
	v_pk_fma_f32 v[26:27], v[6:7], v[244:245], v[26:27] op_sel_hi:[0,1,1] neg_lo:[1,0,0] neg_hi:[1,0,0]
	ds_read_b128 v[242:245], v69 offset:49616
	s_waitcnt lgkmcnt(8)
	v_pk_fma_f32 v[16:17], v[12:13], v[120:121], v[24:25] op_sel_hi:[0,1,1] neg_lo:[1,0,0] neg_hi:[1,0,0]
	v_pk_fma_f32 v[18:19], v[10:11], v[122:123], v[26:27] op_sel_hi:[0,1,1] neg_lo:[1,0,0] neg_hi:[1,0,0]
	ds_read_b128 v[120:123], v69 offset:50112
	v_pk_add_f32 v[178:179], v[16:17], v[18:19]
	s_waitcnt lgkmcnt(8)
	v_pk_fma_f32 v[20:21], v[48:49], v[136:137], v[20:21] op_sel_hi:[0,1,1] neg_lo:[1,0,0] neg_hi:[1,0,0]
	v_pk_fma_f32 v[24:25], v[0:1], v[138:139], 0 op_sel_hi:[0,1,0] neg_lo:[1,0,0] neg_hi:[1,0,0]
	ds_read_b128 v[136:139], v69 offset:50128
	s_waitcnt lgkmcnt(8)
	v_pk_fma_f32 v[20:21], v[4:5], v[112:113], v[20:21] op_sel_hi:[0,1,1] neg_lo:[1,0,0] neg_hi:[1,0,0]
	v_pk_fma_f32 v[24:25], v[2:3], v[114:115], v[24:25] op_sel_hi:[0,1,1] neg_lo:[1,0,0] neg_hi:[1,0,0]
	ds_read_b128 v[112:115], v69 offset:50144
	s_waitcnt lgkmcnt(8)
	v_pk_fma_f32 v[20:21], v[8:9], v[128:129], v[20:21] op_sel_hi:[0,1,1] neg_lo:[1,0,0] neg_hi:[1,0,0]
	v_pk_fma_f32 v[24:25], v[6:7], v[130:131], v[24:25] op_sel_hi:[0,1,1] neg_lo:[1,0,0] neg_hi:[1,0,0]
	ds_read_b128 v[128:131], v69 offset:50160
	s_waitcnt lgkmcnt(8)
	v_pk_fma_f32 v[16:17], v[12:13], v[124:125], v[20:21] op_sel_hi:[0,1,1] neg_lo:[1,0,0] neg_hi:[1,0,0]
	v_pk_fma_f32 v[18:19], v[10:11], v[126:127], v[24:25] op_sel_hi:[0,1,1] neg_lo:[1,0,0] neg_hi:[1,0,0]
	ds_read_b128 v[124:127], v69 offset:50656
	v_pk_add_f32 v[184:185], v[16:17], v[18:19]
	s_waitcnt lgkmcnt(8)
	v_pk_fma_f32 v[20:21], v[48:49], v[238:239], v[22:23] op_sel_hi:[0,1,1] neg_lo:[1,0,0] neg_hi:[1,0,0]
	v_pk_fma_f32 v[22:23], v[0:1], v[240:241], 0 op_sel_hi:[0,1,0] neg_lo:[1,0,0] neg_hi:[1,0,0]
	ds_read_b128 v[238:241], v69 offset:50672
	s_waitcnt lgkmcnt(8)
	v_pk_fma_f32 v[20:21], v[4:5], v[132:133], v[20:21] op_sel_hi:[0,1,1] neg_lo:[1,0,0] neg_hi:[1,0,0]
	v_pk_fma_f32 v[22:23], v[2:3], v[134:135], v[22:23] op_sel_hi:[0,1,1] neg_lo:[1,0,0] neg_hi:[1,0,0]
	ds_read_b128 v[132:135], v69 offset:50688
	s_waitcnt lgkmcnt(8)
	v_pk_fma_f32 v[20:21], v[8:9], v[116:117], v[20:21] op_sel_hi:[0,1,1] neg_lo:[1,0,0] neg_hi:[1,0,0]
	v_pk_fma_f32 v[22:23], v[6:7], v[118:119], v[22:23] op_sel_hi:[0,1,1] neg_lo:[1,0,0] neg_hi:[1,0,0]
	ds_read_b128 v[116:119], v69 offset:50704
	s_waitcnt lgkmcnt(8)
	v_pk_fma_f32 v[16:17], v[12:13], v[242:243], v[20:21] op_sel_hi:[0,1,1] neg_lo:[1,0,0] neg_hi:[1,0,0]
	v_pk_fma_f32 v[18:19], v[10:11], v[244:245], v[22:23] op_sel_hi:[0,1,1] neg_lo:[1,0,0] neg_hi:[1,0,0]
	ds_read_b128 v[242:245], v69 offset:51200
	v_pk_add_f32 v[186:187], v[16:17], v[18:19]
	s_waitcnt lgkmcnt(8)
	v_pk_fma_f32 v[20:21], v[48:49], v[120:121], v[52:53] op_sel_hi:[0,1,1] neg_lo:[1,0,0] neg_hi:[1,0,0]
	v_pk_fma_f32 v[22:23], v[0:1], v[122:123], 0 op_sel_hi:[0,1,0] neg_lo:[1,0,0] neg_hi:[1,0,0]
	ds_read_b128 v[120:123], v69 offset:51216
	s_waitcnt lgkmcnt(8)
	v_pk_fma_f32 v[20:21], v[4:5], v[136:137], v[20:21] op_sel_hi:[0,1,1] neg_lo:[1,0,0] neg_hi:[1,0,0]
	v_pk_fma_f32 v[22:23], v[2:3], v[138:139], v[22:23] op_sel_hi:[0,1,1] neg_lo:[1,0,0] neg_hi:[1,0,0]
	ds_read_b128 v[136:139], v69 offset:51232
	s_waitcnt lgkmcnt(8)
	v_pk_fma_f32 v[20:21], v[8:9], v[112:113], v[20:21] op_sel_hi:[0,1,1] neg_lo:[1,0,0] neg_hi:[1,0,0]
	v_pk_fma_f32 v[22:23], v[6:7], v[114:115], v[22:23] op_sel_hi:[0,1,1] neg_lo:[1,0,0] neg_hi:[1,0,0]
	ds_read_b128 v[112:115], v69 offset:51248
	s_waitcnt lgkmcnt(8)
; #define LAS __attribute__((address_space(3)))
; DI void gdn_prep_phase(const int tid, LAS unsigned char* lds, const P& p, int G, int c) {
;     ...
;           for (int kb = 0; kb < 8; ++kb) {
; #pragma unroll
;               for (int pp = 0; pp < 4; ++pp) { const int pr = 4 * kb + pp;
;                   f32x2 s = (f32x2){xs[2 * pr], xs[2 * pr + 1]};
; #pragma unroll
;                   for (int j = 8 * kb; j < 2 * pr; j += 2) { const f32x4 l = *(const LAS f32x4*)(Ls + pr * 136 + j * 2);
;                       s -= (f32x2){l[0], l[1]} * (f32x2){xs[j], xs[j]}; s -= (f32x2){l[2], l[3]} * (f32x2){xs[j + 1], xs[j + 1]}; }
;                   xs[2 * pr] = s[0];
;                   xs[2 * pr + 1] = s[1] - Ls[pr * 136 + 4 * pr + 1] * s[0]; }
; #pragma unroll
;               for (int pr = 4 * kb + 4; pr < 32; ++pr) {
;                   f32x2 s0 = (f32x2){xs[2 * pr], xs[2 * pr + 1]}, s1 = (f32x2){0.f, 0.f};
; #pragma unroll
;                   for (int q = 0; q < 4; ++q) { const int j = 8 * kb + 2 * q; const f32x4 l = *(const LAS f32x4*)(Ls + pr * 136 + j * 2);
;                       s0 -= (f32x2){l[0], l[1]} * (f32x2){xs[j], xs[j]}; s1 -= (f32x2){l[2], l[3]} * (f32x2){xs[j + 1], xs[j + 1]}; }
;                   const f32x2 s = s0 + s1; xs[2 * pr] = s[0]; xs[2 * pr + 1] = s[1]; }
	v_pk_fma_f32 v[16:17], v[12:13], v[128:129], v[20:21] op_sel_hi:[0,1,1] neg_lo:[1,0,0] neg_hi:[1,0,0]
	v_pk_fma_f32 v[18:19], v[10:11], v[130:131], v[22:23] op_sel_hi:[0,1,1] neg_lo:[1,0,0] neg_hi:[1,0,0]
	ds_read_b128 v[128:131], v69 offset:51744
	v_pk_add_f32 v[52:53], v[16:17], v[18:19]
	s_waitcnt lgkmcnt(8)
	v_pk_fma_f32 v[20:21], v[48:49], v[124:125], v[54:55] op_sel_hi:[0,1,1] neg_lo:[1,0,0] neg_hi:[1,0,0]
	v_pk_fma_f32 v[22:23], v[0:1], v[126:127], 0 op_sel_hi:[0,1,0] neg_lo:[1,0,0] neg_hi:[1,0,0]
	ds_read_b128 v[124:127], v69 offset:51760
	s_waitcnt lgkmcnt(8)
	v_pk_fma_f32 v[20:21], v[4:5], v[238:239], v[20:21] op_sel_hi:[0,1,1] neg_lo:[1,0,0] neg_hi:[1,0,0]
	v_pk_fma_f32 v[22:23], v[2:3], v[240:241], v[22:23] op_sel_hi:[0,1,1] neg_lo:[1,0,0] neg_hi:[1,0,0]
	ds_read_b128 v[238:241], v69 offset:51776
	s_waitcnt lgkmcnt(8)
	v_pk_fma_f32 v[20:21], v[8:9], v[132:133], v[20:21] op_sel_hi:[0,1,1] neg_lo:[1,0,0] neg_hi:[1,0,0]
	v_pk_fma_f32 v[22:23], v[6:7], v[134:135], v[22:23] op_sel_hi:[0,1,1] neg_lo:[1,0,0] neg_hi:[1,0,0]
	ds_read_b128 v[132:135], v69 offset:51792
	s_waitcnt lgkmcnt(8)
	v_pk_fma_f32 v[16:17], v[12:13], v[116:117], v[20:21] op_sel_hi:[0,1,1] neg_lo:[1,0,0] neg_hi:[1,0,0]
	v_pk_fma_f32 v[18:19], v[10:11], v[118:119], v[22:23] op_sel_hi:[0,1,1] neg_lo:[1,0,0] neg_hi:[1,0,0]
	v_add_u32_e32 v141, 0x9800, v69
	ds_read2_b32 v[116:117], v141 offset0:97 offset1:237
	v_pk_add_f32 v[54:55], v[16:17], v[18:19]
	s_waitcnt lgkmcnt(8)
	v_pk_fma_f32 v[20:21], v[48:49], v[242:243], v[44:45] op_sel_hi:[0,1,1] neg_lo:[1,0,0] neg_hi:[1,0,0]
	v_pk_fma_f32 v[22:23], v[0:1], v[244:245], 0 op_sel_hi:[0,1,0] neg_lo:[1,0,0] neg_hi:[1,0,0]
	ds_read_b128 v[242:245], v69 offset:39840
	s_waitcnt lgkmcnt(8)
	v_pk_fma_f32 v[20:21], v[4:5], v[120:121], v[20:21] op_sel_hi:[0,1,1] neg_lo:[1,0,0] neg_hi:[1,0,0]
	v_pk_fma_f32 v[22:23], v[2:3], v[122:123], v[22:23] op_sel_hi:[0,1,1] neg_lo:[1,0,0] neg_hi:[1,0,0]
	ds_read_b128 v[120:123], v69 offset:40384
	s_waitcnt lgkmcnt(8)
	v_pk_fma_f32 v[20:21], v[8:9], v[136:137], v[20:21] op_sel_hi:[0,1,1] neg_lo:[1,0,0] neg_hi:[1,0,0]
	v_pk_fma_f32 v[22:23], v[6:7], v[138:139], v[22:23] op_sel_hi:[0,1,1] neg_lo:[1,0,0] neg_hi:[1,0,0]
	ds_read_b128 v[136:139], v69 offset:40400
	s_waitcnt lgkmcnt(8)
	v_pk_fma_f32 v[16:17], v[12:13], v[112:113], v[20:21] op_sel_hi:[0,1,1] neg_lo:[1,0,0] neg_hi:[1,0,0]
	v_pk_fma_f32 v[18:19], v[10:11], v[114:115], v[22:23] op_sel_hi:[0,1,1] neg_lo:[1,0,0] neg_hi:[1,0,0]
	ds_read_b128 v[112:115], v69 offset:40928
	v_pk_add_f32 v[44:45], v[16:17], v[18:19]
	s_waitcnt lgkmcnt(8)
	v_pk_fma_f32 v[20:21], v[48:49], v[128:129], v[46:47] op_sel_hi:[0,1,1] neg_lo:[1,0,0] neg_hi:[1,0,0]
	v_pk_fma_f32 v[22:23], v[0:1], v[130:131], 0 op_sel_hi:[0,1,0] neg_lo:[1,0,0] neg_hi:[1,0,0]
	ds_read_b128 v[128:131], v69 offset:41472
	s_waitcnt lgkmcnt(8)
	v_pk_fma_f32 v[20:21], v[4:5], v[124:125], v[20:21] op_sel_hi:[0,1,1] neg_lo:[1,0,0] neg_hi:[1,0,0]
	v_pk_fma_f32 v[22:23], v[2:3], v[126:127], v[22:23] op_sel_hi:[0,1,1] neg_lo:[1,0,0] neg_hi:[1,0,0]
	ds_read_b128 v[124:127], v69 offset:40944
	v_cvt_pk_bf16_f32 v3, v162, s0
	s_waitcnt lgkmcnt(8)
	v_pk_fma_f32 v[20:21], v[8:9], v[238:239], v[20:21] op_sel_hi:[0,1,1] neg_lo:[1,0,0] neg_hi:[1,0,0]
	v_pk_fma_f32 v[22:23], v[6:7], v[240:241], v[22:23] op_sel_hi:[0,1,1] neg_lo:[1,0,0] neg_hi:[1,0,0]
	v_add_u32_e32 v183, 0x9d00, v69
	ds_read2_b32 v[238:239], v183 offset0:57 offset1:197
	v_cvt_pk_bf16_f32 v7, v160, s0
	s_waitcnt lgkmcnt(8)
	v_pk_fma_f32 v[16:17], v[12:13], v[132:133], v[20:21] op_sel_hi:[0,1,1] neg_lo:[1,0,0] neg_hi:[1,0,0]
	v_pk_fma_f32 v[18:19], v[10:11], v[134:135], v[22:23] op_sel_hi:[0,1,1] neg_lo:[1,0,0] neg_hi:[1,0,0]
	ds_read_b128 v[132:135], v69 offset:40960
	v_pk_add_f32 v[46:47], v[16:17], v[18:19]
	v_cvt_pk_bf16_f32 v11, v62, s0
	s_waitcnt lgkmcnt(8)
	v_fma_f32 v16, -v14, v116, v15
	s_waitcnt lgkmcnt(7)
	v_pk_fma_f32 v[18:19], v[14:15], v[242:243], v[188:189] op_sel_hi:[0,1,1] neg_lo:[1,0,0] neg_hi:[1,0,0]
	s_waitcnt lgkmcnt(6)
	v_pk_fma_f32 v[22:23], v[14:15], v[120:121], v[190:191] op_sel_hi:[0,1,1] neg_lo:[1,0,0] neg_hi:[1,0,0]
	v_pk_fma_f32 v[26:27], v[122:123], v[16:17], v[22:23] op_sel_hi:[1,0,1] neg_lo:[1,0,0] neg_hi:[1,0,0]
	ds_read_b128 v[120:123], v69 offset:41488
	v_pk_fma_f32 v[20:21], v[244:245], v[16:17], v[18:19] op_sel_hi:[1,0,1] neg_lo:[1,0,0] neg_hi:[1,0,0]
	ds_read_b128 v[242:245], v69 offset:41504
	v_fma_f32 v18, -v117, v20, v21
	ds_read_b128 v[116:119], v69 offset:41520
	s_waitcnt lgkmcnt(8)
	v_pk_fma_f32 v[22:23], v[136:137], v[20:21], v[26:27] op_sel_hi:[1,0,1] neg_lo:[1,0,0] neg_hi:[1,0,0]
	s_nop 0
	v_pk_fma_f32 v[26:27], v[138:139], v[18:19], v[22:23] op_sel_hi:[1,0,1] neg_lo:[1,0,0] neg_hi:[1,0,0]
	ds_read_b128 v[136:139], v69 offset:42016
	s_waitcnt lgkmcnt(8)
	v_pk_fma_f32 v[24:25], v[14:15], v[112:113], v[50:51] op_sel_hi:[0,1,1] neg_lo:[1,0,0] neg_hi:[1,0,0]
	v_pk_fma_f32 v[24:25], v[16:17], v[114:115], v[24:25] op_sel_hi:[0,1,1] neg_lo:[1,0,0] neg_hi:[1,0,0]
	ds_read_b128 v[112:115], v69 offset:42032
	s_waitcnt lgkmcnt(8)
	v_pk_fma_f32 v[50:51], v[16:17], v[130:131], 0 op_sel_hi:[0,1,0] neg_lo:[1,0,0] neg_hi:[1,0,0]
	s_waitcnt lgkmcnt(7)
	v_pk_fma_f32 v[24:25], v[20:21], v[124:125], v[24:25] op_sel_hi:[0,1,1] neg_lo:[1,0,0] neg_hi:[1,0,0]
	v_pk_fma_f32 v[24:25], v[126:127], v[18:19], v[24:25] op_sel_hi:[1,0,1] neg_lo:[1,0,0] neg_hi:[1,0,0]
	ds_read_b128 v[124:127], v69 offset:42048
	s_waitcnt lgkmcnt(7)
	v_fma_f32 v22, -v238, v26, v27
	s_waitcnt lgkmcnt(6)
; #define LAS __attribute__((address_space(3)))
; DI void gdn_prep_phase(const int tid, LAS unsigned char* lds, const P& p, int G, int c) {
;     ...
;           for (int kb = 0; kb < 8; ++kb) {
; #pragma unroll
;               for (int pp = 0; pp < 4; ++pp) { const int pr = 4 * kb + pp;
;                   f32x2 s = (f32x2){xs[2 * pr], xs[2 * pr + 1]};
; #pragma unroll
;                   for (int j = 8 * kb; j < 2 * pr; j += 2) { const f32x4 l = *(const LAS f32x4*)(Ls + pr * 136 + j * 2);
;                       s -= (f32x2){l[0], l[1]} * (f32x2){xs[j], xs[j]}; s -= (f32x2){l[2], l[3]} * (f32x2){xs[j + 1], xs[j + 1]}; }
;                   xs[2 * pr] = s[0];
;                   xs[2 * pr + 1] = s[1] - Ls[pr * 136 + 4 * pr + 1] * s[0]; }
; #pragma unroll
;               for (int pr = 4 * kb + 4; pr < 32; ++pr) {
;                   f32x2 s0 = (f32x2){xs[2 * pr], xs[2 * pr + 1]}, s1 = (f32x2){0.f, 0.f};
; #pragma unroll
;                   for (int q = 0; q < 4; ++q) { const int j = 8 * kb + 2 * q; const f32x4 l = *(const LAS f32x4*)(Ls + pr * 136 + j * 2);
;                       s0 -= (f32x2){l[0], l[1]} * (f32x2){xs[j], xs[j]}; s1 -= (f32x2){l[2], l[3]} * (f32x2){xs[j + 1], xs[j + 1]}; }
;                   const f32x2 s = s0 + s1; xs[2 * pr] = s[0]; xs[2 * pr + 1] = s[1]; }
	v_pk_fma_f32 v[24:25], v[132:133], v[26:27], v[24:25] op_sel_hi:[1,0,1] neg_lo:[1,0,0] neg_hi:[1,0,0]
	s_nop 0
	v_pk_fma_f32 v[28:29], v[134:135], v[22:23], v[24:25] op_sel_hi:[1,0,1] neg_lo:[1,0,0] neg_hi:[1,0,0]
	ds_read_b128 v[132:135], v69 offset:42064
	v_pk_fma_f32 v[30:31], v[14:15], v[128:129], v[164:165] op_sel_hi:[0,1,1] neg_lo:[1,0,0] neg_hi:[1,0,0]
	ds_read_b128 v[128:131], v69 offset:42560
	v_fma_f32 v24, -v239, v28, v29
	ds_read_b128 v[238:241], v69 offset:42576
	s_waitcnt lgkmcnt(8)
	v_pk_fma_f32 v[30:31], v[20:21], v[120:121], v[30:31] op_sel_hi:[0,1,1] neg_lo:[1,0,0] neg_hi:[1,0,0]
	v_pk_fma_f32 v[50:51], v[18:19], v[122:123], v[50:51] op_sel_hi:[0,1,1] neg_lo:[1,0,0] neg_hi:[1,0,0]
	ds_read_b128 v[120:123], v69 offset:42592
	s_waitcnt lgkmcnt(8)
	v_pk_fma_f32 v[30:31], v[242:243], v[26:27], v[30:31] op_sel_hi:[1,0,1] neg_lo:[1,0,0] neg_hi:[1,0,0]
	v_pk_fma_f32 v[50:51], v[244:245], v[22:23], v[50:51] op_sel_hi:[1,0,1] neg_lo:[1,0,0] neg_hi:[1,0,0]
	ds_read_b128 v[242:245], v69 offset:42608
	s_waitcnt lgkmcnt(8)
	v_pk_fma_f32 v[30:31], v[116:117], v[28:29], v[30:31] op_sel_hi:[1,0,1] neg_lo:[1,0,0] neg_hi:[1,0,0]
	v_pk_fma_f32 v[50:51], v[118:119], v[24:25], v[50:51] op_sel_hi:[1,0,1] neg_lo:[1,0,0] neg_hi:[1,0,0]
	ds_read_b128 v[116:119], v69 offset:43104
	v_pk_add_f32 v[30:31], v[30:31], v[50:51]
	s_waitcnt lgkmcnt(8)
	v_pk_fma_f32 v[50:51], v[14:15], v[136:137], v[166:167] op_sel_hi:[0,1,1] neg_lo:[1,0,0] neg_hi:[1,0,0]
	v_pk_fma_f32 v[188:189], v[16:17], v[138:139], 0 op_sel_hi:[0,1,0] neg_lo:[1,0,0] neg_hi:[1,0,0]
	ds_read_b128 v[136:139], v69 offset:43120
	s_waitcnt lgkmcnt(8)
	v_pk_fma_f32 v[50:51], v[20:21], v[112:113], v[50:51] op_sel_hi:[0,1,1] neg_lo:[1,0,0] neg_hi:[1,0,0]
	v_pk_fma_f32 v[188:189], v[18:19], v[114:115], v[188:189] op_sel_hi:[0,1,1] neg_lo:[1,0,0] neg_hi:[1,0,0]
	ds_read_b128 v[112:115], v69 offset:43136
	s_waitcnt lgkmcnt(8)
	v_pk_fma_f32 v[50:51], v[26:27], v[124:125], v[50:51] op_sel_hi:[0,1,1] neg_lo:[1,0,0] neg_hi:[1,0,0]
	v_pk_fma_f32 v[188:189], v[126:127], v[22:23], v[188:189] op_sel_hi:[1,0,1] neg_lo:[1,0,0] neg_hi:[1,0,0]
	ds_read_b128 v[124:127], v69 offset:43152
	s_waitcnt lgkmcnt(8)
	v_pk_fma_f32 v[50:51], v[132:133], v[28:29], v[50:51] op_sel_hi:[1,0,1] neg_lo:[1,0,0] neg_hi:[1,0,0]
	v_pk_fma_f32 v[164:165], v[134:135], v[24:25], v[188:189] op_sel_hi:[1,0,1] neg_lo:[1,0,0] neg_hi:[1,0,0]
	ds_read_b128 v[132:135], v69 offset:43648
	v_pk_add_f32 v[196:197], v[50:51], v[164:165]
	s_waitcnt lgkmcnt(8)
	v_pk_fma_f32 v[50:51], v[14:15], v[128:129], v[168:169] op_sel_hi:[0,1,1] neg_lo:[1,0,0] neg_hi:[1,0,0]
	v_pk_fma_f32 v[168:169], v[16:17], v[130:131], 0 op_sel_hi:[0,1,0] neg_lo:[1,0,0] neg_hi:[1,0,0]
	ds_read_b128 v[128:131], v69 offset:43664
	s_waitcnt lgkmcnt(8)
	v_pk_fma_f32 v[50:51], v[20:21], v[238:239], v[50:51] op_sel_hi:[0,1,1] neg_lo:[1,0,0] neg_hi:[1,0,0]
	v_pk_fma_f32 v[168:169], v[18:19], v[240:241], v[168:169] op_sel_hi:[0,1,1] neg_lo:[1,0,0] neg_hi:[1,0,0]
	ds_read_b128 v[238:241], v69 offset:43680
	s_waitcnt lgkmcnt(8)
	v_pk_fma_f32 v[50:51], v[26:27], v[120:121], v[50:51] op_sel_hi:[0,1,1] neg_lo:[1,0,0] neg_hi:[1,0,0]
	v_pk_fma_f32 v[168:169], v[22:23], v[122:123], v[168:169] op_sel_hi:[0,1,1] neg_lo:[1,0,0] neg_hi:[1,0,0]
	ds_read_b128 v[120:123], v69 offset:43696
	s_waitcnt lgkmcnt(8)
	v_pk_fma_f32 v[50:51], v[28:29], v[242:243], v[50:51] op_sel_hi:[0,1,1] neg_lo:[1,0,0] neg_hi:[1,0,0]
	v_pk_fma_f32 v[164:165], v[244:245], v[24:25], v[168:169] op_sel_hi:[1,0,1] neg_lo:[1,0,0] neg_hi:[1,0,0]
	ds_read_b128 v[242:245], v69 offset:44192
	v_pk_add_f32 v[198:199], v[50:51], v[164:165]
	s_waitcnt lgkmcnt(8)
	v_pk_fma_f32 v[50:51], v[14:15], v[116:117], v[170:171] op_sel_hi:[0,1,1] neg_lo:[1,0,0] neg_hi:[1,0,0]
	v_pk_fma_f32 v[168:169], v[16:17], v[118:119], 0 op_sel_hi:[0,1,0] neg_lo:[1,0,0] neg_hi:[1,0,0]
	ds_read_b128 v[116:119], v69 offset:44208
	s_waitcnt lgkmcnt(8)
	v_pk_fma_f32 v[50:51], v[20:21], v[136:137], v[50:51] op_sel_hi:[0,1,1] neg_lo:[1,0,0] neg_hi:[1,0,0]
	v_pk_fma_f32 v[168:169], v[18:19], v[138:139], v[168:169] op_sel_hi:[0,1,1] neg_lo:[1,0,0] neg_hi:[1,0,0]
	ds_read_b128 v[136:139], v69 offset:44224
	s_waitcnt lgkmcnt(8)
	v_pk_fma_f32 v[50:51], v[26:27], v[112:113], v[50:51] op_sel_hi:[0,1,1] neg_lo:[1,0,0] neg_hi:[1,0,0]
	v_pk_fma_f32 v[168:169], v[22:23], v[114:115], v[168:169] op_sel_hi:[0,1,1] neg_lo:[1,0,0] neg_hi:[1,0,0]
	ds_read_b128 v[112:115], v69 offset:44240
	s_waitcnt lgkmcnt(8)
	v_pk_fma_f32 v[50:51], v[28:29], v[124:125], v[50:51] op_sel_hi:[0,1,1] neg_lo:[1,0,0] neg_hi:[1,0,0]
	v_pk_fma_f32 v[164:165], v[24:25], v[126:127], v[168:169] op_sel_hi:[0,1,1] neg_lo:[1,0,0] neg_hi:[1,0,0]
	ds_read_b128 v[124:127], v69 offset:44736
	v_pk_add_f32 v[50:51], v[50:51], v[164:165]
	s_waitcnt lgkmcnt(8)
	v_pk_fma_f32 v[36:37], v[14:15], v[132:133], v[36:37] op_sel_hi:[0,1,1] neg_lo:[1,0,0] neg_hi:[1,0,0]
	v_pk_fma_f32 v[168:169], v[16:17], v[134:135], 0 op_sel_hi:[0,1,0] neg_lo:[1,0,0] neg_hi:[1,0,0]
	ds_read_b128 v[132:135], v69 offset:44752
	s_waitcnt lgkmcnt(8)
	v_pk_fma_f32 v[36:37], v[20:21], v[128:129], v[36:37] op_sel_hi:[0,1,1] neg_lo:[1,0,0] neg_hi:[1,0,0]
	v_pk_fma_f32 v[168:169], v[18:19], v[130:131], v[168:169] op_sel_hi:[0,1,1] neg_lo:[1,0,0] neg_hi:[1,0,0]
	ds_read_b128 v[128:131], v69 offset:44768
	s_waitcnt lgkmcnt(8)
	v_pk_fma_f32 v[36:37], v[26:27], v[238:239], v[36:37] op_sel_hi:[0,1,1] neg_lo:[1,0,0] neg_hi:[1,0,0]
	v_pk_fma_f32 v[168:169], v[22:23], v[240:241], v[168:169] op_sel_hi:[0,1,1] neg_lo:[1,0,0] neg_hi:[1,0,0]
	ds_read_b128 v[238:241], v69 offset:44784
	s_waitcnt lgkmcnt(8)
; #define LAS __attribute__((address_space(3)))
; DI void gdn_prep_phase(const int tid, LAS unsigned char* lds, const P& p, int G, int c) {
;     ...
; #pragma unroll
;           for (int kb = 0; kb < 8; ++kb) {
; #pragma unroll
;               for (int pp = 0; pp < 4; ++pp) { const int pr = 4 * kb + pp;
;                   f32x2 s = (f32x2){xs[2 * pr], xs[2 * pr + 1]};
; #pragma unroll
;                   for (int j = 8 * kb; j < 2 * pr; j += 2) { const f32x4 l = *(const LAS f32x4*)(Ls + pr * 136 + j * 2);
;                       s -= (f32x2){l[0], l[1]} * (f32x2){xs[j], xs[j]}; s -= (f32x2){l[2], l[3]} * (f32x2){xs[j + 1], xs[j + 1]}; }
;                   xs[2 * pr] = s[0];
;                   xs[2 * pr + 1] = s[1] - Ls[pr * 136 + 4 * pr + 1] * s[0]; }
; #pragma unroll
;               for (int pr = 4 * kb + 4; pr < 32; ++pr) {
;                   f32x2 s0 = (f32x2){xs[2 * pr], xs[2 * pr + 1]}, s1 = (f32x2){0.f, 0.f};
; #pragma unroll
;                   for (int q = 0; q < 4; ++q) { const int j = 8 * kb + 2 * q; const f32x4 l = *(const LAS f32x4*)(Ls + pr * 136 + j * 2);
;                       s0 -= (f32x2){l[0], l[1]} * (f32x2){xs[j], xs[j]}; s1 -= (f32x2){l[2], l[3]} * (f32x2){xs[j + 1], xs[j + 1]}; }
;                   const f32x2 s = s0 + s1; xs[2 * pr] = s[0]; xs[2 * pr + 1] = s[1]; }
	v_pk_fma_f32 v[36:37], v[28:29], v[120:121], v[36:37] op_sel_hi:[0,1,1] neg_lo:[1,0,0] neg_hi:[1,0,0]
	v_pk_fma_f32 v[164:165], v[24:25], v[122:123], v[168:169] op_sel_hi:[0,1,1] neg_lo:[1,0,0] neg_hi:[1,0,0]
	ds_read_b128 v[120:123], v69 offset:45280
	v_pk_add_f32 v[164:165], v[36:37], v[164:165]
	s_waitcnt lgkmcnt(8)
	v_pk_fma_f32 v[166:167], v[14:15], v[242:243], v[38:39] op_sel_hi:[0,1,1] neg_lo:[1,0,0] neg_hi:[1,0,0]
	v_pk_fma_f32 v[168:169], v[16:17], v[244:245], 0 op_sel_hi:[0,1,0] neg_lo:[1,0,0] neg_hi:[1,0,0]
	ds_read_b128 v[242:245], v69 offset:45296
	s_waitcnt lgkmcnt(8)
	v_pk_fma_f32 v[166:167], v[20:21], v[116:117], v[166:167] op_sel_hi:[0,1,1] neg_lo:[1,0,0] neg_hi:[1,0,0]
	v_pk_fma_f32 v[168:169], v[18:19], v[118:119], v[168:169] op_sel_hi:[0,1,1] neg_lo:[1,0,0] neg_hi:[1,0,0]
	ds_read_b128 v[116:119], v69 offset:45312
	s_waitcnt lgkmcnt(8)
	v_pk_fma_f32 v[166:167], v[26:27], v[136:137], v[166:167] op_sel_hi:[0,1,1] neg_lo:[1,0,0] neg_hi:[1,0,0]
	v_pk_fma_f32 v[168:169], v[22:23], v[138:139], v[168:169] op_sel_hi:[0,1,1] neg_lo:[1,0,0] neg_hi:[1,0,0]
	ds_read_b128 v[136:139], v69 offset:45328
	s_waitcnt lgkmcnt(8)
	v_pk_fma_f32 v[36:37], v[28:29], v[112:113], v[166:167] op_sel_hi:[0,1,1] neg_lo:[1,0,0] neg_hi:[1,0,0]
	v_pk_fma_f32 v[38:39], v[24:25], v[114:115], v[168:169] op_sel_hi:[0,1,1] neg_lo:[1,0,0] neg_hi:[1,0,0]
	ds_read_b128 v[112:115], v69 offset:45824
	v_pk_add_f32 v[166:167], v[36:37], v[38:39]
	s_waitcnt lgkmcnt(8)
	v_pk_fma_f32 v[168:169], v[14:15], v[124:125], v[172:173] op_sel_hi:[0,1,1] neg_lo:[1,0,0] neg_hi:[1,0,0]
	v_pk_fma_f32 v[170:171], v[16:17], v[126:127], 0 op_sel_hi:[0,1,0] neg_lo:[1,0,0] neg_hi:[1,0,0]
	ds_read_b128 v[124:127], v69 offset:45840
	s_waitcnt lgkmcnt(8)
	v_pk_fma_f32 v[168:169], v[20:21], v[132:133], v[168:169] op_sel_hi:[0,1,1] neg_lo:[1,0,0] neg_hi:[1,0,0]
	v_pk_fma_f32 v[170:171], v[18:19], v[134:135], v[170:171] op_sel_hi:[0,1,1] neg_lo:[1,0,0] neg_hi:[1,0,0]
	ds_read_b128 v[132:135], v69 offset:45856
	s_waitcnt lgkmcnt(8)
	v_pk_fma_f32 v[168:169], v[26:27], v[128:129], v[168:169] op_sel_hi:[0,1,1] neg_lo:[1,0,0] neg_hi:[1,0,0]
	v_pk_fma_f32 v[170:171], v[22:23], v[130:131], v[170:171] op_sel_hi:[0,1,1] neg_lo:[1,0,0] neg_hi:[1,0,0]
	ds_read_b128 v[128:131], v69 offset:45872
	s_waitcnt lgkmcnt(8)
	v_pk_fma_f32 v[36:37], v[28:29], v[238:239], v[168:169] op_sel_hi:[0,1,1] neg_lo:[1,0,0] neg_hi:[1,0,0]
	v_pk_fma_f32 v[38:39], v[24:25], v[240:241], v[170:171] op_sel_hi:[0,1,1] neg_lo:[1,0,0] neg_hi:[1,0,0]
	ds_read_b128 v[238:241], v69 offset:46368
	v_pk_add_f32 v[168:169], v[36:37], v[38:39]
	s_waitcnt lgkmcnt(8)
	v_pk_fma_f32 v[170:171], v[14:15], v[120:121], v[174:175] op_sel_hi:[0,1,1] neg_lo:[1,0,0] neg_hi:[1,0,0]
	v_pk_fma_f32 v[172:173], v[16:17], v[122:123], 0 op_sel_hi:[0,1,0] neg_lo:[1,0,0] neg_hi:[1,0,0]
	ds_read_b128 v[120:123], v69 offset:46384
	s_waitcnt lgkmcnt(8)
	v_pk_fma_f32 v[170:171], v[20:21], v[242:243], v[170:171] op_sel_hi:[0,1,1] neg_lo:[1,0,0] neg_hi:[1,0,0]
	v_pk_fma_f32 v[172:173], v[18:19], v[244:245], v[172:173] op_sel_hi:[0,1,1] neg_lo:[1,0,0] neg_hi:[1,0,0]
	ds_read_b128 v[242:245], v69 offset:46400
	s_waitcnt lgkmcnt(8)
	v_pk_fma_f32 v[170:171], v[26:27], v[116:117], v[170:171] op_sel_hi:[0,1,1] neg_lo:[1,0,0] neg_hi:[1,0,0]
	v_pk_fma_f32 v[172:173], v[22:23], v[118:119], v[172:173] op_sel_hi:[0,1,1] neg_lo:[1,0,0] neg_hi:[1,0,0]
	ds_read_b128 v[116:119], v69 offset:46416
	s_waitcnt lgkmcnt(8)
	v_pk_fma_f32 v[36:37], v[28:29], v[136:137], v[170:171] op_sel_hi:[0,1,1] neg_lo:[1,0,0] neg_hi:[1,0,0]
	v_pk_fma_f32 v[38:39], v[24:25], v[138:139], v[172:173] op_sel_hi:[0,1,1] neg_lo:[1,0,0] neg_hi:[1,0,0]
	ds_read_b128 v[136:139], v69 offset:46912
	v_pk_add_f32 v[170:171], v[36:37], v[38:39]
	s_waitcnt lgkmcnt(8)
	v_pk_fma_f32 v[40:41], v[14:15], v[112:113], v[40:41] op_sel_hi:[0,1,1] neg_lo:[1,0,0] neg_hi:[1,0,0]
	v_pk_fma_f32 v[172:173], v[16:17], v[114:115], 0 op_sel_hi:[0,1,0] neg_lo:[1,0,0] neg_hi:[1,0,0]
	ds_read_b128 v[112:115], v69 offset:46928
	s_waitcnt lgkmcnt(8)
	v_pk_fma_f32 v[40:41], v[20:21], v[124:125], v[40:41] op_sel_hi:[0,1,1] neg_lo:[1,0,0] neg_hi:[1,0,0]
	v_pk_fma_f32 v[172:173], v[18:19], v[126:127], v[172:173] op_sel_hi:[0,1,1] neg_lo:[1,0,0] neg_hi:[1,0,0]
	ds_read_b128 v[124:127], v69 offset:46944
	s_waitcnt lgkmcnt(8)
	v_pk_fma_f32 v[40:41], v[26:27], v[132:133], v[40:41] op_sel_hi:[0,1,1] neg_lo:[1,0,0] neg_hi:[1,0,0]
	v_pk_fma_f32 v[172:173], v[22:23], v[134:135], v[172:173] op_sel_hi:[0,1,1] neg_lo:[1,0,0] neg_hi:[1,0,0]
	ds_read_b128 v[132:135], v69 offset:46960
	s_waitcnt lgkmcnt(8)
	v_pk_fma_f32 v[36:37], v[28:29], v[128:129], v[40:41] op_sel_hi:[0,1,1] neg_lo:[1,0,0] neg_hi:[1,0,0]
	v_pk_fma_f32 v[38:39], v[24:25], v[130:131], v[172:173] op_sel_hi:[0,1,1] neg_lo:[1,0,0] neg_hi:[1,0,0]
	ds_read_b128 v[128:131], v69 offset:47456
	v_pk_add_f32 v[172:173], v[36:37], v[38:39]
	s_waitcnt lgkmcnt(8)
	v_pk_fma_f32 v[40:41], v[14:15], v[238:239], v[42:43] op_sel_hi:[0,1,1] neg_lo:[1,0,0] neg_hi:[1,0,0]
	v_pk_fma_f32 v[42:43], v[16:17], v[240:241], 0 op_sel_hi:[0,1,0] neg_lo:[1,0,0] neg_hi:[1,0,0]
	ds_read_b128 v[238:241], v69 offset:47472
	s_waitcnt lgkmcnt(8)
	v_pk_fma_f32 v[40:41], v[20:21], v[120:121], v[40:41] op_sel_hi:[0,1,1] neg_lo:[1,0,0] neg_hi:[1,0,0]
	v_pk_fma_f32 v[42:43], v[18:19], v[122:123], v[42:43] op_sel_hi:[0,1,1] neg_lo:[1,0,0] neg_hi:[1,0,0]
	ds_read_b128 v[120:123], v69 offset:47488
	s_waitcnt lgkmcnt(8)
	v_pk_fma_f32 v[40:41], v[26:27], v[242:243], v[40:41] op_sel_hi:[0,1,1] neg_lo:[1,0,0] neg_hi:[1,0,0]
	v_pk_fma_f32 v[42:43], v[22:23], v[244:245], v[42:43] op_sel_hi:[0,1,1] neg_lo:[1,0,0] neg_hi:[1,0,0]
	ds_read_b128 v[242:245], v69 offset:47504
	s_waitcnt lgkmcnt(8)
; #define LAS __attribute__((address_space(3)))
; DI void gdn_prep_phase(const int tid, LAS unsigned char* lds, const P& p, int G, int c) {
;     ...
; #pragma unroll
;           for (int kb = 0; kb < 8; ++kb) {
; #pragma unroll
;               for (int pp = 0; pp < 4; ++pp) { const int pr = 4 * kb + pp;
;                   f32x2 s = (f32x2){xs[2 * pr], xs[2 * pr + 1]};
; #pragma unroll
;                   for (int j = 8 * kb; j < 2 * pr; j += 2) { const f32x4 l = *(const LAS f32x4*)(Ls + pr * 136 + j * 2);
;                       s -= (f32x2){l[0], l[1]} * (f32x2){xs[j], xs[j]}; s -= (f32x2){l[2], l[3]} * (f32x2){xs[j + 1], xs[j + 1]}; }
;                   xs[2 * pr] = s[0];
;                   xs[2 * pr + 1] = s[1] - Ls[pr * 136 + 4 * pr + 1] * s[0]; }
; #pragma unroll
;               for (int pr = 4 * kb + 4; pr < 32; ++pr) {
;                   f32x2 s0 = (f32x2){xs[2 * pr], xs[2 * pr + 1]}, s1 = (f32x2){0.f, 0.f};
; #pragma unroll
;                   for (int q = 0; q < 4; ++q) { const int j = 8 * kb + 2 * q; const f32x4 l = *(const LAS f32x4*)(Ls + pr * 136 + j * 2);
;                       s0 -= (f32x2){l[0], l[1]} * (f32x2){xs[j], xs[j]}; s1 -= (f32x2){l[2], l[3]} * (f32x2){xs[j + 1], xs[j + 1]}; }
;                   const f32x2 s = s0 + s1; xs[2 * pr] = s[0]; xs[2 * pr + 1] = s[1]; }
	v_pk_fma_f32 v[36:37], v[28:29], v[116:117], v[40:41] op_sel_hi:[0,1,1] neg_lo:[1,0,0] neg_hi:[1,0,0]
	v_pk_fma_f32 v[38:39], v[24:25], v[118:119], v[42:43] op_sel_hi:[0,1,1] neg_lo:[1,0,0] neg_hi:[1,0,0]
	ds_read_b128 v[116:119], v69 offset:48000
	v_pk_add_f32 v[174:175], v[36:37], v[38:39]
	s_waitcnt lgkmcnt(8)
	v_pk_fma_f32 v[32:33], v[14:15], v[136:137], v[32:33] op_sel_hi:[0,1,1] neg_lo:[1,0,0] neg_hi:[1,0,0]
	v_pk_fma_f32 v[40:41], v[16:17], v[138:139], 0 op_sel_hi:[0,1,0] neg_lo:[1,0,0] neg_hi:[1,0,0]
	ds_read_b128 v[136:139], v69 offset:48016
	s_waitcnt lgkmcnt(8)
	v_pk_fma_f32 v[32:33], v[20:21], v[112:113], v[32:33] op_sel_hi:[0,1,1] neg_lo:[1,0,0] neg_hi:[1,0,0]
	v_pk_fma_f32 v[40:41], v[18:19], v[114:115], v[40:41] op_sel_hi:[0,1,1] neg_lo:[1,0,0] neg_hi:[1,0,0]
	ds_read_b128 v[112:115], v69 offset:48032
	s_waitcnt lgkmcnt(8)
	v_pk_fma_f32 v[32:33], v[26:27], v[124:125], v[32:33] op_sel_hi:[0,1,1] neg_lo:[1,0,0] neg_hi:[1,0,0]
	v_pk_fma_f32 v[40:41], v[22:23], v[126:127], v[40:41] op_sel_hi:[0,1,1] neg_lo:[1,0,0] neg_hi:[1,0,0]
	ds_read_b128 v[124:127], v69 offset:48048
	s_waitcnt lgkmcnt(8)
	v_pk_fma_f32 v[32:33], v[28:29], v[132:133], v[32:33] op_sel_hi:[0,1,1] neg_lo:[1,0,0] neg_hi:[1,0,0]
	v_pk_fma_f32 v[36:37], v[24:25], v[134:135], v[40:41] op_sel_hi:[0,1,1] neg_lo:[1,0,0] neg_hi:[1,0,0]
	ds_read_b128 v[132:135], v69 offset:48544
	v_pk_add_f32 v[188:189], v[32:33], v[36:37]
	s_waitcnt lgkmcnt(8)
	v_pk_fma_f32 v[36:37], v[14:15], v[128:129], v[34:35] op_sel_hi:[0,1,1] neg_lo:[1,0,0] neg_hi:[1,0,0]
	v_pk_fma_f32 v[38:39], v[16:17], v[130:131], 0 op_sel_hi:[0,1,0] neg_lo:[1,0,0] neg_hi:[1,0,0]
	ds_read_b128 v[128:131], v69 offset:48560
	s_waitcnt lgkmcnt(8)
	v_pk_fma_f32 v[36:37], v[20:21], v[238:239], v[36:37] op_sel_hi:[0,1,1] neg_lo:[1,0,0] neg_hi:[1,0,0]
	v_pk_fma_f32 v[38:39], v[18:19], v[240:241], v[38:39] op_sel_hi:[0,1,1] neg_lo:[1,0,0] neg_hi:[1,0,0]
	ds_read_b128 v[238:241], v69 offset:48576
	s_waitcnt lgkmcnt(8)
	v_pk_fma_f32 v[36:37], v[26:27], v[120:121], v[36:37] op_sel_hi:[0,1,1] neg_lo:[1,0,0] neg_hi:[1,0,0]
	v_pk_fma_f32 v[38:39], v[22:23], v[122:123], v[38:39] op_sel_hi:[0,1,1] neg_lo:[1,0,0] neg_hi:[1,0,0]
	ds_read_b128 v[120:123], v69 offset:48592
	s_waitcnt lgkmcnt(8)
	v_pk_fma_f32 v[32:33], v[28:29], v[242:243], v[36:37] op_sel_hi:[0,1,1] neg_lo:[1,0,0] neg_hi:[1,0,0]
	v_pk_fma_f32 v[34:35], v[24:25], v[244:245], v[38:39] op_sel_hi:[0,1,1] neg_lo:[1,0,0] neg_hi:[1,0,0]
	ds_read_b128 v[242:245], v69 offset:49088
	v_pk_add_f32 v[190:191], v[32:33], v[34:35]
	s_waitcnt lgkmcnt(8)
	v_pk_fma_f32 v[36:37], v[14:15], v[116:117], v[176:177] op_sel_hi:[0,1,1] neg_lo:[1,0,0] neg_hi:[1,0,0]
	v_pk_fma_f32 v[38:39], v[16:17], v[118:119], 0 op_sel_hi:[0,1,0] neg_lo:[1,0,0] neg_hi:[1,0,0]
	ds_read_b128 v[116:119], v69 offset:49104
	s_waitcnt lgkmcnt(8)
	v_pk_fma_f32 v[36:37], v[20:21], v[136:137], v[36:37] op_sel_hi:[0,1,1] neg_lo:[1,0,0] neg_hi:[1,0,0]
	v_pk_fma_f32 v[38:39], v[18:19], v[138:139], v[38:39] op_sel_hi:[0,1,1] neg_lo:[1,0,0] neg_hi:[1,0,0]
	ds_read_b128 v[136:139], v69 offset:49120
	s_waitcnt lgkmcnt(8)
	v_pk_fma_f32 v[36:37], v[26:27], v[112:113], v[36:37] op_sel_hi:[0,1,1] neg_lo:[1,0,0] neg_hi:[1,0,0]
	v_pk_fma_f32 v[38:39], v[22:23], v[114:115], v[38:39] op_sel_hi:[0,1,1] neg_lo:[1,0,0] neg_hi:[1,0,0]
	ds_read_b128 v[112:115], v69 offset:49136
	s_waitcnt lgkmcnt(8)
	v_pk_fma_f32 v[32:33], v[28:29], v[124:125], v[36:37] op_sel_hi:[0,1,1] neg_lo:[1,0,0] neg_hi:[1,0,0]
	v_pk_fma_f32 v[34:35], v[24:25], v[126:127], v[38:39] op_sel_hi:[0,1,1] neg_lo:[1,0,0] neg_hi:[1,0,0]
	ds_read_b128 v[124:127], v69 offset:49632
	v_pk_add_f32 v[176:177], v[32:33], v[34:35]
	s_waitcnt lgkmcnt(8)
	v_pk_fma_f32 v[36:37], v[14:15], v[132:133], v[178:179] op_sel_hi:[0,1,1] neg_lo:[1,0,0] neg_hi:[1,0,0]
	v_pk_fma_f32 v[38:39], v[16:17], v[134:135], 0 op_sel_hi:[0,1,0] neg_lo:[1,0,0] neg_hi:[1,0,0]
	ds_read_b128 v[132:135], v69 offset:49648
	s_waitcnt lgkmcnt(8)
	v_pk_fma_f32 v[36:37], v[20:21], v[128:129], v[36:37] op_sel_hi:[0,1,1] neg_lo:[1,0,0] neg_hi:[1,0,0]
	v_pk_fma_f32 v[38:39], v[18:19], v[130:131], v[38:39] op_sel_hi:[0,1,1] neg_lo:[1,0,0] neg_hi:[1,0,0]
	ds_read_b128 v[128:131], v69 offset:49664
	s_waitcnt lgkmcnt(8)
	v_pk_fma_f32 v[36:37], v[26:27], v[238:239], v[36:37] op_sel_hi:[0,1,1] neg_lo:[1,0,0] neg_hi:[1,0,0]
	v_pk_fma_f32 v[38:39], v[22:23], v[240:241], v[38:39] op_sel_hi:[0,1,1] neg_lo:[1,0,0] neg_hi:[1,0,0]
	ds_read_b128 v[238:241], v69 offset:49680
	s_waitcnt lgkmcnt(8)
	v_pk_fma_f32 v[32:33], v[28:29], v[120:121], v[36:37] op_sel_hi:[0,1,1] neg_lo:[1,0,0] neg_hi:[1,0,0]
	v_pk_fma_f32 v[34:35], v[24:25], v[122:123], v[38:39] op_sel_hi:[0,1,1] neg_lo:[1,0,0] neg_hi:[1,0,0]
	ds_read_b128 v[120:123], v69 offset:50176
	v_pk_add_f32 v[178:179], v[32:33], v[34:35]
	s_waitcnt lgkmcnt(8)
	v_pk_fma_f32 v[36:37], v[14:15], v[242:243], v[184:185] op_sel_hi:[0,1,1] neg_lo:[1,0,0] neg_hi:[1,0,0]
	v_pk_fma_f32 v[38:39], v[16:17], v[244:245], 0 op_sel_hi:[0,1,0] neg_lo:[1,0,0] neg_hi:[1,0,0]
	ds_read_b128 v[242:245], v69 offset:50192
	s_waitcnt lgkmcnt(8)
	v_pk_fma_f32 v[36:37], v[20:21], v[116:117], v[36:37] op_sel_hi:[0,1,1] neg_lo:[1,0,0] neg_hi:[1,0,0]
	v_pk_fma_f32 v[38:39], v[18:19], v[118:119], v[38:39] op_sel_hi:[0,1,1] neg_lo:[1,0,0] neg_hi:[1,0,0]
	ds_read_b128 v[116:119], v69 offset:50208
	s_waitcnt lgkmcnt(8)
	v_pk_fma_f32 v[36:37], v[26:27], v[136:137], v[36:37] op_sel_hi:[0,1,1] neg_lo:[1,0,0] neg_hi:[1,0,0]
	v_pk_fma_f32 v[38:39], v[22:23], v[138:139], v[38:39] op_sel_hi:[0,1,1] neg_lo:[1,0,0] neg_hi:[1,0,0]
	ds_read_b128 v[136:139], v69 offset:50224
	s_waitcnt lgkmcnt(8)
; #define LAS __attribute__((address_space(3)))
; DI void gdn_prep_phase(const int tid, LAS unsigned char* lds, const P& p, int G, int c) {
;     ...
; #pragma unroll
;           for (int kb = 0; kb < 8; ++kb) {
; #pragma unroll
;               for (int pp = 0; pp < 4; ++pp) { const int pr = 4 * kb + pp;
;                   f32x2 s = (f32x2){xs[2 * pr], xs[2 * pr + 1]};
; #pragma unroll
;                   for (int j = 8 * kb; j < 2 * pr; j += 2) { const f32x4 l = *(const LAS f32x4*)(Ls + pr * 136 + j * 2);
;                       s -= (f32x2){l[0], l[1]} * (f32x2){xs[j], xs[j]}; s -= (f32x2){l[2], l[3]} * (f32x2){xs[j + 1], xs[j + 1]}; }
;                   xs[2 * pr] = s[0];
;                   xs[2 * pr + 1] = s[1] - Ls[pr * 136 + 4 * pr + 1] * s[0]; }
; #pragma unroll
;               for (int pr = 4 * kb + 4; pr < 32; ++pr) {
;                   f32x2 s0 = (f32x2){xs[2 * pr], xs[2 * pr + 1]}, s1 = (f32x2){0.f, 0.f};
; #pragma unroll
;                   for (int q = 0; q < 4; ++q) { const int j = 8 * kb + 2 * q; const f32x4 l = *(const LAS f32x4*)(Ls + pr * 136 + j * 2);
;                       s0 -= (f32x2){l[0], l[1]} * (f32x2){xs[j], xs[j]}; s1 -= (f32x2){l[2], l[3]} * (f32x2){xs[j + 1], xs[j + 1]}; }
;                   const f32x2 s = s0 + s1; xs[2 * pr] = s[0]; xs[2 * pr + 1] = s[1]; }
	v_pk_fma_f32 v[32:33], v[28:29], v[112:113], v[36:37] op_sel_hi:[0,1,1] neg_lo:[1,0,0] neg_hi:[1,0,0]
	v_pk_fma_f32 v[34:35], v[24:25], v[114:115], v[38:39] op_sel_hi:[0,1,1] neg_lo:[1,0,0] neg_hi:[1,0,0]
	ds_read_b128 v[112:115], v69 offset:50720
	v_pk_add_f32 v[184:185], v[32:33], v[34:35]
	s_waitcnt lgkmcnt(8)
	v_pk_fma_f32 v[36:37], v[14:15], v[124:125], v[186:187] op_sel_hi:[0,1,1] neg_lo:[1,0,0] neg_hi:[1,0,0]
	v_pk_fma_f32 v[38:39], v[16:17], v[126:127], 0 op_sel_hi:[0,1,0] neg_lo:[1,0,0] neg_hi:[1,0,0]
	ds_read_b128 v[124:127], v69 offset:50736
	s_waitcnt lgkmcnt(8)
	v_pk_fma_f32 v[36:37], v[20:21], v[132:133], v[36:37] op_sel_hi:[0,1,1] neg_lo:[1,0,0] neg_hi:[1,0,0]
	v_pk_fma_f32 v[38:39], v[18:19], v[134:135], v[38:39] op_sel_hi:[0,1,1] neg_lo:[1,0,0] neg_hi:[1,0,0]
	ds_read_b128 v[132:135], v69 offset:50752
	s_waitcnt lgkmcnt(8)
	v_pk_fma_f32 v[36:37], v[26:27], v[128:129], v[36:37] op_sel_hi:[0,1,1] neg_lo:[1,0,0] neg_hi:[1,0,0]
	v_pk_fma_f32 v[38:39], v[22:23], v[130:131], v[38:39] op_sel_hi:[0,1,1] neg_lo:[1,0,0] neg_hi:[1,0,0]
	ds_read_b128 v[128:131], v69 offset:50768
	s_waitcnt lgkmcnt(8)
	v_pk_fma_f32 v[32:33], v[28:29], v[238:239], v[36:37] op_sel_hi:[0,1,1] neg_lo:[1,0,0] neg_hi:[1,0,0]
	v_pk_fma_f32 v[34:35], v[24:25], v[240:241], v[38:39] op_sel_hi:[0,1,1] neg_lo:[1,0,0] neg_hi:[1,0,0]
	ds_read_b128 v[238:241], v69 offset:51264
	v_pk_add_f32 v[186:187], v[32:33], v[34:35]
	s_waitcnt lgkmcnt(8)
	v_pk_fma_f32 v[36:37], v[14:15], v[120:121], v[52:53] op_sel_hi:[0,1,1] neg_lo:[1,0,0] neg_hi:[1,0,0]
	v_pk_fma_f32 v[38:39], v[16:17], v[122:123], 0 op_sel_hi:[0,1,0] neg_lo:[1,0,0] neg_hi:[1,0,0]
	ds_read_b128 v[120:123], v69 offset:51280
	s_waitcnt lgkmcnt(8)
	v_pk_fma_f32 v[36:37], v[20:21], v[242:243], v[36:37] op_sel_hi:[0,1,1] neg_lo:[1,0,0] neg_hi:[1,0,0]
	v_pk_fma_f32 v[38:39], v[18:19], v[244:245], v[38:39] op_sel_hi:[0,1,1] neg_lo:[1,0,0] neg_hi:[1,0,0]
	ds_read_b128 v[242:245], v69 offset:51296
	s_waitcnt lgkmcnt(8)
	v_pk_fma_f32 v[36:37], v[26:27], v[116:117], v[36:37] op_sel_hi:[0,1,1] neg_lo:[1,0,0] neg_hi:[1,0,0]
	v_pk_fma_f32 v[38:39], v[22:23], v[118:119], v[38:39] op_sel_hi:[0,1,1] neg_lo:[1,0,0] neg_hi:[1,0,0]
	ds_read_b128 v[116:119], v69 offset:51312
	s_waitcnt lgkmcnt(8)
	v_pk_fma_f32 v[32:33], v[28:29], v[136:137], v[36:37] op_sel_hi:[0,1,1] neg_lo:[1,0,0] neg_hi:[1,0,0]
	v_pk_fma_f32 v[34:35], v[24:25], v[138:139], v[38:39] op_sel_hi:[0,1,1] neg_lo:[1,0,0] neg_hi:[1,0,0]
	ds_read_b128 v[136:139], v69 offset:51808
	v_pk_add_f32 v[52:53], v[32:33], v[34:35]
	s_waitcnt lgkmcnt(8)
	v_pk_fma_f32 v[36:37], v[14:15], v[112:113], v[54:55] op_sel_hi:[0,1,1] neg_lo:[1,0,0] neg_hi:[1,0,0]
	v_pk_fma_f32 v[38:39], v[16:17], v[114:115], 0 op_sel_hi:[0,1,0] neg_lo:[1,0,0] neg_hi:[1,0,0]
	ds_read_b128 v[112:115], v69 offset:51824
	s_waitcnt lgkmcnt(8)
	v_pk_fma_f32 v[36:37], v[20:21], v[124:125], v[36:37] op_sel_hi:[0,1,1] neg_lo:[1,0,0] neg_hi:[1,0,0]
	v_pk_fma_f32 v[38:39], v[18:19], v[126:127], v[38:39] op_sel_hi:[0,1,1] neg_lo:[1,0,0] neg_hi:[1,0,0]
	ds_read_b128 v[124:127], v69 offset:51840
	s_waitcnt lgkmcnt(8)
	v_pk_fma_f32 v[36:37], v[26:27], v[132:133], v[36:37] op_sel_hi:[0,1,1] neg_lo:[1,0,0] neg_hi:[1,0,0]
	v_pk_fma_f32 v[38:39], v[22:23], v[134:135], v[38:39] op_sel_hi:[0,1,1] neg_lo:[1,0,0] neg_hi:[1,0,0]
	ds_read_b128 v[132:135], v69 offset:51856
	s_waitcnt lgkmcnt(8)
	v_pk_fma_f32 v[32:33], v[28:29], v[128:129], v[36:37] op_sel_hi:[0,1,1] neg_lo:[1,0,0] neg_hi:[1,0,0]
	v_pk_fma_f32 v[34:35], v[24:25], v[130:131], v[38:39] op_sel_hi:[0,1,1] neg_lo:[1,0,0] neg_hi:[1,0,0]
	v_add_u32_e32 v141, 0xa200, v69
	ds_read2_b32 v[128:129], v141 offset0:17 offset1:157
	v_pk_add_f32 v[54:55], v[32:33], v[34:35]
	s_waitcnt lgkmcnt(8)
	v_pk_fma_f32 v[36:37], v[14:15], v[238:239], v[44:45] op_sel_hi:[0,1,1] neg_lo:[1,0,0] neg_hi:[1,0,0]
	v_pk_fma_f32 v[38:39], v[16:17], v[240:241], 0 op_sel_hi:[0,1,0] neg_lo:[1,0,0] neg_hi:[1,0,0]
	ds_read_b128 v[238:241], v69 offset:42080
	s_waitcnt lgkmcnt(8)
	v_pk_fma_f32 v[36:37], v[20:21], v[120:121], v[36:37] op_sel_hi:[0,1,1] neg_lo:[1,0,0] neg_hi:[1,0,0]
	v_pk_fma_f32 v[38:39], v[18:19], v[122:123], v[38:39] op_sel_hi:[0,1,1] neg_lo:[1,0,0] neg_hi:[1,0,0]
	ds_read_b128 v[120:123], v69 offset:42624
	s_waitcnt lgkmcnt(8)
	v_pk_fma_f32 v[36:37], v[26:27], v[242:243], v[36:37] op_sel_hi:[0,1,1] neg_lo:[1,0,0] neg_hi:[1,0,0]
	v_pk_fma_f32 v[38:39], v[22:23], v[244:245], v[38:39] op_sel_hi:[0,1,1] neg_lo:[1,0,0] neg_hi:[1,0,0]
	ds_read_b128 v[242:245], v69 offset:42640
	s_waitcnt lgkmcnt(8)
	v_pk_fma_f32 v[32:33], v[28:29], v[116:117], v[36:37] op_sel_hi:[0,1,1] neg_lo:[1,0,0] neg_hi:[1,0,0]
	v_pk_fma_f32 v[34:35], v[24:25], v[118:119], v[38:39] op_sel_hi:[0,1,1] neg_lo:[1,0,0] neg_hi:[1,0,0]
	ds_read_b128 v[116:119], v69 offset:43168
	v_pk_add_f32 v[192:193], v[32:33], v[34:35]
	s_waitcnt lgkmcnt(8)
	v_pk_fma_f32 v[36:37], v[14:15], v[136:137], v[46:47] op_sel_hi:[0,1,1] neg_lo:[1,0,0] neg_hi:[1,0,0]
	v_pk_fma_f32 v[38:39], v[16:17], v[138:139], 0 op_sel_hi:[0,1,0] neg_lo:[1,0,0] neg_hi:[1,0,0]
	ds_read_b128 v[136:139], v69 offset:43712
	v_cvt_pk_bf16_f32 v17, v66, s0
	s_waitcnt lgkmcnt(8)
	v_pk_fma_f32 v[36:37], v[20:21], v[112:113], v[36:37] op_sel_hi:[0,1,1] neg_lo:[1,0,0] neg_hi:[1,0,0]
	v_pk_fma_f32 v[38:39], v[18:19], v[114:115], v[38:39] op_sel_hi:[0,1,1] neg_lo:[1,0,0] neg_hi:[1,0,0]
	ds_read_b128 v[112:115], v69 offset:43184
	v_cvt_pk_bf16_f32 v19, v158, s0
	s_waitcnt lgkmcnt(8)
	v_pk_fma_f32 v[36:37], v[26:27], v[124:125], v[36:37] op_sel_hi:[0,1,1] neg_lo:[1,0,0] neg_hi:[1,0,0]
	v_pk_fma_f32 v[38:39], v[22:23], v[126:127], v[38:39] op_sel_hi:[0,1,1] neg_lo:[1,0,0] neg_hi:[1,0,0]
	v_add_u32_e32 v183, 0xa600, v69
	ds_read2_b32 v[124:125], v183 offset0:41 offset1:181
	s_waitcnt lgkmcnt(8)
; #define LAS __attribute__((address_space(3)))
; DI void gdn_prep_phase(const int tid, LAS unsigned char* lds, const P& p, int G, int c) {
;     ...
; #pragma unroll
;           for (int kb = 0; kb < 8; ++kb) {
; #pragma unroll
;               for (int pp = 0; pp < 4; ++pp) { const int pr = 4 * kb + pp;
;                   f32x2 s = (f32x2){xs[2 * pr], xs[2 * pr + 1]};
; #pragma unroll
;                   for (int j = 8 * kb; j < 2 * pr; j += 2) { const f32x4 l = *(const LAS f32x4*)(Ls + pr * 136 + j * 2);
;                       s -= (f32x2){l[0], l[1]} * (f32x2){xs[j], xs[j]}; s -= (f32x2){l[2], l[3]} * (f32x2){xs[j + 1], xs[j + 1]}; }
;                   xs[2 * pr] = s[0];
;                   xs[2 * pr + 1] = s[1] - Ls[pr * 136 + 4 * pr + 1] * s[0]; }
; #pragma unroll
;               for (int pr = 4 * kb + 4; pr < 32; ++pr) {
;                   f32x2 s0 = (f32x2){xs[2 * pr], xs[2 * pr + 1]}, s1 = (f32x2){0.f, 0.f};
; #pragma unroll
;                   for (int q = 0; q < 4; ++q) { const int j = 8 * kb + 2 * q; const f32x4 l = *(const LAS f32x4*)(Ls + pr * 136 + j * 2);
;                       s0 -= (f32x2){l[0], l[1]} * (f32x2){xs[j], xs[j]}; s1 -= (f32x2){l[2], l[3]} * (f32x2){xs[j + 1], xs[j + 1]}; }
;                   const f32x2 s = s0 + s1; xs[2 * pr] = s[0]; xs[2 * pr + 1] = s[1]; }
	v_pk_fma_f32 v[32:33], v[28:29], v[132:133], v[36:37] op_sel_hi:[0,1,1] neg_lo:[1,0,0] neg_hi:[1,0,0]
	v_pk_fma_f32 v[34:35], v[24:25], v[134:135], v[38:39] op_sel_hi:[0,1,1] neg_lo:[1,0,0] neg_hi:[1,0,0]
	ds_read_b128 v[132:135], v69 offset:43200
	v_pk_add_f32 v[194:195], v[32:33], v[34:35]
	s_waitcnt lgkmcnt(8)
	v_fma_f32 v32, -v30, v128, v31
	s_waitcnt lgkmcnt(7)
	v_pk_fma_f32 v[34:35], v[30:31], v[238:239], v[196:197] op_sel_hi:[0,1,1] neg_lo:[1,0,0] neg_hi:[1,0,0]
	s_waitcnt lgkmcnt(6)
	v_pk_fma_f32 v[38:39], v[30:31], v[120:121], v[198:199] op_sel_hi:[0,1,1] neg_lo:[1,0,0] neg_hi:[1,0,0]
	v_pk_fma_f32 v[42:43], v[122:123], v[32:33], v[38:39] op_sel_hi:[1,0,1] neg_lo:[1,0,0] neg_hi:[1,0,0]
	ds_read_b128 v[120:123], v69 offset:43728
	v_pk_fma_f32 v[36:37], v[240:241], v[32:33], v[34:35] op_sel_hi:[1,0,1] neg_lo:[1,0,0] neg_hi:[1,0,0]
	ds_read_b128 v[238:241], v69 offset:43744
	v_fma_f32 v34, -v129, v36, v37
	ds_read_b128 v[128:131], v69 offset:43760
	s_waitcnt lgkmcnt(8)
	v_pk_fma_f32 v[38:39], v[242:243], v[36:37], v[42:43] op_sel_hi:[1,0,1] neg_lo:[1,0,0] neg_hi:[1,0,0]
	s_nop 0
	v_pk_fma_f32 v[42:43], v[244:245], v[34:35], v[38:39] op_sel_hi:[1,0,1] neg_lo:[1,0,0] neg_hi:[1,0,0]
	ds_read_b128 v[242:245], v69 offset:44256
	s_waitcnt lgkmcnt(8)
	v_pk_fma_f32 v[40:41], v[30:31], v[116:117], v[50:51] op_sel_hi:[0,1,1] neg_lo:[1,0,0] neg_hi:[1,0,0]
	v_pk_fma_f32 v[40:41], v[32:33], v[118:119], v[40:41] op_sel_hi:[0,1,1] neg_lo:[1,0,0] neg_hi:[1,0,0]
	ds_read_b128 v[116:119], v69 offset:44272
	s_waitcnt lgkmcnt(8)
	v_pk_fma_f32 v[50:51], v[32:33], v[138:139], 0 op_sel_hi:[0,1,0] neg_lo:[1,0,0] neg_hi:[1,0,0]
	s_waitcnt lgkmcnt(7)
	v_pk_fma_f32 v[40:41], v[36:37], v[112:113], v[40:41] op_sel_hi:[0,1,1] neg_lo:[1,0,0] neg_hi:[1,0,0]
	v_pk_fma_f32 v[40:41], v[114:115], v[34:35], v[40:41] op_sel_hi:[1,0,1] neg_lo:[1,0,0] neg_hi:[1,0,0]
	ds_read_b128 v[112:115], v69 offset:44288
	s_waitcnt lgkmcnt(7)
	v_fma_f32 v38, -v124, v42, v43
	s_waitcnt lgkmcnt(6)
	v_pk_fma_f32 v[40:41], v[132:133], v[42:43], v[40:41] op_sel_hi:[1,0,1] neg_lo:[1,0,0] neg_hi:[1,0,0]
	s_nop 0
	v_pk_fma_f32 v[44:45], v[134:135], v[38:39], v[40:41] op_sel_hi:[1,0,1] neg_lo:[1,0,0] neg_hi:[1,0,0]
	ds_read_b128 v[132:135], v69 offset:44304
	v_pk_fma_f32 v[46:47], v[30:31], v[136:137], v[164:165] op_sel_hi:[0,1,1] neg_lo:[1,0,0] neg_hi:[1,0,0]
	ds_read_b128 v[136:139], v69 offset:44800
	v_fma_f32 v40, -v125, v44, v45
	ds_read_b128 v[124:127], v69 offset:44816
	s_waitcnt lgkmcnt(8)
	v_pk_fma_f32 v[46:47], v[36:37], v[120:121], v[46:47] op_sel_hi:[0,1,1] neg_lo:[1,0,0] neg_hi:[1,0,0]
	v_pk_fma_f32 v[50:51], v[34:35], v[122:123], v[50:51] op_sel_hi:[0,1,1] neg_lo:[1,0,0] neg_hi:[1,0,0]
	ds_read_b128 v[120:123], v69 offset:44832
	s_waitcnt lgkmcnt(8)
	v_pk_fma_f32 v[46:47], v[238:239], v[42:43], v[46:47] op_sel_hi:[1,0,1] neg_lo:[1,0,0] neg_hi:[1,0,0]
	v_pk_fma_f32 v[50:51], v[240:241], v[38:39], v[50:51] op_sel_hi:[1,0,1] neg_lo:[1,0,0] neg_hi:[1,0,0]
	ds_read_b128 v[238:241], v69 offset:44848
	s_waitcnt lgkmcnt(8)
	v_pk_fma_f32 v[46:47], v[128:129], v[44:45], v[46:47] op_sel_hi:[1,0,1] neg_lo:[1,0,0] neg_hi:[1,0,0]
	v_pk_fma_f32 v[50:51], v[130:131], v[40:41], v[50:51] op_sel_hi:[1,0,1] neg_lo:[1,0,0] neg_hi:[1,0,0]
	ds_read_b128 v[128:131], v69 offset:45344
	v_pk_add_f32 v[46:47], v[46:47], v[50:51]
	s_waitcnt lgkmcnt(8)
	v_pk_fma_f32 v[50:51], v[30:31], v[242:243], v[166:167] op_sel_hi:[0,1,1] neg_lo:[1,0,0] neg_hi:[1,0,0]
	v_pk_fma_f32 v[196:197], v[32:33], v[244:245], 0 op_sel_hi:[0,1,0] neg_lo:[1,0,0] neg_hi:[1,0,0]
	ds_read_b128 v[242:245], v69 offset:45360
	s_waitcnt lgkmcnt(8)
	v_pk_fma_f32 v[50:51], v[36:37], v[116:117], v[50:51] op_sel_hi:[0,1,1] neg_lo:[1,0,0] neg_hi:[1,0,0]
	v_pk_fma_f32 v[196:197], v[34:35], v[118:119], v[196:197] op_sel_hi:[0,1,1] neg_lo:[1,0,0] neg_hi:[1,0,0]
	ds_read_b128 v[116:119], v69 offset:45376
	s_waitcnt lgkmcnt(8)
	v_pk_fma_f32 v[50:51], v[42:43], v[112:113], v[50:51] op_sel_hi:[0,1,1] neg_lo:[1,0,0] neg_hi:[1,0,0]
	v_pk_fma_f32 v[196:197], v[114:115], v[38:39], v[196:197] op_sel_hi:[1,0,1] neg_lo:[1,0,0] neg_hi:[1,0,0]
	ds_read_b128 v[112:115], v69 offset:45392
	s_waitcnt lgkmcnt(8)
	v_pk_fma_f32 v[50:51], v[132:133], v[44:45], v[50:51] op_sel_hi:[1,0,1] neg_lo:[1,0,0] neg_hi:[1,0,0]
	v_pk_fma_f32 v[164:165], v[134:135], v[40:41], v[196:197] op_sel_hi:[1,0,1] neg_lo:[1,0,0] neg_hi:[1,0,0]
	ds_read_b128 v[132:135], v69 offset:45888
	v_pk_add_f32 v[164:165], v[50:51], v[164:165]
	s_waitcnt lgkmcnt(8)
	v_pk_fma_f32 v[50:51], v[30:31], v[136:137], v[168:169] op_sel_hi:[0,1,1] neg_lo:[1,0,0] neg_hi:[1,0,0]
	v_pk_fma_f32 v[196:197], v[32:33], v[138:139], 0 op_sel_hi:[0,1,0] neg_lo:[1,0,0] neg_hi:[1,0,0]
	ds_read_b128 v[136:139], v69 offset:45904
	s_waitcnt lgkmcnt(8)
	v_pk_fma_f32 v[50:51], v[36:37], v[124:125], v[50:51] op_sel_hi:[0,1,1] neg_lo:[1,0,0] neg_hi:[1,0,0]
	v_pk_fma_f32 v[196:197], v[34:35], v[126:127], v[196:197] op_sel_hi:[0,1,1] neg_lo:[1,0,0] neg_hi:[1,0,0]
	ds_read_b128 v[124:127], v69 offset:45920
	s_waitcnt lgkmcnt(8)
	v_pk_fma_f32 v[50:51], v[42:43], v[120:121], v[50:51] op_sel_hi:[0,1,1] neg_lo:[1,0,0] neg_hi:[1,0,0]
	v_pk_fma_f32 v[196:197], v[38:39], v[122:123], v[196:197] op_sel_hi:[0,1,1] neg_lo:[1,0,0] neg_hi:[1,0,0]
	ds_read_b128 v[120:123], v69 offset:45936
	s_waitcnt lgkmcnt(8)
	v_pk_fma_f32 v[50:51], v[44:45], v[238:239], v[50:51] op_sel_hi:[0,1,1] neg_lo:[1,0,0] neg_hi:[1,0,0]
	v_pk_fma_f32 v[166:167], v[240:241], v[40:41], v[196:197] op_sel_hi:[1,0,1] neg_lo:[1,0,0] neg_hi:[1,0,0]
	ds_read_b128 v[238:241], v69 offset:46432
	v_pk_add_f32 v[168:169], v[50:51], v[166:167]
	s_waitcnt lgkmcnt(8)
; #define LAS __attribute__((address_space(3)))
; DI void gdn_prep_phase(const int tid, LAS unsigned char* lds, const P& p, int G, int c) {
;     ...
;               for (int pr = 4 * kb + 4; pr < 32; ++pr) {
;                   f32x2 s0 = (f32x2){xs[2 * pr], xs[2 * pr + 1]}, s1 = (f32x2){0.f, 0.f};
; #pragma unroll
;                   for (int q = 0; q < 4; ++q) { const int j = 8 * kb + 2 * q; const f32x4 l = *(const LAS f32x4*)(Ls + pr * 136 + j * 2);
;                       s0 -= (f32x2){l[0], l[1]} * (f32x2){xs[j], xs[j]}; s1 -= (f32x2){l[2], l[3]} * (f32x2){xs[j + 1], xs[j + 1]}; }
;                   const f32x2 s = s0 + s1; xs[2 * pr] = s[0]; xs[2 * pr + 1] = s[1]; }
	v_pk_fma_f32 v[50:51], v[30:31], v[128:129], v[170:171] op_sel_hi:[0,1,1] neg_lo:[1,0,0] neg_hi:[1,0,0]
	v_pk_fma_f32 v[166:167], v[32:33], v[130:131], 0 op_sel_hi:[0,1,0] neg_lo:[1,0,0] neg_hi:[1,0,0]
	ds_read_b128 v[128:131], v69 offset:46448
	s_waitcnt lgkmcnt(8)
	v_pk_fma_f32 v[50:51], v[36:37], v[242:243], v[50:51] op_sel_hi:[0,1,1] neg_lo:[1,0,0] neg_hi:[1,0,0]
	v_pk_fma_f32 v[166:167], v[34:35], v[244:245], v[166:167] op_sel_hi:[0,1,1] neg_lo:[1,0,0] neg_hi:[1,0,0]
	ds_read_b128 v[242:245], v69 offset:46464
	s_waitcnt lgkmcnt(8)
	v_pk_fma_f32 v[50:51], v[42:43], v[116:117], v[50:51] op_sel_hi:[0,1,1] neg_lo:[1,0,0] neg_hi:[1,0,0]
	v_pk_fma_f32 v[166:167], v[38:39], v[118:119], v[166:167] op_sel_hi:[0,1,1] neg_lo:[1,0,0] neg_hi:[1,0,0]
	ds_read_b128 v[116:119], v69 offset:46480
	s_waitcnt lgkmcnt(8)
	v_pk_fma_f32 v[50:51], v[44:45], v[112:113], v[50:51] op_sel_hi:[0,1,1] neg_lo:[1,0,0] neg_hi:[1,0,0]
	v_pk_fma_f32 v[166:167], v[40:41], v[114:115], v[166:167] op_sel_hi:[0,1,1] neg_lo:[1,0,0] neg_hi:[1,0,0]
	ds_read_b128 v[112:115], v69 offset:46976
	v_pk_add_f32 v[166:167], v[50:51], v[166:167]
	s_waitcnt lgkmcnt(8)
	v_pk_fma_f32 v[50:51], v[30:31], v[132:133], v[172:173] op_sel_hi:[0,1,1] neg_lo:[1,0,0] neg_hi:[1,0,0]
	v_pk_fma_f32 v[196:197], v[32:33], v[134:135], 0 op_sel_hi:[0,1,0] neg_lo:[1,0,0] neg_hi:[1,0,0]
	ds_read_b128 v[132:135], v69 offset:46992
	s_waitcnt lgkmcnt(8)
	v_pk_fma_f32 v[50:51], v[36:37], v[136:137], v[50:51] op_sel_hi:[0,1,1] neg_lo:[1,0,0] neg_hi:[1,0,0]
	v_pk_fma_f32 v[196:197], v[34:35], v[138:139], v[196:197] op_sel_hi:[0,1,1] neg_lo:[1,0,0] neg_hi:[1,0,0]
	ds_read_b128 v[136:139], v69 offset:47008
	s_waitcnt lgkmcnt(8)
	v_pk_fma_f32 v[50:51], v[42:43], v[124:125], v[50:51] op_sel_hi:[0,1,1] neg_lo:[1,0,0] neg_hi:[1,0,0]
	v_pk_fma_f32 v[196:197], v[38:39], v[126:127], v[196:197] op_sel_hi:[0,1,1] neg_lo:[1,0,0] neg_hi:[1,0,0]
	ds_read_b128 v[124:127], v69 offset:47024
	s_waitcnt lgkmcnt(8)
	v_pk_fma_f32 v[50:51], v[44:45], v[120:121], v[50:51] op_sel_hi:[0,1,1] neg_lo:[1,0,0] neg_hi:[1,0,0]
	v_pk_fma_f32 v[170:171], v[40:41], v[122:123], v[196:197] op_sel_hi:[0,1,1] neg_lo:[1,0,0] neg_hi:[1,0,0]
	ds_read_b128 v[120:123], v69 offset:47520
	v_pk_add_f32 v[172:173], v[50:51], v[170:171]
	s_waitcnt lgkmcnt(8)
	v_pk_fma_f32 v[50:51], v[30:31], v[238:239], v[174:175] op_sel_hi:[0,1,1] neg_lo:[1,0,0] neg_hi:[1,0,0]
	v_pk_fma_f32 v[170:171], v[32:33], v[240:241], 0 op_sel_hi:[0,1,0] neg_lo:[1,0,0] neg_hi:[1,0,0]
	ds_read_b128 v[238:241], v69 offset:47536
	s_waitcnt lgkmcnt(8)
	v_pk_fma_f32 v[50:51], v[36:37], v[128:129], v[50:51] op_sel_hi:[0,1,1] neg_lo:[1,0,0] neg_hi:[1,0,0]
	v_pk_fma_f32 v[170:171], v[34:35], v[130:131], v[170:171] op_sel_hi:[0,1,1] neg_lo:[1,0,0] neg_hi:[1,0,0]
	ds_read_b128 v[128:131], v69 offset:47552
	s_waitcnt lgkmcnt(8)
	v_pk_fma_f32 v[50:51], v[42:43], v[242:243], v[50:51] op_sel_hi:[0,1,1] neg_lo:[1,0,0] neg_hi:[1,0,0]
	v_pk_fma_f32 v[170:171], v[38:39], v[244:245], v[170:171] op_sel_hi:[0,1,1] neg_lo:[1,0,0] neg_hi:[1,0,0]
	ds_read_b128 v[242:245], v69 offset:47568
	s_waitcnt lgkmcnt(8)
	v_pk_fma_f32 v[50:51], v[44:45], v[116:117], v[50:51] op_sel_hi:[0,1,1] neg_lo:[1,0,0] neg_hi:[1,0,0]
	v_pk_fma_f32 v[170:171], v[40:41], v[118:119], v[170:171] op_sel_hi:[0,1,1] neg_lo:[1,0,0] neg_hi:[1,0,0]
	ds_read_b128 v[116:119], v69 offset:48064
	v_pk_add_f32 v[174:175], v[50:51], v[170:171]
	s_waitcnt lgkmcnt(8)
	v_pk_fma_f32 v[50:51], v[30:31], v[112:113], v[188:189] op_sel_hi:[0,1,1] neg_lo:[1,0,0] neg_hi:[1,0,0]
	v_pk_fma_f32 v[170:171], v[32:33], v[114:115], 0 op_sel_hi:[0,1,0] neg_lo:[1,0,0] neg_hi:[1,0,0]
	ds_read_b128 v[112:115], v69 offset:48080
	s_waitcnt lgkmcnt(8)
	v_pk_fma_f32 v[50:51], v[36:37], v[132:133], v[50:51] op_sel_hi:[0,1,1] neg_lo:[1,0,0] neg_hi:[1,0,0]
	v_pk_fma_f32 v[170:171], v[34:35], v[134:135], v[170:171] op_sel_hi:[0,1,1] neg_lo:[1,0,0] neg_hi:[1,0,0]
	ds_read_b128 v[132:135], v69 offset:48096
	s_waitcnt lgkmcnt(8)
	v_pk_fma_f32 v[50:51], v[42:43], v[136:137], v[50:51] op_sel_hi:[0,1,1] neg_lo:[1,0,0] neg_hi:[1,0,0]
	v_pk_fma_f32 v[170:171], v[38:39], v[138:139], v[170:171] op_sel_hi:[0,1,1] neg_lo:[1,0,0] neg_hi:[1,0,0]
	ds_read_b128 v[136:139], v69 offset:48112
	s_waitcnt lgkmcnt(8)
	v_pk_fma_f32 v[50:51], v[44:45], v[124:125], v[50:51] op_sel_hi:[0,1,1] neg_lo:[1,0,0] neg_hi:[1,0,0]
	v_pk_fma_f32 v[170:171], v[40:41], v[126:127], v[170:171] op_sel_hi:[0,1,1] neg_lo:[1,0,0] neg_hi:[1,0,0]
	ds_read_b128 v[124:127], v69 offset:48608
	v_pk_add_f32 v[188:189], v[50:51], v[170:171]
	s_waitcnt lgkmcnt(8)
	v_pk_fma_f32 v[50:51], v[30:31], v[120:121], v[190:191] op_sel_hi:[0,1,1] neg_lo:[1,0,0] neg_hi:[1,0,0]
	v_pk_fma_f32 v[170:171], v[32:33], v[122:123], 0 op_sel_hi:[0,1,0] neg_lo:[1,0,0] neg_hi:[1,0,0]
	ds_read_b128 v[120:123], v69 offset:48624
	s_waitcnt lgkmcnt(8)
	v_pk_fma_f32 v[50:51], v[36:37], v[238:239], v[50:51] op_sel_hi:[0,1,1] neg_lo:[1,0,0] neg_hi:[1,0,0]
	v_pk_fma_f32 v[170:171], v[34:35], v[240:241], v[170:171] op_sel_hi:[0,1,1] neg_lo:[1,0,0] neg_hi:[1,0,0]
	ds_read_b128 v[238:241], v69 offset:48640
	s_waitcnt lgkmcnt(8)
	v_pk_fma_f32 v[50:51], v[42:43], v[128:129], v[50:51] op_sel_hi:[0,1,1] neg_lo:[1,0,0] neg_hi:[1,0,0]
	v_pk_fma_f32 v[170:171], v[38:39], v[130:131], v[170:171] op_sel_hi:[0,1,1] neg_lo:[1,0,0] neg_hi:[1,0,0]
	ds_read_b128 v[128:131], v69 offset:48656
	s_waitcnt lgkmcnt(8)
	v_pk_fma_f32 v[50:51], v[44:45], v[242:243], v[50:51] op_sel_hi:[0,1,1] neg_lo:[1,0,0] neg_hi:[1,0,0]
	v_pk_fma_f32 v[170:171], v[40:41], v[244:245], v[170:171] op_sel_hi:[0,1,1] neg_lo:[1,0,0] neg_hi:[1,0,0]
	ds_read_b128 v[242:245], v69 offset:49152
	v_pk_add_f32 v[190:191], v[50:51], v[170:171]
	s_waitcnt lgkmcnt(8)
; #define LAS __attribute__((address_space(3)))
; DI void gdn_prep_phase(const int tid, LAS unsigned char* lds, const P& p, int G, int c) {
;     ...
;               for (int pr = 4 * kb + 4; pr < 32; ++pr) {
;                   f32x2 s0 = (f32x2){xs[2 * pr], xs[2 * pr + 1]}, s1 = (f32x2){0.f, 0.f};
; #pragma unroll
;                   for (int q = 0; q < 4; ++q) { const int j = 8 * kb + 2 * q; const f32x4 l = *(const LAS f32x4*)(Ls + pr * 136 + j * 2);
;                       s0 -= (f32x2){l[0], l[1]} * (f32x2){xs[j], xs[j]}; s1 -= (f32x2){l[2], l[3]} * (f32x2){xs[j + 1], xs[j + 1]}; }
;                   const f32x2 s = s0 + s1; xs[2 * pr] = s[0]; xs[2 * pr + 1] = s[1]; }
	v_pk_fma_f32 v[50:51], v[30:31], v[116:117], v[176:177] op_sel_hi:[0,1,1] neg_lo:[1,0,0] neg_hi:[1,0,0]
	v_pk_fma_f32 v[170:171], v[32:33], v[118:119], 0 op_sel_hi:[0,1,0] neg_lo:[1,0,0] neg_hi:[1,0,0]
	ds_read_b128 v[116:119], v69 offset:49168
	s_waitcnt lgkmcnt(8)
	v_pk_fma_f32 v[50:51], v[36:37], v[112:113], v[50:51] op_sel_hi:[0,1,1] neg_lo:[1,0,0] neg_hi:[1,0,0]
	v_pk_fma_f32 v[170:171], v[34:35], v[114:115], v[170:171] op_sel_hi:[0,1,1] neg_lo:[1,0,0] neg_hi:[1,0,0]
	ds_read_b128 v[112:115], v69 offset:49184
	s_waitcnt lgkmcnt(8)
	v_pk_fma_f32 v[50:51], v[42:43], v[132:133], v[50:51] op_sel_hi:[0,1,1] neg_lo:[1,0,0] neg_hi:[1,0,0]
	v_pk_fma_f32 v[170:171], v[38:39], v[134:135], v[170:171] op_sel_hi:[0,1,1] neg_lo:[1,0,0] neg_hi:[1,0,0]
	ds_read_b128 v[132:135], v69 offset:49200
	s_waitcnt lgkmcnt(8)
	v_pk_fma_f32 v[50:51], v[44:45], v[136:137], v[50:51] op_sel_hi:[0,1,1] neg_lo:[1,0,0] neg_hi:[1,0,0]
	v_pk_fma_f32 v[170:171], v[40:41], v[138:139], v[170:171] op_sel_hi:[0,1,1] neg_lo:[1,0,0] neg_hi:[1,0,0]
	ds_read_b128 v[136:139], v69 offset:49696
	v_pk_add_f32 v[176:177], v[50:51], v[170:171]
	s_waitcnt lgkmcnt(8)
	v_pk_fma_f32 v[50:51], v[30:31], v[124:125], v[178:179] op_sel_hi:[0,1,1] neg_lo:[1,0,0] neg_hi:[1,0,0]
	v_pk_fma_f32 v[170:171], v[32:33], v[126:127], 0 op_sel_hi:[0,1,0] neg_lo:[1,0,0] neg_hi:[1,0,0]
	ds_read_b128 v[124:127], v69 offset:49712
	s_waitcnt lgkmcnt(8)
	v_pk_fma_f32 v[50:51], v[36:37], v[120:121], v[50:51] op_sel_hi:[0,1,1] neg_lo:[1,0,0] neg_hi:[1,0,0]
	v_pk_fma_f32 v[170:171], v[34:35], v[122:123], v[170:171] op_sel_hi:[0,1,1] neg_lo:[1,0,0] neg_hi:[1,0,0]
	ds_read_b128 v[120:123], v69 offset:49728
	s_waitcnt lgkmcnt(8)
	v_pk_fma_f32 v[50:51], v[42:43], v[238:239], v[50:51] op_sel_hi:[0,1,1] neg_lo:[1,0,0] neg_hi:[1,0,0]
	v_pk_fma_f32 v[170:171], v[38:39], v[240:241], v[170:171] op_sel_hi:[0,1,1] neg_lo:[1,0,0] neg_hi:[1,0,0]
	ds_read_b128 v[238:241], v69 offset:49744
	s_waitcnt lgkmcnt(8)
	v_pk_fma_f32 v[50:51], v[44:45], v[128:129], v[50:51] op_sel_hi:[0,1,1] neg_lo:[1,0,0] neg_hi:[1,0,0]
	v_pk_fma_f32 v[170:171], v[40:41], v[130:131], v[170:171] op_sel_hi:[0,1,1] neg_lo:[1,0,0] neg_hi:[1,0,0]
	ds_read_b128 v[128:131], v69 offset:50240
	v_pk_add_f32 v[178:179], v[50:51], v[170:171]
	s_waitcnt lgkmcnt(8)
	v_pk_fma_f32 v[50:51], v[30:31], v[242:243], v[184:185] op_sel_hi:[0,1,1] neg_lo:[1,0,0] neg_hi:[1,0,0]
	v_pk_fma_f32 v[170:171], v[32:33], v[244:245], 0 op_sel_hi:[0,1,0] neg_lo:[1,0,0] neg_hi:[1,0,0]
	ds_read_b128 v[242:245], v69 offset:50256
	s_waitcnt lgkmcnt(8)
	v_pk_fma_f32 v[50:51], v[36:37], v[116:117], v[50:51] op_sel_hi:[0,1,1] neg_lo:[1,0,0] neg_hi:[1,0,0]
	v_pk_fma_f32 v[170:171], v[34:35], v[118:119], v[170:171] op_sel_hi:[0,1,1] neg_lo:[1,0,0] neg_hi:[1,0,0]
	ds_read_b128 v[116:119], v69 offset:50272
	s_waitcnt lgkmcnt(8)
	v_pk_fma_f32 v[50:51], v[42:43], v[112:113], v[50:51] op_sel_hi:[0,1,1] neg_lo:[1,0,0] neg_hi:[1,0,0]
	v_pk_fma_f32 v[170:171], v[38:39], v[114:115], v[170:171] op_sel_hi:[0,1,1] neg_lo:[1,0,0] neg_hi:[1,0,0]
	ds_read_b128 v[112:115], v69 offset:50288
	s_waitcnt lgkmcnt(8)
	v_pk_fma_f32 v[50:51], v[44:45], v[132:133], v[50:51] op_sel_hi:[0,1,1] neg_lo:[1,0,0] neg_hi:[1,0,0]
	v_pk_fma_f32 v[170:171], v[40:41], v[134:135], v[170:171] op_sel_hi:[0,1,1] neg_lo:[1,0,0] neg_hi:[1,0,0]
	ds_read_b128 v[132:135], v69 offset:50784
	v_pk_add_f32 v[184:185], v[50:51], v[170:171]
	s_waitcnt lgkmcnt(8)
	v_pk_fma_f32 v[50:51], v[30:31], v[136:137], v[186:187] op_sel_hi:[0,1,1] neg_lo:[1,0,0] neg_hi:[1,0,0]
	v_pk_fma_f32 v[170:171], v[32:33], v[138:139], 0 op_sel_hi:[0,1,0] neg_lo:[1,0,0] neg_hi:[1,0,0]
	ds_read_b128 v[136:139], v69 offset:50800
	s_waitcnt lgkmcnt(8)
	v_pk_fma_f32 v[50:51], v[36:37], v[124:125], v[50:51] op_sel_hi:[0,1,1] neg_lo:[1,0,0] neg_hi:[1,0,0]
	v_pk_fma_f32 v[170:171], v[34:35], v[126:127], v[170:171] op_sel_hi:[0,1,1] neg_lo:[1,0,0] neg_hi:[1,0,0]
	ds_read_b128 v[124:127], v69 offset:50816
	s_waitcnt lgkmcnt(8)
	v_pk_fma_f32 v[50:51], v[42:43], v[120:121], v[50:51] op_sel_hi:[0,1,1] neg_lo:[1,0,0] neg_hi:[1,0,0]
	v_pk_fma_f32 v[170:171], v[38:39], v[122:123], v[170:171] op_sel_hi:[0,1,1] neg_lo:[1,0,0] neg_hi:[1,0,0]
	ds_read_b128 v[120:123], v69 offset:50832
	s_waitcnt lgkmcnt(8)
	v_pk_fma_f32 v[50:51], v[44:45], v[238:239], v[50:51] op_sel_hi:[0,1,1] neg_lo:[1,0,0] neg_hi:[1,0,0]
	v_pk_fma_f32 v[170:171], v[40:41], v[240:241], v[170:171] op_sel_hi:[0,1,1] neg_lo:[1,0,0] neg_hi:[1,0,0]
	ds_read_b128 v[238:241], v69 offset:51328
	v_pk_add_f32 v[186:187], v[50:51], v[170:171]
	s_waitcnt lgkmcnt(8)
	v_pk_fma_f32 v[170:171], v[30:31], v[128:129], v[52:53] op_sel_hi:[0,1,1] neg_lo:[1,0,0] neg_hi:[1,0,0]
	v_pk_fma_f32 v[196:197], v[32:33], v[130:131], 0 op_sel_hi:[0,1,0] neg_lo:[1,0,0] neg_hi:[1,0,0]
	ds_read_b128 v[128:131], v69 offset:51344
	s_waitcnt lgkmcnt(8)
	v_pk_fma_f32 v[170:171], v[36:37], v[242:243], v[170:171] op_sel_hi:[0,1,1] neg_lo:[1,0,0] neg_hi:[1,0,0]
	v_pk_fma_f32 v[196:197], v[34:35], v[244:245], v[196:197] op_sel_hi:[0,1,1] neg_lo:[1,0,0] neg_hi:[1,0,0]
	ds_read_b128 v[242:245], v69 offset:51360
	s_waitcnt lgkmcnt(8)
	v_pk_fma_f32 v[170:171], v[42:43], v[116:117], v[170:171] op_sel_hi:[0,1,1] neg_lo:[1,0,0] neg_hi:[1,0,0]
	v_pk_fma_f32 v[196:197], v[38:39], v[118:119], v[196:197] op_sel_hi:[0,1,1] neg_lo:[1,0,0] neg_hi:[1,0,0]
	ds_read_b128 v[116:119], v69 offset:51376
	s_waitcnt lgkmcnt(8)
	v_pk_fma_f32 v[50:51], v[44:45], v[112:113], v[170:171] op_sel_hi:[0,1,1] neg_lo:[1,0,0] neg_hi:[1,0,0]
	v_pk_fma_f32 v[52:53], v[40:41], v[114:115], v[196:197] op_sel_hi:[0,1,1] neg_lo:[1,0,0] neg_hi:[1,0,0]
	ds_read_b128 v[112:115], v69 offset:51872
	v_pk_add_f32 v[196:197], v[50:51], v[52:53]
	s_waitcnt lgkmcnt(8)
; #define LAS __attribute__((address_space(3)))
; DI void gdn_prep_phase(const int tid, LAS unsigned char* lds, const P& p, int G, int c) {
;     ...
; #pragma unroll
;           for (int kb = 0; kb < 8; ++kb) {
; #pragma unroll
;               for (int pp = 0; pp < 4; ++pp) { const int pr = 4 * kb + pp;
;                   f32x2 s = (f32x2){xs[2 * pr], xs[2 * pr + 1]};
; #pragma unroll
;                   for (int j = 8 * kb; j < 2 * pr; j += 2) { const f32x4 l = *(const LAS f32x4*)(Ls + pr * 136 + j * 2);
;                       s -= (f32x2){l[0], l[1]} * (f32x2){xs[j], xs[j]}; s -= (f32x2){l[2], l[3]} * (f32x2){xs[j + 1], xs[j + 1]}; }
;                   xs[2 * pr] = s[0];
;                   xs[2 * pr + 1] = s[1] - Ls[pr * 136 + 4 * pr + 1] * s[0]; }
; #pragma unroll
;               for (int pr = 4 * kb + 4; pr < 32; ++pr) {
;                   f32x2 s0 = (f32x2){xs[2 * pr], xs[2 * pr + 1]}, s1 = (f32x2){0.f, 0.f};
; #pragma unroll
;                   for (int q = 0; q < 4; ++q) { const int j = 8 * kb + 2 * q; const f32x4 l = *(const LAS f32x4*)(Ls + pr * 136 + j * 2);
;                       s0 -= (f32x2){l[0], l[1]} * (f32x2){xs[j], xs[j]}; s1 -= (f32x2){l[2], l[3]} * (f32x2){xs[j + 1], xs[j + 1]}; }
;                   const f32x2 s = s0 + s1; xs[2 * pr] = s[0]; xs[2 * pr + 1] = s[1]; }
	v_pk_fma_f32 v[54:55], v[30:31], v[132:133], v[54:55] op_sel_hi:[0,1,1] neg_lo:[1,0,0] neg_hi:[1,0,0]
	v_pk_fma_f32 v[170:171], v[32:33], v[134:135], 0 op_sel_hi:[0,1,0] neg_lo:[1,0,0] neg_hi:[1,0,0]
	ds_read_b128 v[132:135], v69 offset:51888
	s_waitcnt lgkmcnt(8)
	v_pk_fma_f32 v[54:55], v[36:37], v[136:137], v[54:55] op_sel_hi:[0,1,1] neg_lo:[1,0,0] neg_hi:[1,0,0]
	v_pk_fma_f32 v[170:171], v[34:35], v[138:139], v[170:171] op_sel_hi:[0,1,1] neg_lo:[1,0,0] neg_hi:[1,0,0]
	ds_read_b128 v[136:139], v69 offset:51904
	s_waitcnt lgkmcnt(8)
	v_pk_fma_f32 v[54:55], v[42:43], v[124:125], v[54:55] op_sel_hi:[0,1,1] neg_lo:[1,0,0] neg_hi:[1,0,0]
	v_pk_fma_f32 v[170:171], v[38:39], v[126:127], v[170:171] op_sel_hi:[0,1,1] neg_lo:[1,0,0] neg_hi:[1,0,0]
	ds_read_b128 v[124:127], v69 offset:51920
	s_waitcnt lgkmcnt(8)
	v_pk_fma_f32 v[50:51], v[44:45], v[120:121], v[54:55] op_sel_hi:[0,1,1] neg_lo:[1,0,0] neg_hi:[1,0,0]
	v_pk_fma_f32 v[52:53], v[40:41], v[122:123], v[170:171] op_sel_hi:[0,1,1] neg_lo:[1,0,0] neg_hi:[1,0,0]
	v_add_u32_e32 v141, 0xaa00, v69
	ds_read2_b32 v[120:121], v141 offset0:65 offset1:205
	v_pk_add_f32 v[198:199], v[50:51], v[52:53]
	s_waitcnt lgkmcnt(8)
	v_pk_fma_f32 v[54:55], v[30:31], v[238:239], v[192:193] op_sel_hi:[0,1,1] neg_lo:[1,0,0] neg_hi:[1,0,0]
	v_pk_fma_f32 v[170:171], v[32:33], v[240:241], 0 op_sel_hi:[0,1,0] neg_lo:[1,0,0] neg_hi:[1,0,0]
	ds_read_b128 v[238:241], v69 offset:44320
	s_waitcnt lgkmcnt(8)
	v_pk_fma_f32 v[54:55], v[36:37], v[128:129], v[54:55] op_sel_hi:[0,1,1] neg_lo:[1,0,0] neg_hi:[1,0,0]
	v_pk_fma_f32 v[170:171], v[34:35], v[130:131], v[170:171] op_sel_hi:[0,1,1] neg_lo:[1,0,0] neg_hi:[1,0,0]
	ds_read_b128 v[128:131], v69 offset:44864
	s_waitcnt lgkmcnt(8)
	v_pk_fma_f32 v[54:55], v[42:43], v[242:243], v[54:55] op_sel_hi:[0,1,1] neg_lo:[1,0,0] neg_hi:[1,0,0]
	v_pk_fma_f32 v[170:171], v[38:39], v[244:245], v[170:171] op_sel_hi:[0,1,1] neg_lo:[1,0,0] neg_hi:[1,0,0]
	ds_read_b128 v[242:245], v69 offset:45408
	s_waitcnt lgkmcnt(8)
	v_pk_fma_f32 v[50:51], v[44:45], v[116:117], v[54:55] op_sel_hi:[0,1,1] neg_lo:[1,0,0] neg_hi:[1,0,0]
	v_pk_fma_f32 v[52:53], v[40:41], v[118:119], v[170:171] op_sel_hi:[0,1,1] neg_lo:[1,0,0] neg_hi:[1,0,0]
	ds_read_b128 v[116:119], v69 offset:44880
	v_pk_add_f32 v[192:193], v[50:51], v[52:53]
	s_waitcnt lgkmcnt(8)
	v_pk_fma_f32 v[54:55], v[30:31], v[112:113], v[194:195] op_sel_hi:[0,1,1] neg_lo:[1,0,0] neg_hi:[1,0,0]
	v_pk_fma_f32 v[170:171], v[32:33], v[114:115], 0 op_sel_hi:[0,1,0] neg_lo:[1,0,0] neg_hi:[1,0,0]
	ds_read_b128 v[112:115], v69 offset:45424
	s_waitcnt lgkmcnt(8)
	v_pk_fma_f32 v[54:55], v[36:37], v[132:133], v[54:55] op_sel_hi:[0,1,1] neg_lo:[1,0,0] neg_hi:[1,0,0]
	v_pk_fma_f32 v[170:171], v[34:35], v[134:135], v[170:171] op_sel_hi:[0,1,1] neg_lo:[1,0,0] neg_hi:[1,0,0]
	v_add_u32_e32 v183, 0xae00, v69
	ds_read2_b32 v[132:133], v183 offset0:89 offset1:229
	s_waitcnt lgkmcnt(8)
	v_pk_fma_f32 v[54:55], v[42:43], v[136:137], v[54:55] op_sel_hi:[0,1,1] neg_lo:[1,0,0] neg_hi:[1,0,0]
	v_pk_fma_f32 v[170:171], v[38:39], v[138:139], v[170:171] op_sel_hi:[0,1,1] neg_lo:[1,0,0] neg_hi:[1,0,0]
	ds_read_b128 v[136:139], v69 offset:45440
	s_waitcnt lgkmcnt(8)
	v_pk_fma_f32 v[50:51], v[44:45], v[124:125], v[54:55] op_sel_hi:[0,1,1] neg_lo:[1,0,0] neg_hi:[1,0,0]
	v_pk_fma_f32 v[52:53], v[40:41], v[126:127], v[170:171] op_sel_hi:[0,1,1] neg_lo:[1,0,0] neg_hi:[1,0,0]
	ds_read_b128 v[124:127], v69 offset:45952
	v_pk_add_f32 v[194:195], v[50:51], v[52:53]
	s_waitcnt lgkmcnt(8)
	v_fma_f32 v50, -v46, v120, v47
	s_waitcnt lgkmcnt(7)
	v_pk_fma_f32 v[52:53], v[46:47], v[238:239], v[164:165] op_sel_hi:[0,1,1] neg_lo:[1,0,0] neg_hi:[1,0,0]
	s_waitcnt lgkmcnt(6)
	v_pk_fma_f32 v[164:165], v[46:47], v[128:129], v[168:169] op_sel_hi:[0,1,1] neg_lo:[1,0,0] neg_hi:[1,0,0]
	v_pk_fma_f32 v[164:165], v[130:131], v[50:51], v[164:165] op_sel_hi:[1,0,1] neg_lo:[1,0,0] neg_hi:[1,0,0]
	ds_read_b128 v[128:131], v69 offset:45968
	v_pk_fma_f32 v[54:55], v[240:241], v[50:51], v[52:53] op_sel_hi:[1,0,1] neg_lo:[1,0,0] neg_hi:[1,0,0]
	ds_read_b128 v[238:241], v69 offset:45984
	s_waitcnt lgkmcnt(7)
	v_pk_fma_f32 v[166:167], v[46:47], v[242:243], v[166:167] op_sel_hi:[0,1,1] neg_lo:[1,0,0] neg_hi:[1,0,0]
	v_pk_fma_f32 v[166:167], v[50:51], v[244:245], v[166:167] op_sel_hi:[0,1,1] neg_lo:[1,0,0] neg_hi:[1,0,0]
	ds_read_b128 v[242:245], v69 offset:46000
	v_fma_f32 v52, -v121, v54, v55
	ds_read_b128 v[120:123], v69 offset:46496
	s_waitcnt lgkmcnt(8)
	v_pk_fma_f32 v[164:165], v[116:117], v[54:55], v[164:165] op_sel_hi:[1,0,1] neg_lo:[1,0,0] neg_hi:[1,0,0]
	s_waitcnt lgkmcnt(7)
	v_pk_fma_f32 v[166:167], v[54:55], v[112:113], v[166:167] op_sel_hi:[0,1,1] neg_lo:[1,0,0] neg_hi:[1,0,0]
	v_pk_fma_f32 v[168:169], v[118:119], v[52:53], v[164:165] op_sel_hi:[1,0,1] neg_lo:[1,0,0] neg_hi:[1,0,0]
	ds_read_b128 v[116:119], v69 offset:46512
	v_pk_fma_f32 v[166:167], v[114:115], v[52:53], v[166:167] op_sel_hi:[1,0,1] neg_lo:[1,0,0] neg_hi:[1,0,0]
	ds_read_b128 v[112:115], v69 offset:46528
	s_waitcnt lgkmcnt(8)
	v_fma_f32 v164, -v132, v168, v169
	s_waitcnt lgkmcnt(7)
	v_pk_fma_f32 v[166:167], v[136:137], v[168:169], v[166:167] op_sel_hi:[1,0,1] neg_lo:[1,0,0] neg_hi:[1,0,0]
	s_nop 0
	v_pk_fma_f32 v[170:171], v[138:139], v[164:165], v[166:167] op_sel_hi:[1,0,1] neg_lo:[1,0,0] neg_hi:[1,0,0]
	ds_read_b128 v[136:139], v69 offset:46544
	v_fma_f32 v166, -v133, v170, v171
	ds_read_b128 v[132:135], v69 offset:47040
	s_waitcnt lgkmcnt(8)
	v_pk_fma_f32 v[172:173], v[46:47], v[124:125], v[172:173] op_sel_hi:[0,1,1] neg_lo:[1,0,0] neg_hi:[1,0,0]
	v_pk_fma_f32 v[204:205], v[50:51], v[126:127], 0 op_sel_hi:[0,1,0] neg_lo:[1,0,0] neg_hi:[1,0,0]
	ds_read_b128 v[124:127], v69 offset:47056
	s_waitcnt lgkmcnt(8)
; #define LAS __attribute__((address_space(3)))
; DI void gdn_prep_phase(const int tid, LAS unsigned char* lds, const P& p, int G, int c) {
;     ...
;               for (int pr = 4 * kb + 4; pr < 32; ++pr) {
;                   f32x2 s0 = (f32x2){xs[2 * pr], xs[2 * pr + 1]}, s1 = (f32x2){0.f, 0.f};
; #pragma unroll
;                   for (int q = 0; q < 4; ++q) { const int j = 8 * kb + 2 * q; const f32x4 l = *(const LAS f32x4*)(Ls + pr * 136 + j * 2);
;                       s0 -= (f32x2){l[0], l[1]} * (f32x2){xs[j], xs[j]}; s1 -= (f32x2){l[2], l[3]} * (f32x2){xs[j + 1], xs[j + 1]}; }
;                   const f32x2 s = s0 + s1; xs[2 * pr] = s[0]; xs[2 * pr + 1] = s[1]; }
	v_pk_fma_f32 v[172:173], v[54:55], v[128:129], v[172:173] op_sel_hi:[0,1,1] neg_lo:[1,0,0] neg_hi:[1,0,0]
	v_pk_fma_f32 v[204:205], v[52:53], v[130:131], v[204:205] op_sel_hi:[0,1,1] neg_lo:[1,0,0] neg_hi:[1,0,0]
	ds_read_b128 v[128:131], v69 offset:47072
	s_waitcnt lgkmcnt(8)
	v_pk_fma_f32 v[172:173], v[238:239], v[168:169], v[172:173] op_sel_hi:[1,0,1] neg_lo:[1,0,0] neg_hi:[1,0,0]
	v_pk_fma_f32 v[204:205], v[240:241], v[164:165], v[204:205] op_sel_hi:[1,0,1] neg_lo:[1,0,0] neg_hi:[1,0,0]
	ds_read_b128 v[238:241], v69 offset:47088
	s_waitcnt lgkmcnt(8)
	v_pk_fma_f32 v[172:173], v[242:243], v[170:171], v[172:173] op_sel_hi:[1,0,1] neg_lo:[1,0,0] neg_hi:[1,0,0]
	v_pk_fma_f32 v[200:201], v[244:245], v[166:167], v[204:205] op_sel_hi:[1,0,1] neg_lo:[1,0,0] neg_hi:[1,0,0]
	ds_read_b128 v[242:245], v69 offset:47584
	v_pk_add_f32 v[172:173], v[172:173], v[200:201]
	s_waitcnt lgkmcnt(8)
	v_pk_fma_f32 v[174:175], v[46:47], v[120:121], v[174:175] op_sel_hi:[0,1,1] neg_lo:[1,0,0] neg_hi:[1,0,0]
	v_pk_fma_f32 v[204:205], v[50:51], v[122:123], 0 op_sel_hi:[0,1,0] neg_lo:[1,0,0] neg_hi:[1,0,0]
	ds_read_b128 v[120:123], v69 offset:47600
	s_waitcnt lgkmcnt(8)
	v_pk_fma_f32 v[174:175], v[54:55], v[116:117], v[174:175] op_sel_hi:[0,1,1] neg_lo:[1,0,0] neg_hi:[1,0,0]
	v_pk_fma_f32 v[204:205], v[52:53], v[118:119], v[204:205] op_sel_hi:[0,1,1] neg_lo:[1,0,0] neg_hi:[1,0,0]
	ds_read_b128 v[116:119], v69 offset:47616
	s_waitcnt lgkmcnt(8)
	v_pk_fma_f32 v[174:175], v[168:169], v[112:113], v[174:175] op_sel_hi:[0,1,1] neg_lo:[1,0,0] neg_hi:[1,0,0]
	v_pk_fma_f32 v[204:205], v[114:115], v[164:165], v[204:205] op_sel_hi:[1,0,1] neg_lo:[1,0,0] neg_hi:[1,0,0]
	ds_read_b128 v[112:115], v69 offset:47632
	s_waitcnt lgkmcnt(8)
	v_pk_fma_f32 v[174:175], v[136:137], v[170:171], v[174:175] op_sel_hi:[1,0,1] neg_lo:[1,0,0] neg_hi:[1,0,0]
	v_pk_fma_f32 v[200:201], v[138:139], v[166:167], v[204:205] op_sel_hi:[1,0,1] neg_lo:[1,0,0] neg_hi:[1,0,0]
	ds_read_b128 v[136:139], v69 offset:48128
	v_pk_add_f32 v[206:207], v[174:175], v[200:201]
	s_waitcnt lgkmcnt(8)
	v_pk_fma_f32 v[174:175], v[46:47], v[132:133], v[188:189] op_sel_hi:[0,1,1] neg_lo:[1,0,0] neg_hi:[1,0,0]
	v_pk_fma_f32 v[188:189], v[50:51], v[134:135], 0 op_sel_hi:[0,1,0] neg_lo:[1,0,0] neg_hi:[1,0,0]
	ds_read_b128 v[132:135], v69 offset:48144
	s_waitcnt lgkmcnt(8)
	v_pk_fma_f32 v[174:175], v[54:55], v[124:125], v[174:175] op_sel_hi:[0,1,1] neg_lo:[1,0,0] neg_hi:[1,0,0]
	v_pk_fma_f32 v[188:189], v[52:53], v[126:127], v[188:189] op_sel_hi:[0,1,1] neg_lo:[1,0,0] neg_hi:[1,0,0]
	ds_read_b128 v[124:127], v69 offset:48160
	s_waitcnt lgkmcnt(8)
	v_pk_fma_f32 v[174:175], v[168:169], v[128:129], v[174:175] op_sel_hi:[0,1,1] neg_lo:[1,0,0] neg_hi:[1,0,0]
	v_pk_fma_f32 v[188:189], v[164:165], v[130:131], v[188:189] op_sel_hi:[0,1,1] neg_lo:[1,0,0] neg_hi:[1,0,0]
	ds_read_b128 v[128:131], v69 offset:48176
	s_waitcnt lgkmcnt(8)
	v_pk_fma_f32 v[174:175], v[170:171], v[238:239], v[174:175] op_sel_hi:[0,1,1] neg_lo:[1,0,0] neg_hi:[1,0,0]
	v_pk_fma_f32 v[188:189], v[240:241], v[166:167], v[188:189] op_sel_hi:[1,0,1] neg_lo:[1,0,0] neg_hi:[1,0,0]
	ds_read_b128 v[238:241], v69 offset:48672
	v_pk_add_f32 v[208:209], v[174:175], v[188:189]
	s_waitcnt lgkmcnt(8)
	v_pk_fma_f32 v[174:175], v[46:47], v[242:243], v[190:191] op_sel_hi:[0,1,1] neg_lo:[1,0,0] neg_hi:[1,0,0]
	v_pk_fma_f32 v[200:201], v[50:51], v[244:245], 0 op_sel_hi:[0,1,0] neg_lo:[1,0,0] neg_hi:[1,0,0]
	ds_read_b128 v[242:245], v69 offset:48688
	s_waitcnt lgkmcnt(8)
	v_pk_fma_f32 v[174:175], v[54:55], v[120:121], v[174:175] op_sel_hi:[0,1,1] neg_lo:[1,0,0] neg_hi:[1,0,0]
	v_pk_fma_f32 v[200:201], v[52:53], v[122:123], v[200:201] op_sel_hi:[0,1,1] neg_lo:[1,0,0] neg_hi:[1,0,0]
	ds_read_b128 v[120:123], v69 offset:48704
	s_waitcnt lgkmcnt(8)
	v_pk_fma_f32 v[174:175], v[168:169], v[116:117], v[174:175] op_sel_hi:[0,1,1] neg_lo:[1,0,0] neg_hi:[1,0,0]
	v_pk_fma_f32 v[200:201], v[164:165], v[118:119], v[200:201] op_sel_hi:[0,1,1] neg_lo:[1,0,0] neg_hi:[1,0,0]
	ds_read_b128 v[116:119], v69 offset:48720
	s_waitcnt lgkmcnt(8)
	v_pk_fma_f32 v[174:175], v[170:171], v[112:113], v[174:175] op_sel_hi:[0,1,1] neg_lo:[1,0,0] neg_hi:[1,0,0]
	v_pk_fma_f32 v[188:189], v[166:167], v[114:115], v[200:201] op_sel_hi:[0,1,1] neg_lo:[1,0,0] neg_hi:[1,0,0]
	ds_read_b128 v[112:115], v69 offset:49216
	v_pk_add_f32 v[188:189], v[174:175], v[188:189]
	s_waitcnt lgkmcnt(8)
	v_pk_fma_f32 v[190:191], v[46:47], v[136:137], v[176:177] op_sel_hi:[0,1,1] neg_lo:[1,0,0] neg_hi:[1,0,0]
	v_pk_fma_f32 v[200:201], v[50:51], v[138:139], 0 op_sel_hi:[0,1,0] neg_lo:[1,0,0] neg_hi:[1,0,0]
	ds_read_b128 v[136:139], v69 offset:49232
	s_waitcnt lgkmcnt(8)
	v_pk_fma_f32 v[190:191], v[54:55], v[132:133], v[190:191] op_sel_hi:[0,1,1] neg_lo:[1,0,0] neg_hi:[1,0,0]
	v_pk_fma_f32 v[200:201], v[52:53], v[134:135], v[200:201] op_sel_hi:[0,1,1] neg_lo:[1,0,0] neg_hi:[1,0,0]
	ds_read_b128 v[132:135], v69 offset:49248
	s_waitcnt lgkmcnt(8)
	v_pk_fma_f32 v[190:191], v[168:169], v[124:125], v[190:191] op_sel_hi:[0,1,1] neg_lo:[1,0,0] neg_hi:[1,0,0]
	v_pk_fma_f32 v[200:201], v[164:165], v[126:127], v[200:201] op_sel_hi:[0,1,1] neg_lo:[1,0,0] neg_hi:[1,0,0]
	ds_read_b128 v[124:127], v69 offset:49264
	s_waitcnt lgkmcnt(8)
	v_pk_fma_f32 v[174:175], v[170:171], v[128:129], v[190:191] op_sel_hi:[0,1,1] neg_lo:[1,0,0] neg_hi:[1,0,0]
	v_pk_fma_f32 v[176:177], v[166:167], v[130:131], v[200:201] op_sel_hi:[0,1,1] neg_lo:[1,0,0] neg_hi:[1,0,0]
	ds_read_b128 v[128:131], v69 offset:49760
	v_pk_add_f32 v[190:191], v[174:175], v[176:177]
	s_waitcnt lgkmcnt(8)
; #define LAS __attribute__((address_space(3)))
; DI void gdn_prep_phase(const int tid, LAS unsigned char* lds, const P& p, int G, int c) {
;     ...
;               for (int pr = 4 * kb + 4; pr < 32; ++pr) {
;                   f32x2 s0 = (f32x2){xs[2 * pr], xs[2 * pr + 1]}, s1 = (f32x2){0.f, 0.f};
; #pragma unroll
;                   for (int q = 0; q < 4; ++q) { const int j = 8 * kb + 2 * q; const f32x4 l = *(const LAS f32x4*)(Ls + pr * 136 + j * 2);
;                       s0 -= (f32x2){l[0], l[1]} * (f32x2){xs[j], xs[j]}; s1 -= (f32x2){l[2], l[3]} * (f32x2){xs[j + 1], xs[j + 1]}; }
;                   const f32x2 s = s0 + s1; xs[2 * pr] = s[0]; xs[2 * pr + 1] = s[1]; }
	v_pk_fma_f32 v[178:179], v[46:47], v[238:239], v[178:179] op_sel_hi:[0,1,1] neg_lo:[1,0,0] neg_hi:[1,0,0]
	v_pk_fma_f32 v[200:201], v[50:51], v[240:241], 0 op_sel_hi:[0,1,0] neg_lo:[1,0,0] neg_hi:[1,0,0]
	ds_read_b128 v[238:241], v69 offset:49776
	s_waitcnt lgkmcnt(8)
	v_pk_fma_f32 v[178:179], v[54:55], v[242:243], v[178:179] op_sel_hi:[0,1,1] neg_lo:[1,0,0] neg_hi:[1,0,0]
	v_pk_fma_f32 v[200:201], v[52:53], v[244:245], v[200:201] op_sel_hi:[0,1,1] neg_lo:[1,0,0] neg_hi:[1,0,0]
	ds_read_b128 v[242:245], v69 offset:49792
	s_waitcnt lgkmcnt(8)
	v_pk_fma_f32 v[178:179], v[168:169], v[120:121], v[178:179] op_sel_hi:[0,1,1] neg_lo:[1,0,0] neg_hi:[1,0,0]
	v_pk_fma_f32 v[200:201], v[164:165], v[122:123], v[200:201] op_sel_hi:[0,1,1] neg_lo:[1,0,0] neg_hi:[1,0,0]
	ds_read_b128 v[120:123], v69 offset:49808
	s_waitcnt lgkmcnt(8)
	v_pk_fma_f32 v[174:175], v[170:171], v[116:117], v[178:179] op_sel_hi:[0,1,1] neg_lo:[1,0,0] neg_hi:[1,0,0]
	v_pk_fma_f32 v[176:177], v[166:167], v[118:119], v[200:201] op_sel_hi:[0,1,1] neg_lo:[1,0,0] neg_hi:[1,0,0]
	ds_read_b128 v[116:119], v69 offset:50304
	v_pk_add_f32 v[200:201], v[174:175], v[176:177]
	s_waitcnt lgkmcnt(8)
	v_pk_fma_f32 v[178:179], v[46:47], v[112:113], v[184:185] op_sel_hi:[0,1,1] neg_lo:[1,0,0] neg_hi:[1,0,0]
	v_pk_fma_f32 v[184:185], v[50:51], v[114:115], 0 op_sel_hi:[0,1,0] neg_lo:[1,0,0] neg_hi:[1,0,0]
	ds_read_b128 v[112:115], v69 offset:50320
	s_waitcnt lgkmcnt(8)
	v_pk_fma_f32 v[178:179], v[54:55], v[136:137], v[178:179] op_sel_hi:[0,1,1] neg_lo:[1,0,0] neg_hi:[1,0,0]
	v_pk_fma_f32 v[184:185], v[52:53], v[138:139], v[184:185] op_sel_hi:[0,1,1] neg_lo:[1,0,0] neg_hi:[1,0,0]
	ds_read_b128 v[136:139], v69 offset:50336
	s_waitcnt lgkmcnt(8)
	v_pk_fma_f32 v[178:179], v[168:169], v[132:133], v[178:179] op_sel_hi:[0,1,1] neg_lo:[1,0,0] neg_hi:[1,0,0]
	v_pk_fma_f32 v[184:185], v[164:165], v[134:135], v[184:185] op_sel_hi:[0,1,1] neg_lo:[1,0,0] neg_hi:[1,0,0]
	ds_read_b128 v[132:135], v69 offset:50352
	s_waitcnt lgkmcnt(8)
	v_pk_fma_f32 v[174:175], v[170:171], v[124:125], v[178:179] op_sel_hi:[0,1,1] neg_lo:[1,0,0] neg_hi:[1,0,0]
	v_pk_fma_f32 v[176:177], v[166:167], v[126:127], v[184:185] op_sel_hi:[0,1,1] neg_lo:[1,0,0] neg_hi:[1,0,0]
	ds_read_b128 v[124:127], v69 offset:50848
	v_pk_add_f32 v[202:203], v[174:175], v[176:177]
	s_waitcnt lgkmcnt(8)
	v_pk_fma_f32 v[178:179], v[46:47], v[128:129], v[186:187] op_sel_hi:[0,1,1] neg_lo:[1,0,0] neg_hi:[1,0,0]
	v_pk_fma_f32 v[184:185], v[50:51], v[130:131], 0 op_sel_hi:[0,1,0] neg_lo:[1,0,0] neg_hi:[1,0,0]
	ds_read_b128 v[128:131], v69 offset:50864
	s_waitcnt lgkmcnt(8)
	v_pk_fma_f32 v[178:179], v[54:55], v[238:239], v[178:179] op_sel_hi:[0,1,1] neg_lo:[1,0,0] neg_hi:[1,0,0]
	v_pk_fma_f32 v[184:185], v[52:53], v[240:241], v[184:185] op_sel_hi:[0,1,1] neg_lo:[1,0,0] neg_hi:[1,0,0]
	ds_read_b128 v[238:241], v69 offset:50880
	s_waitcnt lgkmcnt(8)
	v_pk_fma_f32 v[178:179], v[168:169], v[242:243], v[178:179] op_sel_hi:[0,1,1] neg_lo:[1,0,0] neg_hi:[1,0,0]
	v_pk_fma_f32 v[184:185], v[164:165], v[244:245], v[184:185] op_sel_hi:[0,1,1] neg_lo:[1,0,0] neg_hi:[1,0,0]
	ds_read_b128 v[242:245], v69 offset:50896
	s_waitcnt lgkmcnt(8)
	v_pk_fma_f32 v[174:175], v[170:171], v[120:121], v[178:179] op_sel_hi:[0,1,1] neg_lo:[1,0,0] neg_hi:[1,0,0]
	v_pk_fma_f32 v[176:177], v[166:167], v[122:123], v[184:185] op_sel_hi:[0,1,1] neg_lo:[1,0,0] neg_hi:[1,0,0]
	ds_read_b128 v[120:123], v69 offset:51392
	v_pk_add_f32 v[204:205], v[174:175], v[176:177]
	s_waitcnt lgkmcnt(8)
	v_pk_fma_f32 v[178:179], v[46:47], v[116:117], v[196:197] op_sel_hi:[0,1,1] neg_lo:[1,0,0] neg_hi:[1,0,0]
	v_pk_fma_f32 v[184:185], v[50:51], v[118:119], 0 op_sel_hi:[0,1,0] neg_lo:[1,0,0] neg_hi:[1,0,0]
	ds_read_b128 v[116:119], v69 offset:51408
	s_waitcnt lgkmcnt(8)
	v_pk_fma_f32 v[178:179], v[54:55], v[112:113], v[178:179] op_sel_hi:[0,1,1] neg_lo:[1,0,0] neg_hi:[1,0,0]
	v_pk_fma_f32 v[184:185], v[52:53], v[114:115], v[184:185] op_sel_hi:[0,1,1] neg_lo:[1,0,0] neg_hi:[1,0,0]
	ds_read_b128 v[112:115], v69 offset:51424
	s_waitcnt lgkmcnt(8)
	v_pk_fma_f32 v[178:179], v[168:169], v[136:137], v[178:179] op_sel_hi:[0,1,1] neg_lo:[1,0,0] neg_hi:[1,0,0]
	v_pk_fma_f32 v[184:185], v[164:165], v[138:139], v[184:185] op_sel_hi:[0,1,1] neg_lo:[1,0,0] neg_hi:[1,0,0]
	ds_read_b128 v[136:139], v69 offset:51440
	s_waitcnt lgkmcnt(8)
	v_pk_fma_f32 v[174:175], v[170:171], v[132:133], v[178:179] op_sel_hi:[0,1,1] neg_lo:[1,0,0] neg_hi:[1,0,0]
	v_pk_fma_f32 v[176:177], v[166:167], v[134:135], v[184:185] op_sel_hi:[0,1,1] neg_lo:[1,0,0] neg_hi:[1,0,0]
	ds_read_b128 v[132:135], v69 offset:51936
	v_pk_add_f32 v[196:197], v[174:175], v[176:177]
	s_waitcnt lgkmcnt(8)
	v_pk_fma_f32 v[178:179], v[46:47], v[124:125], v[198:199] op_sel_hi:[0,1,1] neg_lo:[1,0,0] neg_hi:[1,0,0]
	v_pk_fma_f32 v[184:185], v[50:51], v[126:127], 0 op_sel_hi:[0,1,0] neg_lo:[1,0,0] neg_hi:[1,0,0]
	ds_read_b128 v[124:127], v69 offset:51952
	s_waitcnt lgkmcnt(8)
	v_pk_fma_f32 v[178:179], v[54:55], v[128:129], v[178:179] op_sel_hi:[0,1,1] neg_lo:[1,0,0] neg_hi:[1,0,0]
	v_pk_fma_f32 v[184:185], v[52:53], v[130:131], v[184:185] op_sel_hi:[0,1,1] neg_lo:[1,0,0] neg_hi:[1,0,0]
	ds_read_b128 v[128:131], v69 offset:51968
	s_waitcnt lgkmcnt(8)
	v_pk_fma_f32 v[178:179], v[168:169], v[238:239], v[178:179] op_sel_hi:[0,1,1] neg_lo:[1,0,0] neg_hi:[1,0,0]
	v_pk_fma_f32 v[184:185], v[164:165], v[240:241], v[184:185] op_sel_hi:[0,1,1] neg_lo:[1,0,0] neg_hi:[1,0,0]
	ds_read_b128 v[238:241], v69 offset:51984
	s_waitcnt lgkmcnt(8)
; #define LAS __attribute__((address_space(3)))
; DI void gdn_prep_phase(const int tid, LAS unsigned char* lds, const P& p, int G, int c) {
;     ...
; #pragma unroll
;           for (int kb = 0; kb < 8; ++kb) {
; #pragma unroll
;               for (int pp = 0; pp < 4; ++pp) { const int pr = 4 * kb + pp;
;                   f32x2 s = (f32x2){xs[2 * pr], xs[2 * pr + 1]};
; #pragma unroll
;                   for (int j = 8 * kb; j < 2 * pr; j += 2) { const f32x4 l = *(const LAS f32x4*)(Ls + pr * 136 + j * 2);
;                       s -= (f32x2){l[0], l[1]} * (f32x2){xs[j], xs[j]}; s -= (f32x2){l[2], l[3]} * (f32x2){xs[j + 1], xs[j + 1]}; }
;                   xs[2 * pr] = s[0];
;                   xs[2 * pr + 1] = s[1] - Ls[pr * 136 + 4 * pr + 1] * s[0]; }
; #pragma unroll
;               for (int pr = 4 * kb + 4; pr < 32; ++pr) {
;                   f32x2 s0 = (f32x2){xs[2 * pr], xs[2 * pr + 1]}, s1 = (f32x2){0.f, 0.f};
; #pragma unroll
;                   for (int q = 0; q < 4; ++q) { const int j = 8 * kb + 2 * q; const f32x4 l = *(const LAS f32x4*)(Ls + pr * 136 + j * 2);
;                       s0 -= (f32x2){l[0], l[1]} * (f32x2){xs[j], xs[j]}; s1 -= (f32x2){l[2], l[3]} * (f32x2){xs[j + 1], xs[j + 1]}; }
;                   const f32x2 s = s0 + s1; xs[2 * pr] = s[0]; xs[2 * pr + 1] = s[1]; }
	v_pk_fma_f32 v[174:175], v[170:171], v[242:243], v[178:179] op_sel_hi:[0,1,1] neg_lo:[1,0,0] neg_hi:[1,0,0]
	v_pk_fma_f32 v[176:177], v[166:167], v[244:245], v[184:185] op_sel_hi:[0,1,1] neg_lo:[1,0,0] neg_hi:[1,0,0]
	v_add_u32_e32 v141, 0xb200, v69
	ds_read2_b32 v[242:243], v141 offset0:113 offset1:253
	v_pk_add_f32 v[198:199], v[174:175], v[176:177]
	s_waitcnt lgkmcnt(8)
	v_pk_fma_f32 v[178:179], v[46:47], v[120:121], v[192:193] op_sel_hi:[0,1,1] neg_lo:[1,0,0] neg_hi:[1,0,0]
	v_pk_fma_f32 v[184:185], v[50:51], v[122:123], 0 op_sel_hi:[0,1,0] neg_lo:[1,0,0] neg_hi:[1,0,0]
	ds_read_b128 v[120:123], v69 offset:46560
	s_waitcnt lgkmcnt(8)
	v_pk_fma_f32 v[178:179], v[54:55], v[116:117], v[178:179] op_sel_hi:[0,1,1] neg_lo:[1,0,0] neg_hi:[1,0,0]
	v_pk_fma_f32 v[184:185], v[52:53], v[118:119], v[184:185] op_sel_hi:[0,1,1] neg_lo:[1,0,0] neg_hi:[1,0,0]
	ds_read_b128 v[116:119], v69 offset:47104
	s_waitcnt lgkmcnt(8)
	v_pk_fma_f32 v[178:179], v[168:169], v[112:113], v[178:179] op_sel_hi:[0,1,1] neg_lo:[1,0,0] neg_hi:[1,0,0]
	v_pk_fma_f32 v[184:185], v[164:165], v[114:115], v[184:185] op_sel_hi:[0,1,1] neg_lo:[1,0,0] neg_hi:[1,0,0]
	ds_read_b128 v[112:115], v69 offset:47120
	s_waitcnt lgkmcnt(8)
	v_pk_fma_f32 v[174:175], v[170:171], v[136:137], v[178:179] op_sel_hi:[0,1,1] neg_lo:[1,0,0] neg_hi:[1,0,0]
	v_pk_fma_f32 v[176:177], v[166:167], v[138:139], v[184:185] op_sel_hi:[0,1,1] neg_lo:[1,0,0] neg_hi:[1,0,0]
	ds_read_b128 v[136:139], v69 offset:47648
	v_pk_add_f32 v[192:193], v[174:175], v[176:177]
	s_waitcnt lgkmcnt(8)
	v_pk_fma_f32 v[178:179], v[46:47], v[132:133], v[194:195] op_sel_hi:[0,1,1] neg_lo:[1,0,0] neg_hi:[1,0,0]
	v_pk_fma_f32 v[184:185], v[50:51], v[134:135], 0 op_sel_hi:[0,1,0] neg_lo:[1,0,0] neg_hi:[1,0,0]
	v_add_u32_e32 v183, 0xb800, v69
	ds_read2_b32 v[132:133], v183 offset0:9 offset1:149
	s_waitcnt lgkmcnt(8)
	v_pk_fma_f32 v[178:179], v[54:55], v[124:125], v[178:179] op_sel_hi:[0,1,1] neg_lo:[1,0,0] neg_hi:[1,0,0]
	v_pk_fma_f32 v[184:185], v[52:53], v[126:127], v[184:185] op_sel_hi:[0,1,1] neg_lo:[1,0,0] neg_hi:[1,0,0]
	ds_read_b128 v[124:127], v69 offset:47664
	s_waitcnt lgkmcnt(8)
	v_pk_fma_f32 v[178:179], v[168:169], v[128:129], v[178:179] op_sel_hi:[0,1,1] neg_lo:[1,0,0] neg_hi:[1,0,0]
	v_pk_fma_f32 v[184:185], v[164:165], v[130:131], v[184:185] op_sel_hi:[0,1,1] neg_lo:[1,0,0] neg_hi:[1,0,0]
	ds_read_b128 v[128:131], v69 offset:47680
	s_waitcnt lgkmcnt(8)
	v_pk_fma_f32 v[174:175], v[170:171], v[238:239], v[178:179] op_sel_hi:[0,1,1] neg_lo:[1,0,0] neg_hi:[1,0,0]
	v_pk_fma_f32 v[176:177], v[166:167], v[240:241], v[184:185] op_sel_hi:[0,1,1] neg_lo:[1,0,0] neg_hi:[1,0,0]
	ds_read_b128 v[238:241], v69 offset:48192
	v_pk_add_f32 v[194:195], v[174:175], v[176:177]
	s_waitcnt lgkmcnt(8)
	v_fma_f32 v174, -v172, v242, v173
	s_waitcnt lgkmcnt(7)
	v_pk_fma_f32 v[176:177], v[172:173], v[120:121], v[206:207] op_sel_hi:[0,1,1] neg_lo:[1,0,0] neg_hi:[1,0,0]
	s_waitcnt lgkmcnt(6)
	v_pk_fma_f32 v[184:185], v[172:173], v[116:117], v[208:209] op_sel_hi:[0,1,1] neg_lo:[1,0,0] neg_hi:[1,0,0]
	v_pk_fma_f32 v[206:207], v[118:119], v[174:175], v[184:185] op_sel_hi:[1,0,1] neg_lo:[1,0,0] neg_hi:[1,0,0]
	ds_read_b128 v[116:119], v69 offset:48208
	v_pk_fma_f32 v[178:179], v[122:123], v[174:175], v[176:177] op_sel_hi:[1,0,1] neg_lo:[1,0,0] neg_hi:[1,0,0]
	ds_read_b128 v[120:123], v69 offset:48224
	v_fma_f32 v176, -v243, v178, v179
	ds_read_b128 v[242:245], v69 offset:48240
	s_waitcnt lgkmcnt(8)
	v_pk_fma_f32 v[184:185], v[112:113], v[178:179], v[206:207] op_sel_hi:[1,0,1] neg_lo:[1,0,0] neg_hi:[1,0,0]
	s_nop 0
	v_pk_fma_f32 v[186:187], v[114:115], v[176:177], v[184:185] op_sel_hi:[1,0,1] neg_lo:[1,0,0] neg_hi:[1,0,0]
	ds_read_b128 v[112:115], v69 offset:48736
	s_waitcnt lgkmcnt(8)
	v_pk_fma_f32 v[188:189], v[172:173], v[136:137], v[188:189] op_sel_hi:[0,1,1] neg_lo:[1,0,0] neg_hi:[1,0,0]
	v_pk_fma_f32 v[188:189], v[174:175], v[138:139], v[188:189] op_sel_hi:[0,1,1] neg_lo:[1,0,0] neg_hi:[1,0,0]
	ds_read_b128 v[136:139], v69 offset:48752
	s_waitcnt lgkmcnt(8)
	v_fma_f32 v180, -v132, v186, v187
	s_waitcnt lgkmcnt(7)
	v_pk_fma_f32 v[188:189], v[178:179], v[124:125], v[188:189] op_sel_hi:[0,1,1] neg_lo:[1,0,0] neg_hi:[1,0,0]
	v_pk_fma_f32 v[188:189], v[126:127], v[176:177], v[188:189] op_sel_hi:[1,0,1] neg_lo:[1,0,0] neg_hi:[1,0,0]
	ds_read_b128 v[124:127], v69 offset:48768
	s_waitcnt lgkmcnt(7)
	v_pk_fma_f32 v[188:189], v[128:129], v[186:187], v[188:189] op_sel_hi:[1,0,1] neg_lo:[1,0,0] neg_hi:[1,0,0]
	s_nop 0
	v_pk_fma_f32 v[188:189], v[130:131], v[180:181], v[188:189] op_sel_hi:[1,0,1] neg_lo:[1,0,0] neg_hi:[1,0,0]
	ds_read_b128 v[128:131], v69 offset:48784
	v_fma_f32 v184, -v133, v188, v189
	ds_read_b128 v[132:135], v69 offset:49280
	s_waitcnt lgkmcnt(8)
	v_pk_fma_f32 v[190:191], v[172:173], v[238:239], v[190:191] op_sel_hi:[0,1,1] neg_lo:[1,0,0] neg_hi:[1,0,0]
	v_pk_fma_f32 v[210:211], v[174:175], v[240:241], 0 op_sel_hi:[0,1,0] neg_lo:[1,0,0] neg_hi:[1,0,0]
	ds_read_b128 v[238:241], v69 offset:49296
	s_waitcnt lgkmcnt(8)
	v_pk_fma_f32 v[190:191], v[178:179], v[116:117], v[190:191] op_sel_hi:[0,1,1] neg_lo:[1,0,0] neg_hi:[1,0,0]
	v_pk_fma_f32 v[210:211], v[176:177], v[118:119], v[210:211] op_sel_hi:[0,1,1] neg_lo:[1,0,0] neg_hi:[1,0,0]
	ds_read_b128 v[116:119], v69 offset:49312
	s_waitcnt lgkmcnt(8)
	v_pk_fma_f32 v[190:191], v[120:121], v[186:187], v[190:191] op_sel_hi:[1,0,1] neg_lo:[1,0,0] neg_hi:[1,0,0]
	v_pk_fma_f32 v[210:211], v[122:123], v[180:181], v[210:211] op_sel_hi:[1,0,1] neg_lo:[1,0,0] neg_hi:[1,0,0]
	ds_read_b128 v[120:123], v69 offset:49328
	s_waitcnt lgkmcnt(8)
; #define LAS __attribute__((address_space(3)))
; DI void gdn_prep_phase(const int tid, LAS unsigned char* lds, const P& p, int G, int c) {
;     ...
;               for (int pr = 4 * kb + 4; pr < 32; ++pr) {
;                   f32x2 s0 = (f32x2){xs[2 * pr], xs[2 * pr + 1]}, s1 = (f32x2){0.f, 0.f};
; #pragma unroll
;                   for (int q = 0; q < 4; ++q) { const int j = 8 * kb + 2 * q; const f32x4 l = *(const LAS f32x4*)(Ls + pr * 136 + j * 2);
;                       s0 -= (f32x2){l[0], l[1]} * (f32x2){xs[j], xs[j]}; s1 -= (f32x2){l[2], l[3]} * (f32x2){xs[j + 1], xs[j + 1]}; }
;                   const f32x2 s = s0 + s1; xs[2 * pr] = s[0]; xs[2 * pr + 1] = s[1]; }
	v_pk_fma_f32 v[190:191], v[242:243], v[188:189], v[190:191] op_sel_hi:[1,0,1] neg_lo:[1,0,0] neg_hi:[1,0,0]
	v_pk_fma_f32 v[206:207], v[244:245], v[184:185], v[210:211] op_sel_hi:[1,0,1] neg_lo:[1,0,0] neg_hi:[1,0,0]
	ds_read_b128 v[242:245], v69 offset:49824
	v_pk_add_f32 v[190:191], v[190:191], v[206:207]
	s_waitcnt lgkmcnt(8)
	v_pk_fma_f32 v[200:201], v[172:173], v[112:113], v[200:201] op_sel_hi:[0,1,1] neg_lo:[1,0,0] neg_hi:[1,0,0]
	v_pk_fma_f32 v[210:211], v[174:175], v[114:115], 0 op_sel_hi:[0,1,0] neg_lo:[1,0,0] neg_hi:[1,0,0]
	ds_read_b128 v[112:115], v69 offset:49840
	s_waitcnt lgkmcnt(8)
	v_pk_fma_f32 v[200:201], v[178:179], v[136:137], v[200:201] op_sel_hi:[0,1,1] neg_lo:[1,0,0] neg_hi:[1,0,0]
	v_pk_fma_f32 v[210:211], v[176:177], v[138:139], v[210:211] op_sel_hi:[0,1,1] neg_lo:[1,0,0] neg_hi:[1,0,0]
	ds_read_b128 v[136:139], v69 offset:49856
	s_waitcnt lgkmcnt(8)
	v_pk_fma_f32 v[200:201], v[186:187], v[124:125], v[200:201] op_sel_hi:[0,1,1] neg_lo:[1,0,0] neg_hi:[1,0,0]
	v_pk_fma_f32 v[210:211], v[126:127], v[180:181], v[210:211] op_sel_hi:[1,0,1] neg_lo:[1,0,0] neg_hi:[1,0,0]
	ds_read_b128 v[124:127], v69 offset:49872
	s_waitcnt lgkmcnt(8)
	v_pk_fma_f32 v[200:201], v[128:129], v[188:189], v[200:201] op_sel_hi:[1,0,1] neg_lo:[1,0,0] neg_hi:[1,0,0]
	v_pk_fma_f32 v[206:207], v[130:131], v[184:185], v[210:211] op_sel_hi:[1,0,1] neg_lo:[1,0,0] neg_hi:[1,0,0]
	ds_read_b128 v[128:131], v69 offset:50368
	v_pk_add_f32 v[214:215], v[200:201], v[206:207]
	s_waitcnt lgkmcnt(8)
	v_pk_fma_f32 v[206:207], v[172:173], v[132:133], v[202:203] op_sel_hi:[0,1,1] neg_lo:[1,0,0] neg_hi:[1,0,0]
	v_pk_fma_f32 v[208:209], v[174:175], v[134:135], 0 op_sel_hi:[0,1,0] neg_lo:[1,0,0] neg_hi:[1,0,0]
	ds_read_b128 v[132:135], v69 offset:50384
	s_waitcnt lgkmcnt(8)
	v_pk_fma_f32 v[206:207], v[178:179], v[238:239], v[206:207] op_sel_hi:[0,1,1] neg_lo:[1,0,0] neg_hi:[1,0,0]
	v_pk_fma_f32 v[208:209], v[176:177], v[240:241], v[208:209] op_sel_hi:[0,1,1] neg_lo:[1,0,0] neg_hi:[1,0,0]
	ds_read_b128 v[238:241], v69 offset:50400
	s_waitcnt lgkmcnt(8)
	v_pk_fma_f32 v[206:207], v[186:187], v[116:117], v[206:207] op_sel_hi:[0,1,1] neg_lo:[1,0,0] neg_hi:[1,0,0]
	v_pk_fma_f32 v[208:209], v[180:181], v[118:119], v[208:209] op_sel_hi:[0,1,1] neg_lo:[1,0,0] neg_hi:[1,0,0]
	ds_read_b128 v[116:119], v69 offset:50416
	s_waitcnt lgkmcnt(8)
	v_pk_fma_f32 v[200:201], v[188:189], v[120:121], v[206:207] op_sel_hi:[0,1,1] neg_lo:[1,0,0] neg_hi:[1,0,0]
	v_pk_fma_f32 v[202:203], v[122:123], v[184:185], v[208:209] op_sel_hi:[1,0,1] neg_lo:[1,0,0] neg_hi:[1,0,0]
	ds_read_b128 v[120:123], v69 offset:50912
	v_pk_add_f32 v[202:203], v[200:201], v[202:203]
	s_waitcnt lgkmcnt(8)
	v_pk_fma_f32 v[200:201], v[172:173], v[242:243], v[204:205] op_sel_hi:[0,1,1] neg_lo:[1,0,0] neg_hi:[1,0,0]
	v_pk_fma_f32 v[208:209], v[174:175], v[244:245], 0 op_sel_hi:[0,1,0] neg_lo:[1,0,0] neg_hi:[1,0,0]
	ds_read_b128 v[242:245], v69 offset:50928
	s_waitcnt lgkmcnt(8)
	v_pk_fma_f32 v[200:201], v[178:179], v[112:113], v[200:201] op_sel_hi:[0,1,1] neg_lo:[1,0,0] neg_hi:[1,0,0]
	v_pk_fma_f32 v[208:209], v[176:177], v[114:115], v[208:209] op_sel_hi:[0,1,1] neg_lo:[1,0,0] neg_hi:[1,0,0]
	ds_read_b128 v[112:115], v69 offset:50944
	s_waitcnt lgkmcnt(8)
	v_pk_fma_f32 v[200:201], v[186:187], v[136:137], v[200:201] op_sel_hi:[0,1,1] neg_lo:[1,0,0] neg_hi:[1,0,0]
	v_pk_fma_f32 v[208:209], v[180:181], v[138:139], v[208:209] op_sel_hi:[0,1,1] neg_lo:[1,0,0] neg_hi:[1,0,0]
	ds_read_b128 v[136:139], v69 offset:50960
	s_waitcnt lgkmcnt(8)
	v_pk_fma_f32 v[200:201], v[188:189], v[124:125], v[200:201] op_sel_hi:[0,1,1] neg_lo:[1,0,0] neg_hi:[1,0,0]
	v_pk_fma_f32 v[204:205], v[184:185], v[126:127], v[208:209] op_sel_hi:[0,1,1] neg_lo:[1,0,0] neg_hi:[1,0,0]
	ds_read_b128 v[124:127], v69 offset:51456
	v_pk_add_f32 v[200:201], v[200:201], v[204:205]
	s_waitcnt lgkmcnt(8)
	v_pk_fma_f32 v[196:197], v[172:173], v[128:129], v[196:197] op_sel_hi:[0,1,1] neg_lo:[1,0,0] neg_hi:[1,0,0]
	v_pk_fma_f32 v[208:209], v[174:175], v[130:131], 0 op_sel_hi:[0,1,0] neg_lo:[1,0,0] neg_hi:[1,0,0]
	ds_read_b128 v[128:131], v69 offset:51472
	s_waitcnt lgkmcnt(8)
	v_pk_fma_f32 v[196:197], v[178:179], v[132:133], v[196:197] op_sel_hi:[0,1,1] neg_lo:[1,0,0] neg_hi:[1,0,0]
	v_pk_fma_f32 v[208:209], v[176:177], v[134:135], v[208:209] op_sel_hi:[0,1,1] neg_lo:[1,0,0] neg_hi:[1,0,0]
	ds_read_b128 v[132:135], v69 offset:51488
	s_waitcnt lgkmcnt(8)
	v_pk_fma_f32 v[196:197], v[186:187], v[238:239], v[196:197] op_sel_hi:[0,1,1] neg_lo:[1,0,0] neg_hi:[1,0,0]
	v_pk_fma_f32 v[208:209], v[180:181], v[240:241], v[208:209] op_sel_hi:[0,1,1] neg_lo:[1,0,0] neg_hi:[1,0,0]
	ds_read_b128 v[238:241], v69 offset:51504
	s_waitcnt lgkmcnt(8)
	v_pk_fma_f32 v[196:197], v[188:189], v[116:117], v[196:197] op_sel_hi:[0,1,1] neg_lo:[1,0,0] neg_hi:[1,0,0]
	v_pk_fma_f32 v[204:205], v[184:185], v[118:119], v[208:209] op_sel_hi:[0,1,1] neg_lo:[1,0,0] neg_hi:[1,0,0]
	ds_read_b128 v[116:119], v69 offset:52000
	v_pk_add_f32 v[206:207], v[196:197], v[204:205]
	s_waitcnt lgkmcnt(8)
	v_pk_fma_f32 v[204:205], v[172:173], v[120:121], v[198:199] op_sel_hi:[0,1,1] neg_lo:[1,0,0] neg_hi:[1,0,0]
	v_pk_fma_f32 v[208:209], v[174:175], v[122:123], 0 op_sel_hi:[0,1,0] neg_lo:[1,0,0] neg_hi:[1,0,0]
	ds_read_b128 v[120:123], v69 offset:52016
	s_waitcnt lgkmcnt(8)
	v_pk_fma_f32 v[204:205], v[178:179], v[242:243], v[204:205] op_sel_hi:[0,1,1] neg_lo:[1,0,0] neg_hi:[1,0,0]
	v_pk_fma_f32 v[208:209], v[176:177], v[244:245], v[208:209] op_sel_hi:[0,1,1] neg_lo:[1,0,0] neg_hi:[1,0,0]
	ds_read_b128 v[242:245], v69 offset:52032
	s_waitcnt lgkmcnt(8)
; #define LAS __attribute__((address_space(3)))
; DI void gdn_prep_phase(const int tid, LAS unsigned char* lds, const P& p, int G, int c) {
;     ...
; #pragma unroll
;           for (int kb = 0; kb < 8; ++kb) {
; #pragma unroll
;               for (int pp = 0; pp < 4; ++pp) { const int pr = 4 * kb + pp;
;                   f32x2 s = (f32x2){xs[2 * pr], xs[2 * pr + 1]};
; #pragma unroll
;                   for (int j = 8 * kb; j < 2 * pr; j += 2) { const f32x4 l = *(const LAS f32x4*)(Ls + pr * 136 + j * 2);
;                       s -= (f32x2){l[0], l[1]} * (f32x2){xs[j], xs[j]}; s -= (f32x2){l[2], l[3]} * (f32x2){xs[j + 1], xs[j + 1]}; }
;                   xs[2 * pr] = s[0];
;                   xs[2 * pr + 1] = s[1] - Ls[pr * 136 + 4 * pr + 1] * s[0]; }
; #pragma unroll
;               for (int pr = 4 * kb + 4; pr < 32; ++pr) {
;                   f32x2 s0 = (f32x2){xs[2 * pr], xs[2 * pr + 1]}, s1 = (f32x2){0.f, 0.f};
; #pragma unroll
;                   for (int q = 0; q < 4; ++q) { const int j = 8 * kb + 2 * q; const f32x4 l = *(const LAS f32x4*)(Ls + pr * 136 + j * 2);
;                       s0 -= (f32x2){l[0], l[1]} * (f32x2){xs[j], xs[j]}; s1 -= (f32x2){l[2], l[3]} * (f32x2){xs[j + 1], xs[j + 1]}; }
;                   const f32x2 s = s0 + s1; xs[2 * pr] = s[0]; xs[2 * pr + 1] = s[1]; }
	v_pk_fma_f32 v[204:205], v[186:187], v[112:113], v[204:205] op_sel_hi:[0,1,1] neg_lo:[1,0,0] neg_hi:[1,0,0]
	v_pk_fma_f32 v[208:209], v[180:181], v[114:115], v[208:209] op_sel_hi:[0,1,1] neg_lo:[1,0,0] neg_hi:[1,0,0]
	ds_read_b128 v[112:115], v69 offset:52048
	s_waitcnt lgkmcnt(8)
	v_pk_fma_f32 v[196:197], v[188:189], v[136:137], v[204:205] op_sel_hi:[0,1,1] neg_lo:[1,0,0] neg_hi:[1,0,0]
	v_pk_fma_f32 v[198:199], v[184:185], v[138:139], v[208:209] op_sel_hi:[0,1,1] neg_lo:[1,0,0] neg_hi:[1,0,0]
	ds_read_b128 v[136:139], v69 offset:48800
	v_pk_add_f32 v[208:209], v[196:197], v[198:199]
	s_waitcnt lgkmcnt(8)
	v_pk_fma_f32 v[192:193], v[172:173], v[124:125], v[192:193] op_sel_hi:[0,1,1] neg_lo:[1,0,0] neg_hi:[1,0,0]
	v_pk_fma_f32 v[204:205], v[174:175], v[126:127], 0 op_sel_hi:[0,1,0] neg_lo:[1,0,0] neg_hi:[1,0,0]
	v_add_u32_e32 v141, 0xbc00, v69
	ds_read2_b32 v[124:125], v141 offset0:33 offset1:173
	s_waitcnt lgkmcnt(8)
	v_pk_fma_f32 v[192:193], v[178:179], v[128:129], v[192:193] op_sel_hi:[0,1,1] neg_lo:[1,0,0] neg_hi:[1,0,0]
	v_pk_fma_f32 v[204:205], v[176:177], v[130:131], v[204:205] op_sel_hi:[0,1,1] neg_lo:[1,0,0] neg_hi:[1,0,0]
	ds_read_b128 v[128:131], v69 offset:49344
	s_waitcnt lgkmcnt(8)
	v_pk_fma_f32 v[192:193], v[186:187], v[132:133], v[192:193] op_sel_hi:[0,1,1] neg_lo:[1,0,0] neg_hi:[1,0,0]
	v_pk_fma_f32 v[204:205], v[180:181], v[134:135], v[204:205] op_sel_hi:[0,1,1] neg_lo:[1,0,0] neg_hi:[1,0,0]
	ds_read_b128 v[132:135], v69 offset:49360
	s_waitcnt lgkmcnt(8)
	v_pk_fma_f32 v[192:193], v[188:189], v[238:239], v[192:193] op_sel_hi:[0,1,1] neg_lo:[1,0,0] neg_hi:[1,0,0]
	v_pk_fma_f32 v[196:197], v[184:185], v[240:241], v[204:205] op_sel_hi:[0,1,1] neg_lo:[1,0,0] neg_hi:[1,0,0]
	ds_read_b128 v[238:241], v69 offset:49888
	v_pk_add_f32 v[210:211], v[192:193], v[196:197]
	s_waitcnt lgkmcnt(8)
	v_pk_fma_f32 v[196:197], v[172:173], v[116:117], v[194:195] op_sel_hi:[0,1,1] neg_lo:[1,0,0] neg_hi:[1,0,0]
	v_pk_fma_f32 v[198:199], v[174:175], v[118:119], 0 op_sel_hi:[0,1,0] neg_lo:[1,0,0] neg_hi:[1,0,0]
	ds_read_b128 v[116:119], v69 offset:49904
	s_waitcnt lgkmcnt(8)
	v_pk_fma_f32 v[196:197], v[178:179], v[120:121], v[196:197] op_sel_hi:[0,1,1] neg_lo:[1,0,0] neg_hi:[1,0,0]
	v_pk_fma_f32 v[198:199], v[176:177], v[122:123], v[198:199] op_sel_hi:[0,1,1] neg_lo:[1,0,0] neg_hi:[1,0,0]
	v_add_u32_e32 v183, 0xc000, v69
	ds_read2_b32 v[120:121], v183 offset0:57 offset1:197
	s_waitcnt lgkmcnt(8)
	v_pk_fma_f32 v[196:197], v[186:187], v[242:243], v[196:197] op_sel_hi:[0,1,1] neg_lo:[1,0,0] neg_hi:[1,0,0]
	v_pk_fma_f32 v[198:199], v[180:181], v[244:245], v[198:199] op_sel_hi:[0,1,1] neg_lo:[1,0,0] neg_hi:[1,0,0]
	ds_read_b128 v[242:245], v69 offset:49920
	s_waitcnt lgkmcnt(8)
	v_pk_fma_f32 v[192:193], v[188:189], v[112:113], v[196:197] op_sel_hi:[0,1,1] neg_lo:[1,0,0] neg_hi:[1,0,0]
	v_pk_fma_f32 v[194:195], v[184:185], v[114:115], v[198:199] op_sel_hi:[0,1,1] neg_lo:[1,0,0] neg_hi:[1,0,0]
	ds_read_b128 v[112:115], v69 offset:50432
	v_pk_add_f32 v[212:213], v[192:193], v[194:195]
	s_waitcnt lgkmcnt(8)
	v_pk_fma_f32 v[194:195], v[190:191], v[136:137], v[214:215] op_sel_hi:[0,1,1] neg_lo:[1,0,0] neg_hi:[1,0,0]
	s_waitcnt lgkmcnt(7)
	v_fma_f32 v192, -v190, v124, v191
	v_pk_fma_f32 v[196:197], v[138:139], v[192:193], v[194:195] op_sel_hi:[1,0,1] neg_lo:[1,0,0] neg_hi:[1,0,0]
	ds_read_b128 v[136:139], v69 offset:50448
	s_waitcnt lgkmcnt(7)
	v_pk_fma_f32 v[198:199], v[190:191], v[128:129], v[202:203] op_sel_hi:[0,1,1] neg_lo:[1,0,0] neg_hi:[1,0,0]
	v_pk_fma_f32 v[198:199], v[130:131], v[192:193], v[198:199] op_sel_hi:[1,0,1] neg_lo:[1,0,0] neg_hi:[1,0,0]
	ds_read_b128 v[128:131], v69 offset:50464
	v_fma_f32 v194, -v125, v196, v197
	ds_read_b128 v[124:127], v69 offset:50480
	s_waitcnt lgkmcnt(8)
	v_pk_fma_f32 v[198:199], v[132:133], v[196:197], v[198:199] op_sel_hi:[1,0,1] neg_lo:[1,0,0] neg_hi:[1,0,0]
	s_waitcnt lgkmcnt(7)
	v_pk_fma_f32 v[200:201], v[190:191], v[238:239], v[200:201] op_sel_hi:[0,1,1] neg_lo:[1,0,0] neg_hi:[1,0,0]
	v_pk_fma_f32 v[200:201], v[192:193], v[240:241], v[200:201] op_sel_hi:[0,1,1] neg_lo:[1,0,0] neg_hi:[1,0,0]
	ds_read_b128 v[238:241], v69 offset:50976
	v_pk_fma_f32 v[202:203], v[134:135], v[194:195], v[198:199] op_sel_hi:[1,0,1] neg_lo:[1,0,0] neg_hi:[1,0,0]
	ds_read_b128 v[132:135], v69 offset:50992
	s_waitcnt lgkmcnt(8)
	v_pk_fma_f32 v[200:201], v[196:197], v[116:117], v[200:201] op_sel_hi:[0,1,1] neg_lo:[1,0,0] neg_hi:[1,0,0]
	v_pk_fma_f32 v[200:201], v[118:119], v[194:195], v[200:201] op_sel_hi:[1,0,1] neg_lo:[1,0,0] neg_hi:[1,0,0]
	ds_read_b128 v[116:119], v69 offset:51008
	s_waitcnt lgkmcnt(8)
	v_fma_f32 v198, -v120, v202, v203
	s_waitcnt lgkmcnt(7)
	v_pk_fma_f32 v[200:201], v[242:243], v[202:203], v[200:201] op_sel_hi:[1,0,1] neg_lo:[1,0,0] neg_hi:[1,0,0]
	s_nop 0
	v_pk_fma_f32 v[204:205], v[244:245], v[198:199], v[200:201] op_sel_hi:[1,0,1] neg_lo:[1,0,0] neg_hi:[1,0,0]
	ds_read_b128 v[242:245], v69 offset:51024
	v_fma_f32 v200, -v121, v204, v205
	ds_read_b128 v[120:123], v69 offset:51520
	s_waitcnt lgkmcnt(8)
	v_pk_fma_f32 v[206:207], v[190:191], v[112:113], v[206:207] op_sel_hi:[0,1,1] neg_lo:[1,0,0] neg_hi:[1,0,0]
	v_pk_fma_f32 v[218:219], v[192:193], v[114:115], 0 op_sel_hi:[0,1,0] neg_lo:[1,0,0] neg_hi:[1,0,0]
	ds_read_b128 v[112:115], v69 offset:51536
	s_waitcnt lgkmcnt(8)
	v_pk_fma_f32 v[206:207], v[196:197], v[136:137], v[206:207] op_sel_hi:[0,1,1] neg_lo:[1,0,0] neg_hi:[1,0,0]
	v_pk_fma_f32 v[218:219], v[194:195], v[138:139], v[218:219] op_sel_hi:[0,1,1] neg_lo:[1,0,0] neg_hi:[1,0,0]
	ds_read_b128 v[136:139], v69 offset:51552
	s_waitcnt lgkmcnt(8)
; #define LAS __attribute__((address_space(3)))
; DI void gdn_prep_phase(const int tid, LAS unsigned char* lds, const P& p, int G, int c) {
;     ...
; #pragma unroll
;           for (int kb = 0; kb < 8; ++kb) {
; #pragma unroll
;               for (int pp = 0; pp < 4; ++pp) { const int pr = 4 * kb + pp;
;                   f32x2 s = (f32x2){xs[2 * pr], xs[2 * pr + 1]};
; #pragma unroll
;                   for (int j = 8 * kb; j < 2 * pr; j += 2) { const f32x4 l = *(const LAS f32x4*)(Ls + pr * 136 + j * 2);
;                       s -= (f32x2){l[0], l[1]} * (f32x2){xs[j], xs[j]}; s -= (f32x2){l[2], l[3]} * (f32x2){xs[j + 1], xs[j + 1]}; }
;                   xs[2 * pr] = s[0];
;                   xs[2 * pr + 1] = s[1] - Ls[pr * 136 + 4 * pr + 1] * s[0]; }
; #pragma unroll
;               for (int pr = 4 * kb + 4; pr < 32; ++pr) {
;                   f32x2 s0 = (f32x2){xs[2 * pr], xs[2 * pr + 1]}, s1 = (f32x2){0.f, 0.f};
; #pragma unroll
;                   for (int q = 0; q < 4; ++q) { const int j = 8 * kb + 2 * q; const f32x4 l = *(const LAS f32x4*)(Ls + pr * 136 + j * 2);
;                       s0 -= (f32x2){l[0], l[1]} * (f32x2){xs[j], xs[j]}; s1 -= (f32x2){l[2], l[3]} * (f32x2){xs[j + 1], xs[j + 1]}; }
;                   const f32x2 s = s0 + s1; xs[2 * pr] = s[0]; xs[2 * pr + 1] = s[1]; }
;           }
;           if (isv) {
	v_pk_fma_f32 v[206:207], v[128:129], v[202:203], v[206:207] op_sel_hi:[1,0,1] neg_lo:[1,0,0] neg_hi:[1,0,0]
	v_pk_fma_f32 v[218:219], v[130:131], v[198:199], v[218:219] op_sel_hi:[1,0,1] neg_lo:[1,0,0] neg_hi:[1,0,0]
	ds_read_b128 v[128:131], v69 offset:51568
	s_waitcnt lgkmcnt(8)
	v_pk_fma_f32 v[206:207], v[124:125], v[204:205], v[206:207] op_sel_hi:[1,0,1] neg_lo:[1,0,0] neg_hi:[1,0,0]
	v_pk_fma_f32 v[214:215], v[126:127], v[200:201], v[218:219] op_sel_hi:[1,0,1] neg_lo:[1,0,0] neg_hi:[1,0,0]
	ds_read_b128 v[124:127], v69 offset:52064
	v_pk_add_f32 v[206:207], v[206:207], v[214:215]
	s_waitcnt lgkmcnt(8)
	v_pk_fma_f32 v[208:209], v[190:191], v[238:239], v[208:209] op_sel_hi:[0,1,1] neg_lo:[1,0,0] neg_hi:[1,0,0]
	v_pk_fma_f32 v[218:219], v[192:193], v[240:241], 0 op_sel_hi:[0,1,0] neg_lo:[1,0,0] neg_hi:[1,0,0]
	ds_read_b128 v[238:241], v69 offset:52080
	s_waitcnt lgkmcnt(8)
	v_pk_fma_f32 v[208:209], v[196:197], v[132:133], v[208:209] op_sel_hi:[0,1,1] neg_lo:[1,0,0] neg_hi:[1,0,0]
	v_pk_fma_f32 v[218:219], v[194:195], v[134:135], v[218:219] op_sel_hi:[0,1,1] neg_lo:[1,0,0] neg_hi:[1,0,0]
	ds_read_b128 v[132:135], v69 offset:52096
	s_waitcnt lgkmcnt(8)
	v_pk_fma_f32 v[208:209], v[202:203], v[116:117], v[208:209] op_sel_hi:[0,1,1] neg_lo:[1,0,0] neg_hi:[1,0,0]
	v_pk_fma_f32 v[218:219], v[118:119], v[198:199], v[218:219] op_sel_hi:[1,0,1] neg_lo:[1,0,0] neg_hi:[1,0,0]
	ds_read_b128 v[116:119], v69 offset:52112
	s_waitcnt lgkmcnt(8)
	v_pk_fma_f32 v[208:209], v[242:243], v[204:205], v[208:209] op_sel_hi:[1,0,1] neg_lo:[1,0,0] neg_hi:[1,0,0]
	v_pk_fma_f32 v[214:215], v[244:245], v[200:201], v[218:219] op_sel_hi:[1,0,1] neg_lo:[1,0,0] neg_hi:[1,0,0]
	v_add_u32_e32 v141, 0xc400, v69
	ds_read2_b32 v[242:243], v141 offset0:81 offset1:221
	v_pk_add_f32 v[214:215], v[208:209], v[214:215]
	s_waitcnt lgkmcnt(8)
	v_pk_fma_f32 v[216:217], v[190:191], v[120:121], v[210:211] op_sel_hi:[0,1,1] neg_lo:[1,0,0] neg_hi:[1,0,0]
	v_pk_fma_f32 v[218:219], v[192:193], v[122:123], 0 op_sel_hi:[0,1,0] neg_lo:[1,0,0] neg_hi:[1,0,0]
	ds_read_b128 v[120:123], v69 offset:51040
	s_waitcnt lgkmcnt(8)
	v_pk_fma_f32 v[216:217], v[196:197], v[112:113], v[216:217] op_sel_hi:[0,1,1] neg_lo:[1,0,0] neg_hi:[1,0,0]
	v_pk_fma_f32 v[218:219], v[194:195], v[114:115], v[218:219] op_sel_hi:[0,1,1] neg_lo:[1,0,0] neg_hi:[1,0,0]
	ds_read_b128 v[112:115], v69 offset:51584
	s_waitcnt lgkmcnt(8)
	v_pk_fma_f32 v[216:217], v[202:203], v[136:137], v[216:217] op_sel_hi:[0,1,1] neg_lo:[1,0,0] neg_hi:[1,0,0]
	v_pk_fma_f32 v[218:219], v[198:199], v[138:139], v[218:219] op_sel_hi:[0,1,1] neg_lo:[1,0,0] neg_hi:[1,0,0]
	ds_read_b128 v[136:139], v69 offset:51600
	s_waitcnt lgkmcnt(8)
	v_pk_fma_f32 v[208:209], v[204:205], v[128:129], v[216:217] op_sel_hi:[0,1,1] neg_lo:[1,0,0] neg_hi:[1,0,0]
	v_pk_fma_f32 v[210:211], v[130:131], v[200:201], v[218:219] op_sel_hi:[1,0,1] neg_lo:[1,0,0] neg_hi:[1,0,0]
	ds_read_b128 v[128:131], v69 offset:52128
	v_pk_add_f32 v[216:217], v[208:209], v[210:211]
	s_waitcnt lgkmcnt(8)
	v_pk_fma_f32 v[212:213], v[190:191], v[124:125], v[212:213] op_sel_hi:[0,1,1] neg_lo:[1,0,0] neg_hi:[1,0,0]
	v_pk_fma_f32 v[218:219], v[192:193], v[126:127], 0 op_sel_hi:[0,1,0] neg_lo:[1,0,0] neg_hi:[1,0,0]
	v_add_u32_e32 v183, 0xc800, v69
	ds_read2_b32 v[124:125], v183 offset0:105 offset1:245
	s_waitcnt lgkmcnt(8)
	v_pk_fma_f32 v[212:213], v[196:197], v[238:239], v[212:213] op_sel_hi:[0,1,1] neg_lo:[1,0,0] neg_hi:[1,0,0]
	v_pk_fma_f32 v[218:219], v[194:195], v[240:241], v[218:219] op_sel_hi:[0,1,1] neg_lo:[1,0,0] neg_hi:[1,0,0]
	ds_read_b128 v[238:241], v69 offset:52144
	s_waitcnt lgkmcnt(8)
	v_pk_fma_f32 v[212:213], v[202:203], v[132:133], v[212:213] op_sel_hi:[0,1,1] neg_lo:[1,0,0] neg_hi:[1,0,0]
	v_pk_fma_f32 v[218:219], v[198:199], v[134:135], v[218:219] op_sel_hi:[0,1,1] neg_lo:[1,0,0] neg_hi:[1,0,0]
	ds_read_b128 v[132:135], v69 offset:52160
	s_waitcnt lgkmcnt(8)
	v_pk_fma_f32 v[208:209], v[204:205], v[116:117], v[212:213] op_sel_hi:[0,1,1] neg_lo:[1,0,0] neg_hi:[1,0,0]
	v_pk_fma_f32 v[210:211], v[200:201], v[118:119], v[218:219] op_sel_hi:[0,1,1] neg_lo:[1,0,0] neg_hi:[1,0,0]
	v_pk_add_f32 v[212:213], v[208:209], v[210:211]
	s_waitcnt lgkmcnt(7)
	v_fma_f32 v208, -v242, v206, v207
	s_waitcnt lgkmcnt(6)
	v_pk_fma_f32 v[210:211], v[120:121], v[206:207], v[214:215] op_sel_hi:[1,0,1] neg_lo:[1,0,0] neg_hi:[1,0,0]
	s_nop 0
	v_pk_fma_f32 v[214:215], v[122:123], v[208:209], v[210:211] op_sel_hi:[1,0,1] neg_lo:[1,0,0] neg_hi:[1,0,0]
	s_nop 0
	v_fma_f32 v210, -v243, v214, v215
	s_waitcnt lgkmcnt(5)
	v_pk_fma_f32 v[216:217], v[206:207], v[112:113], v[216:217] op_sel_hi:[0,1,1] neg_lo:[1,0,0] neg_hi:[1,0,0]
	v_pk_fma_f32 v[220:221], v[114:115], v[208:209], v[216:217] op_sel_hi:[1,0,1] neg_lo:[1,0,0] neg_hi:[1,0,0]
	s_waitcnt lgkmcnt(4)
	v_pk_fma_f32 v[216:217], v[136:137], v[214:215], v[220:221] op_sel_hi:[1,0,1] neg_lo:[1,0,0] neg_hi:[1,0,0]
	s_nop 0
	v_pk_fma_f32 v[218:219], v[138:139], v[210:211], v[216:217] op_sel_hi:[1,0,1] neg_lo:[1,0,0] neg_hi:[1,0,0]
	s_waitcnt lgkmcnt(3)
	v_pk_fma_f32 v[212:213], v[206:207], v[128:129], v[212:213] op_sel_hi:[0,1,1] neg_lo:[1,0,0] neg_hi:[1,0,0]
	v_pk_fma_f32 v[212:213], v[130:131], v[208:209], v[212:213] op_sel_hi:[1,0,1] neg_lo:[1,0,0] neg_hi:[1,0,0]
	s_waitcnt lgkmcnt(2)
	v_fma_f32 v216, -v124, v218, v219
	s_waitcnt lgkmcnt(1)
	v_pk_fma_f32 v[212:213], v[238:239], v[214:215], v[212:213] op_sel_hi:[1,0,1] neg_lo:[1,0,0] neg_hi:[1,0,0]
	s_nop 0
	v_pk_fma_f32 v[212:213], v[240:241], v[210:211], v[212:213] op_sel_hi:[1,0,1] neg_lo:[1,0,0] neg_hi:[1,0,0]
	s_waitcnt lgkmcnt(0)
	v_pk_fma_f32 v[212:213], v[132:133], v[218:219], v[212:213] op_sel_hi:[1,0,1] neg_lo:[1,0,0] neg_hi:[1,0,0]
	s_nop 0
	v_pk_fma_f32 v[212:213], v[134:135], v[216:217], v[212:213] op_sel_hi:[1,0,1] neg_lo:[1,0,0] neg_hi:[1,0,0]
	s_nop 0
	v_fma_f32 v1, -v125, v212, v213
	s_and_saveexec_b64 s[0:1], s[40:41]
	s_xor_b64 s[0:1], exec, s[0:1]
	s_cbranch_execz .LBB0_632
; DI void gdn_prep_phase(const int tid, LAS unsigned char* lds, const P& p, int G, int c) {
;     ...
;           if (isv) {
; #pragma unroll
;               for (int i8 = 0; i8 < 8; ++i8) { u32x4 w; w.x = pk2(xs[i8 * 8], xs[i8 * 8 + 1]); w.y = pk2(xs[i8 * 8 + 2], xs[i8 * 8 + 3]); w.z = pk2(xs[i8 * 8 + 4], xs[i8 * 8 + 5]); w.w = pk2(xs[i8 * 8 + 6], xs[i8 * 8 + 7]);
;                   *(u32x4*)(Uc + cid * 8192 + ch * 64 + i8 * 8) = w; }
	s_mov_b32 s26, 0x5040100
	v_cvt_pk_bf16_f32 v5, v60, s0
	v_perm_b32 v159, v11, v5, s26
	v_cvt_pk_bf16_f32 v5, v56, s0
	v_perm_b32 v160, v7, v5, s26
	v_cvt_pk_bf16_f32 v5, v58, s0
	v_add_co_u32_e32 v60, vcc, 0x20600000, v64
	v_perm_b32 v161, v3, v5, s26
	s_nop 0
	v_addc_co_u32_e32 v61, vcc, 0, v65, vcc
	v_cvt_pk_bf16_f32 v57, v4, v2
	v_cvt_pk_bf16_f32 v2, v14, v16
	v_cvt_pk_bf16_f32 v3, v20, v18
	v_cvt_pk_bf16_f32 v4, v26, v22
	v_cvt_pk_bf16_f32 v5, v28, v24
	global_store_dwordx4 v[60:61], v[2:5], off offset:32
	v_perm_b32 v158, v19, v17, s26
	v_cvt_pk_bf16_f32 v56, v48, v0
	v_cvt_pk_bf16_f32 v2, v30, v32
	v_cvt_pk_bf16_f32 v3, v36, v34
	v_cvt_pk_bf16_f32 v4, v42, v38
	v_cvt_pk_bf16_f32 v5, v44, v40
	global_store_dwordx4 v[60:61], v[2:5], off offset:48
	v_cvt_pk_bf16_f32 v58, v8, v6
	v_cvt_pk_bf16_f32 v59, v12, v10
	v_cvt_pk_bf16_f32 v2, v46, v50
	v_cvt_pk_bf16_f32 v3, v54, v52
	v_cvt_pk_bf16_f32 v4, v168, v164
	v_cvt_pk_bf16_f32 v5, v170, v166
	global_store_dwordx4 v[60:61], v[2:5], off offset:64
	global_store_dwordx4 v[60:61], v[158:161], off
	global_store_dwordx4 v[60:61], v[56:59], off offset:16
	v_cvt_pk_bf16_f32 v2, v172, v174
	v_cvt_pk_bf16_f32 v3, v178, v176
	v_cvt_pk_bf16_f32 v4, v186, v180
	v_cvt_pk_bf16_f32 v5, v188, v184
	global_store_dwordx4 v[60:61], v[2:5], off offset:80
	s_nop 1
	v_cvt_pk_bf16_f32 v2, v190, v192
	v_cvt_pk_bf16_f32 v3, v196, v194
	v_cvt_pk_bf16_f32 v4, v202, v198
	v_cvt_pk_bf16_f32 v5, v204, v200
	global_store_dwordx4 v[60:61], v[2:5], off offset:96
	s_nop 1
	v_cvt_pk_bf16_f32 v2, v206, v208
	v_cvt_pk_bf16_f32 v3, v214, v210
	v_cvt_pk_bf16_f32 v4, v218, v216
	v_cvt_pk_bf16_f32 v5, v212, v1
	global_store_dwordx4 v[60:61], v[2:5], off offset:112
